# K-loop phase-closing barrier moved up by 3 MFMAs instead of 4 (tail of 3 MFMAs at priority 2 after the barrier), otherwise identical to the previous version
# speedup vs baseline: 1.0061x; 1.0061x over previous
.LBB0_227:
	s_add_u32 s26, s44, vcc_lo
	s_addc_u32 s27, s45, vcc_hi
	s_add_u32 s26, s26, 0x100
	s_addc_u32 s27, s27, 0
	s_add_u32 s70, s25, vcc_lo
	s_addc_u32 s71, s30, vcc_hi
	s_add_i32 s72, 0, 0x10000
	s_cmpk_eq_i32 vcc_lo, 0x700
	s_cselect_b32 s53, s13, s27
	s_cselect_b32 s52, s37, s26
	v_add_u32_e32 v160, s72, v133
	s_cselect_b32 s27, s56, s71
	s_cselect_b32 s26, s68, s70
	s_add_i32 s73, 0, 0x14000
	ds_read_b128 v[178:181], v160
	ds_read_b128 v[182:185], v160 offset:1024
	ds_read_b128 v[186:189], v160 offset:2048
	ds_read_b128 v[190:193], v160 offset:3072
	v_add_u32_e32 v160, s73, v133
	ds_read_b128 v[194:197], v160
	ds_read_b128 v[198:201], v160 offset:1024
	ds_read_b128 v[202:205], v160 offset:2048
	ds_read_b128 v[206:209], v160 offset:3072
	v_lshl_add_u64 v[160:161], v[154:155], 0, vcc
	s_add_i32 m0, s64, 0xc000
	ds_read_b128 v[210:213], v159
	ds_read_b128 v[214:217], v159 offset:1024
	ds_read_b128 v[218:221], v159 offset:2048
	ds_read_b128 v[222:225], v159 offset:3072
	ds_read_b128 v[226:229], v159 offset:4096
	ds_read_b128 v[230:233], v159 offset:5120
	ds_read_b128 v[234:237], v159 offset:6144
	ds_read_b128 v[238:241], v159 offset:7168
	global_load_lds_dwordx4 v[160:161], off
	v_lshl_add_u64 v[160:161], v[156:157], 0, vcc
	s_add_i32 m0, s64, 0xe000
	s_nop 0
	global_load_lds_dwordx4 v[160:161], off
	s_waitcnt vmcnt(8)
	s_waitcnt lgkmcnt(0)
	s_barrier
	s_setprio 1
	s_waitcnt lgkmcnt(0)
	v_mfma_f32_16x16x32_bf16 v[126:129], v[178:181], v[210:213], v[126:129]
	v_mfma_f32_16x16x32_bf16 v[122:125], v[186:189], v[210:213], v[122:125]
	v_mfma_f32_16x16x32_bf16 v[118:121], v[178:181], v[218:221], v[118:121]
	v_mfma_f32_16x16x32_bf16 v[114:117], v[186:189], v[218:221], v[114:117]
	v_mfma_f32_16x16x32_bf16 v[110:113], v[178:181], v[226:229], v[110:113]
	v_mfma_f32_16x16x32_bf16 v[106:109], v[186:189], v[226:229], v[106:109]
	v_mfma_f32_16x16x32_bf16 v[102:105], v[178:181], v[234:237], v[102:105]
	v_mfma_f32_16x16x32_bf16 v[98:101], v[186:189], v[234:237], v[98:101]
	v_mfma_f32_16x16x32_bf16 v[126:129], v[182:185], v[214:217], v[126:129]
	v_mfma_f32_16x16x32_bf16 v[122:125], v[190:193], v[214:217], v[122:125]
	v_mfma_f32_16x16x32_bf16 v[118:121], v[182:185], v[222:225], v[118:121]
	v_mfma_f32_16x16x32_bf16 v[114:117], v[190:193], v[222:225], v[114:117]
	v_mfma_f32_16x16x32_bf16 v[110:113], v[182:185], v[230:233], v[110:113]
	v_mfma_f32_16x16x32_bf16 v[106:109], v[190:193], v[230:233], v[106:109]
	v_mfma_f32_16x16x32_bf16 v[102:105], v[182:185], v[238:241], v[102:105]
	v_mfma_f32_16x16x32_bf16 v[98:101], v[190:193], v[238:241], v[98:101]
	s_setprio 0
	s_setprio 1
	v_mfma_f32_16x16x32_bf16 v[82:85], v[194:197], v[210:213], v[82:85]
	v_mfma_f32_16x16x32_bf16 v[74:77], v[202:205], v[210:213], v[74:77]
	v_mfma_f32_16x16x32_bf16 v[66:69], v[194:197], v[218:221], v[66:69]
	v_mfma_f32_16x16x32_bf16 v[58:61], v[202:205], v[218:221], v[58:61]
	v_mfma_f32_16x16x32_bf16 v[54:57], v[194:197], v[226:229], v[54:57]
	v_mfma_f32_16x16x32_bf16 v[46:49], v[202:205], v[226:229], v[46:49]
	v_mfma_f32_16x16x32_bf16 v[38:41], v[194:197], v[234:237], v[38:41]
	v_mfma_f32_16x16x32_bf16 v[34:37], v[202:205], v[234:237], v[34:37]
	v_mfma_f32_16x16x32_bf16 v[82:85], v[198:201], v[214:217], v[82:85]
	v_mfma_f32_16x16x32_bf16 v[74:77], v[206:209], v[214:217], v[74:77]
	v_mfma_f32_16x16x32_bf16 v[66:69], v[198:201], v[222:225], v[66:69]
	v_mfma_f32_16x16x32_bf16 v[58:61], v[206:209], v[222:225], v[58:61]
	v_mfma_f32_16x16x32_bf16 v[54:57], v[198:201], v[230:233], v[54:57]
	s_setprio 2
	s_barrier
	v_mfma_f32_16x16x32_bf16 v[46:49], v[206:209], v[230:233], v[46:49]
	v_mfma_f32_16x16x32_bf16 v[38:41], v[198:201], v[238:241], v[38:41]
	v_mfma_f32_16x16x32_bf16 v[34:37], v[206:209], v[238:241], v[34:37]
	s_setprio 0
	s_add_i32 s70, s72, s60
	v_lshl_add_u64 v[160:161], s[26:27], 0, v[134:135]
	s_mov_b32 m0, s70
	ds_read_b128 v[210:213], v159 offset:16384
	ds_read_b128 v[214:217], v159 offset:17408
	ds_read_b128 v[218:221], v159 offset:18432
	ds_read_b128 v[222:225], v159 offset:19456
	ds_read_b128 v[226:229], v159 offset:20480
	ds_read_b128 v[230:233], v159 offset:21504
	ds_read_b128 v[234:237], v159 offset:22528
	ds_read_b128 v[238:241], v159 offset:23552
	global_load_lds_dwordx4 v[160:161], off
	s_add_i32 m0, s70, 0x2000
	s_add_u32 s70, s26, 0x40000
	v_lshl_add_u64 v[164:165], s[26:27], 0, v[148:149]
	s_addc_u32 s71, s27, 0
	s_add_i32 s72, s73, s60
	global_load_lds_dwordx4 v[164:165], off
	v_lshl_add_u64 v[242:243], s[70:71], 0, v[134:135]
	s_mov_b32 m0, s72
	v_lshl_add_u64 v[244:245], s[52:53], 0, v[146:147]
	global_load_lds_dwordx4 v[242:243], off
	v_lshl_add_u64 v[242:243], s[70:71], 0, v[148:149]
	s_add_i32 m0, s72, 0x2000
	s_nop 0
	global_load_lds_dwordx4 v[242:243], off
	v_lshl_add_u64 v[242:243], s[52:53], 0, v[144:145]
	s_mov_b32 m0, s64
	s_nop 0
	global_load_lds_dwordx4 v[242:243], off
	s_mov_b32 m0, s65
	s_nop 0
	global_load_lds_dwordx4 v[244:245], off
	s_waitcnt vmcnt(8)
	s_waitcnt lgkmcnt(0)
	s_barrier
	s_setprio 1
	s_waitcnt lgkmcnt(0)
	v_mfma_f32_16x16x32_bf16 v[94:97], v[178:181], v[210:213], v[94:97]
	v_mfma_f32_16x16x32_bf16 v[90:93], v[186:189], v[210:213], v[90:93]
	v_mfma_f32_16x16x32_bf16 v[86:89], v[178:181], v[218:221], v[86:89]
	v_mfma_f32_16x16x32_bf16 v[78:81], v[186:189], v[218:221], v[78:81]
	v_mfma_f32_16x16x32_bf16 v[70:73], v[178:181], v[226:229], v[70:73]
	v_mfma_f32_16x16x32_bf16 v[62:65], v[186:189], v[226:229], v[62:65]
	v_mfma_f32_16x16x32_bf16 v[50:53], v[178:181], v[234:237], v[50:53]
	v_mfma_f32_16x16x32_bf16 v[42:45], v[186:189], v[234:237], v[42:45]
	v_mfma_f32_16x16x32_bf16 v[94:97], v[182:185], v[214:217], v[94:97]
	v_mfma_f32_16x16x32_bf16 v[90:93], v[190:193], v[214:217], v[90:93]
	v_mfma_f32_16x16x32_bf16 v[86:89], v[182:185], v[222:225], v[86:89]
	v_mfma_f32_16x16x32_bf16 v[78:81], v[190:193], v[222:225], v[78:81]
	v_mfma_f32_16x16x32_bf16 v[70:73], v[182:185], v[230:233], v[70:73]
	v_mfma_f32_16x16x32_bf16 v[62:65], v[190:193], v[230:233], v[62:65]
	v_mfma_f32_16x16x32_bf16 v[50:53], v[182:185], v[238:241], v[50:53]
	v_mfma_f32_16x16x32_bf16 v[42:45], v[190:193], v[238:241], v[42:45]
	s_setprio 0
	s_setprio 1
	v_mfma_f32_16x16x32_bf16 v[30:33], v[194:197], v[210:213], v[30:33]
	v_mfma_f32_16x16x32_bf16 v[26:29], v[202:205], v[210:213], v[26:29]
	v_mfma_f32_16x16x32_bf16 v[22:25], v[194:197], v[218:221], v[22:25]
	v_mfma_f32_16x16x32_bf16 v[18:21], v[202:205], v[218:221], v[18:21]
	v_mfma_f32_16x16x32_bf16 v[14:17], v[194:197], v[226:229], v[14:17]
	v_mfma_f32_16x16x32_bf16 v[10:13], v[202:205], v[226:229], v[10:13]
	v_mfma_f32_16x16x32_bf16 v[6:9], v[194:197], v[234:237], v[6:9]
	v_mfma_f32_16x16x32_bf16 v[2:5], v[202:205], v[234:237], v[2:5]
	v_mfma_f32_16x16x32_bf16 v[30:33], v[198:201], v[214:217], v[30:33]
	v_mfma_f32_16x16x32_bf16 v[26:29], v[206:209], v[214:217], v[26:29]
	v_mfma_f32_16x16x32_bf16 v[22:25], v[198:201], v[222:225], v[22:25]
	v_mfma_f32_16x16x32_bf16 v[18:21], v[206:209], v[222:225], v[18:21]
	v_mfma_f32_16x16x32_bf16 v[14:17], v[198:201], v[230:233], v[14:17]
	s_setprio 2
	s_barrier
	v_mfma_f32_16x16x32_bf16 v[10:13], v[206:209], v[230:233], v[10:13]
	v_mfma_f32_16x16x32_bf16 v[6:9], v[198:201], v[238:241], v[6:9]
	v_mfma_f32_16x16x32_bf16 v[2:5], v[206:209], v[238:241], v[2:5]
	s_setprio 0
	s_add_i32 s70, 0, 0x18000
	v_add_u32_e32 v162, s70, v133
	s_add_i32 s71, 0, 0x1c000
	ds_read_b128 v[178:181], v162
	ds_read_b128 v[182:185], v162 offset:1024
	ds_read_b128 v[186:189], v162 offset:2048
	ds_read_b128 v[190:193], v162 offset:3072
	v_add_u32_e32 v162, s71, v133
	ds_read_b128 v[194:197], v162
	ds_read_b128 v[198:201], v162 offset:1024
	ds_read_b128 v[202:205], v162 offset:2048
	ds_read_b128 v[206:209], v162 offset:3072
	s_add_u32 s52, s52, 0x40000
	s_addc_u32 s53, s53, 0
	s_mov_b32 m0, s74
	v_lshl_add_u64 v[246:247], s[52:53], 0, v[144:145]
	ds_read_b128 v[210:213], v159 offset:32768
	ds_read_b128 v[214:217], v159 offset:33792
	ds_read_b128 v[218:221], v159 offset:34816
	ds_read_b128 v[222:225], v159 offset:35840
	ds_read_b128 v[226:229], v159 offset:36864
	ds_read_b128 v[230:233], v159 offset:37888
	ds_read_b128 v[234:237], v159 offset:38912
	ds_read_b128 v[238:241], v159 offset:39936
	global_load_lds_dwordx4 v[246:247], off
	v_lshl_add_u64 v[246:247], s[52:53], 0, v[146:147]
	s_mov_b32 m0, s75
	s_nop 0
	global_load_lds_dwordx4 v[246:247], off
	s_waitcnt vmcnt(8)
	s_waitcnt lgkmcnt(0)
	s_barrier
	s_setprio 1
	s_waitcnt lgkmcnt(0)
	v_mfma_f32_16x16x32_bf16 v[126:129], v[178:181], v[210:213], v[126:129]
	v_mfma_f32_16x16x32_bf16 v[122:125], v[186:189], v[210:213], v[122:125]
	v_mfma_f32_16x16x32_bf16 v[118:121], v[178:181], v[218:221], v[118:121]
	v_mfma_f32_16x16x32_bf16 v[114:117], v[186:189], v[218:221], v[114:117]
	v_mfma_f32_16x16x32_bf16 v[110:113], v[178:181], v[226:229], v[110:113]
	v_mfma_f32_16x16x32_bf16 v[106:109], v[186:189], v[226:229], v[106:109]
	v_mfma_f32_16x16x32_bf16 v[102:105], v[178:181], v[234:237], v[102:105]
	v_mfma_f32_16x16x32_bf16 v[98:101], v[186:189], v[234:237], v[98:101]
	v_mfma_f32_16x16x32_bf16 v[126:129], v[182:185], v[214:217], v[126:129]
	v_mfma_f32_16x16x32_bf16 v[122:125], v[190:193], v[214:217], v[122:125]
	v_mfma_f32_16x16x32_bf16 v[118:121], v[182:185], v[222:225], v[118:121]
	v_mfma_f32_16x16x32_bf16 v[114:117], v[190:193], v[222:225], v[114:117]
	v_mfma_f32_16x16x32_bf16 v[110:113], v[182:185], v[230:233], v[110:113]
	v_mfma_f32_16x16x32_bf16 v[106:109], v[190:193], v[230:233], v[106:109]
	v_mfma_f32_16x16x32_bf16 v[102:105], v[182:185], v[238:241], v[102:105]
	v_mfma_f32_16x16x32_bf16 v[98:101], v[190:193], v[238:241], v[98:101]
	s_setprio 0
	s_setprio 1
	v_mfma_f32_16x16x32_bf16 v[82:85], v[194:197], v[210:213], v[82:85]
	v_mfma_f32_16x16x32_bf16 v[74:77], v[202:205], v[210:213], v[74:77]
	v_mfma_f32_16x16x32_bf16 v[66:69], v[194:197], v[218:221], v[66:69]
	v_mfma_f32_16x16x32_bf16 v[58:61], v[202:205], v[218:221], v[58:61]
	v_mfma_f32_16x16x32_bf16 v[54:57], v[194:197], v[226:229], v[54:57]
	v_mfma_f32_16x16x32_bf16 v[46:49], v[202:205], v[226:229], v[46:49]
	v_mfma_f32_16x16x32_bf16 v[38:41], v[194:197], v[234:237], v[38:41]
	v_mfma_f32_16x16x32_bf16 v[34:37], v[202:205], v[234:237], v[34:37]
	v_mfma_f32_16x16x32_bf16 v[82:85], v[198:201], v[214:217], v[82:85]
	v_mfma_f32_16x16x32_bf16 v[74:77], v[206:209], v[214:217], v[74:77]
	v_mfma_f32_16x16x32_bf16 v[66:69], v[198:201], v[222:225], v[66:69]
	v_mfma_f32_16x16x32_bf16 v[58:61], v[206:209], v[222:225], v[58:61]
	v_mfma_f32_16x16x32_bf16 v[54:57], v[198:201], v[230:233], v[54:57]
	s_setprio 2
	s_barrier
	v_mfma_f32_16x16x32_bf16 v[46:49], v[206:209], v[230:233], v[46:49]
	v_mfma_f32_16x16x32_bf16 v[38:41], v[198:201], v[238:241], v[38:41]
	v_mfma_f32_16x16x32_bf16 v[34:37], v[206:209], v[238:241], v[34:37]
	s_setprio 0
	s_add_i32 s52, s70, s60
	v_lshl_add_u64 v[160:161], v[160:161], 0, s[66:67]
	s_mov_b32 m0, s52
	ds_read_b128 v[210:213], v159 offset:49152
	ds_read_b128 v[214:217], v159 offset:50176
	ds_read_b128 v[218:221], v159 offset:51200
	ds_read_b128 v[222:225], v159 offset:52224
	ds_read_b128 v[226:229], v159 offset:53248
	ds_read_b128 v[230:233], v159 offset:54272
	ds_read_b128 v[234:237], v159 offset:55296
	ds_read_b128 v[238:241], v159 offset:56320
	global_load_lds_dwordx4 v[160:161], off
	s_add_i32 m0, s52, 0x2000
	s_add_u32 s26, s26, 0x40080
	v_lshl_add_u64 v[160:161], v[164:165], 0, s[66:67]
	s_addc_u32 s27, s27, 0
	s_add_i32 s52, s71, s60
	global_load_lds_dwordx4 v[160:161], off
	v_lshl_add_u64 v[160:161], s[26:27], 0, v[134:135]
	s_mov_b32 m0, s52
	s_nop 0
	global_load_lds_dwordx4 v[160:161], off
	v_lshl_add_u64 v[160:161], s[26:27], 0, v[148:149]
	s_add_i32 m0, s52, 0x2000
	s_nop 0
	global_load_lds_dwordx4 v[160:161], off
	v_lshl_add_u64 v[160:161], v[242:243], 0, s[66:67]
	s_mov_b32 m0, s62
	s_nop 0
	global_load_lds_dwordx4 v[160:161], off
	v_lshl_add_u64 v[160:161], v[244:245], 0, s[66:67]
	s_mov_b32 m0, s19
	s_nop 0
	global_load_lds_dwordx4 v[160:161], off
	s_waitcnt vmcnt(8)
	s_waitcnt lgkmcnt(0)
	s_barrier
	s_setprio 1
	s_waitcnt lgkmcnt(0)
	v_mfma_f32_16x16x32_bf16 v[94:97], v[178:181], v[210:213], v[94:97]
	v_mfma_f32_16x16x32_bf16 v[90:93], v[186:189], v[210:213], v[90:93]
	v_mfma_f32_16x16x32_bf16 v[86:89], v[178:181], v[218:221], v[86:89]
	v_mfma_f32_16x16x32_bf16 v[78:81], v[186:189], v[218:221], v[78:81]
	v_mfma_f32_16x16x32_bf16 v[70:73], v[178:181], v[226:229], v[70:73]
	v_mfma_f32_16x16x32_bf16 v[62:65], v[186:189], v[226:229], v[62:65]
	v_mfma_f32_16x16x32_bf16 v[50:53], v[178:181], v[234:237], v[50:53]
	v_mfma_f32_16x16x32_bf16 v[42:45], v[186:189], v[234:237], v[42:45]
	v_mfma_f32_16x16x32_bf16 v[94:97], v[182:185], v[214:217], v[94:97]
	v_mfma_f32_16x16x32_bf16 v[90:93], v[190:193], v[214:217], v[90:93]
	v_mfma_f32_16x16x32_bf16 v[86:89], v[182:185], v[222:225], v[86:89]
	v_mfma_f32_16x16x32_bf16 v[78:81], v[190:193], v[222:225], v[78:81]
	v_mfma_f32_16x16x32_bf16 v[70:73], v[182:185], v[230:233], v[70:73]
	v_mfma_f32_16x16x32_bf16 v[62:65], v[190:193], v[230:233], v[62:65]
	v_mfma_f32_16x16x32_bf16 v[50:53], v[182:185], v[238:241], v[50:53]
	v_mfma_f32_16x16x32_bf16 v[42:45], v[190:193], v[238:241], v[42:45]
	s_setprio 0
	s_setprio 1
	v_mfma_f32_16x16x32_bf16 v[30:33], v[194:197], v[210:213], v[30:33]
	v_mfma_f32_16x16x32_bf16 v[26:29], v[202:205], v[210:213], v[26:29]
	v_mfma_f32_16x16x32_bf16 v[22:25], v[194:197], v[218:221], v[22:25]
	v_mfma_f32_16x16x32_bf16 v[18:21], v[202:205], v[218:221], v[18:21]
	v_mfma_f32_16x16x32_bf16 v[14:17], v[194:197], v[226:229], v[14:17]
	v_mfma_f32_16x16x32_bf16 v[10:13], v[202:205], v[226:229], v[10:13]
	v_mfma_f32_16x16x32_bf16 v[6:9], v[194:197], v[234:237], v[6:9]
	v_mfma_f32_16x16x32_bf16 v[2:5], v[202:205], v[234:237], v[2:5]
	v_mfma_f32_16x16x32_bf16 v[30:33], v[198:201], v[214:217], v[30:33]
	v_mfma_f32_16x16x32_bf16 v[26:29], v[206:209], v[214:217], v[26:29]
	v_mfma_f32_16x16x32_bf16 v[22:25], v[198:201], v[222:225], v[22:25]
	v_mfma_f32_16x16x32_bf16 v[18:21], v[206:209], v[222:225], v[18:21]
	v_mfma_f32_16x16x32_bf16 v[14:17], v[198:201], v[230:233], v[14:17]
	s_setprio 2
	s_barrier
	v_mfma_f32_16x16x32_bf16 v[10:13], v[206:209], v[230:233], v[10:13]
	v_mfma_f32_16x16x32_bf16 v[6:9], v[198:201], v[238:241], v[6:9]
	v_mfma_f32_16x16x32_bf16 v[2:5], v[206:209], v[238:241], v[2:5]
	s_setprio 0
	s_add_i32 s69, s69, 2
	s_add_u32 vcc_lo, vcc_lo, 0x100
	s_addc_u32 vcc_hi, vcc_hi, 0
	s_cmp_gt_u32 s69, 13
	s_cbranch_scc0 .LBB0_227
	s_and_b64 vcc, exec, s[98:99]
	s_cbranch_vccz .LBB0_230
	s_barrier

.Lpz_kvq:
	s_add_u32 s50, s98, 0xfffc0080
	s_addc_u32 s51, s99, -1
	s_add_i32 s72, 0, 0x10000
	s_cmp_eq_u32 s71, 12
	s_cselect_b32 s53, s60, s51
	s_cselect_b32 s52, s93, s50
	v_add_u32_e32 v162, s72, v159
	s_cselect_b32 s51, s47, s70
	s_cselect_b32 s50, vcc_lo, vcc_hi
	s_add_i32 s41, 0, 0x14000
	ds_read_b128 v[154:157], v162
	ds_read_b128 v[178:181], v162 offset:1024
	ds_read_b128 v[182:185], v162 offset:2048
	ds_read_b128 v[186:189], v162 offset:3072
	v_add_u32_e32 v162, s41, v159
	ds_read_b128 v[190:193], v162
	ds_read_b128 v[194:197], v162 offset:1024
	ds_read_b128 v[198:201], v162 offset:2048
	ds_read_b128 v[202:205], v162 offset:3072
	v_lshl_add_u64 v[164:165], s[98:99], 0, v[150:151]
	s_add_i32 m0, s27, 0xc000
	ds_read_b128 v[206:209], v161
	ds_read_b128 v[210:213], v161 offset:1024
	ds_read_b128 v[214:217], v161 offset:2048
	ds_read_b128 v[218:221], v161 offset:3072
	ds_read_b128 v[222:225], v161 offset:4096
	ds_read_b128 v[226:229], v161 offset:5120
	ds_read_b128 v[230:233], v161 offset:6144
	ds_read_b128 v[234:237], v161 offset:7168
	global_load_lds_dwordx4 v[164:165], off
	v_lshl_add_u64 v[164:165], s[98:99], 0, v[152:153]
	s_add_i32 m0, s27, 0xe000
	s_nop 0
	global_load_lds_dwordx4 v[164:165], off
	s_waitcnt vmcnt(24)
	s_waitcnt lgkmcnt(0)
	s_barrier
	s_setprio 1
	s_waitcnt lgkmcnt(0)
	v_mfma_f32_16x16x32_bf16 v[126:129], v[154:157], v[206:209], 0
	v_mfma_f32_16x16x32_bf16 v[122:125], v[182:185], v[206:209], 0
	v_mfma_f32_16x16x32_bf16 v[114:117], v[154:157], v[214:217], 0
	v_mfma_f32_16x16x32_bf16 v[106:109], v[182:185], v[214:217], 0
	v_mfma_f32_16x16x32_bf16 v[98:101], v[154:157], v[222:225], 0
	v_mfma_f32_16x16x32_bf16 v[90:93], v[182:185], v[222:225], 0
	v_mfma_f32_16x16x32_bf16 v[82:85], v[154:157], v[230:233], 0
	v_mfma_f32_16x16x32_bf16 v[74:77], v[182:185], v[230:233], 0
	v_mfma_f32_16x16x32_bf16 v[126:129], v[178:181], v[210:213], v[126:129]
	v_mfma_f32_16x16x32_bf16 v[122:125], v[186:189], v[210:213], v[122:125]
	v_mfma_f32_16x16x32_bf16 v[114:117], v[178:181], v[218:221], v[114:117]
	v_mfma_f32_16x16x32_bf16 v[106:109], v[186:189], v[218:221], v[106:109]
	v_mfma_f32_16x16x32_bf16 v[98:101], v[178:181], v[226:229], v[98:101]
	v_mfma_f32_16x16x32_bf16 v[90:93], v[186:189], v[226:229], v[90:93]
	v_mfma_f32_16x16x32_bf16 v[82:85], v[178:181], v[234:237], v[82:85]
	v_mfma_f32_16x16x32_bf16 v[74:77], v[186:189], v[234:237], v[74:77]
	s_setprio 0
	s_setprio 1
	v_mfma_f32_16x16x32_bf16 v[118:121], v[190:193], v[206:209], 0
	v_mfma_f32_16x16x32_bf16 v[110:113], v[198:201], v[206:209], 0
	v_mfma_f32_16x16x32_bf16 v[102:105], v[190:193], v[214:217], 0
	v_mfma_f32_16x16x32_bf16 v[94:97], v[198:201], v[214:217], 0
	v_mfma_f32_16x16x32_bf16 v[86:89], v[190:193], v[222:225], 0
	v_mfma_f32_16x16x32_bf16 v[78:81], v[198:201], v[222:225], 0
	v_mfma_f32_16x16x32_bf16 v[70:73], v[190:193], v[230:233], 0
	v_mfma_f32_16x16x32_bf16 v[66:69], v[198:201], v[230:233], 0
	v_mfma_f32_16x16x32_bf16 v[118:121], v[194:197], v[210:213], v[118:121]
	v_mfma_f32_16x16x32_bf16 v[110:113], v[202:205], v[210:213], v[110:113]
	v_mfma_f32_16x16x32_bf16 v[102:105], v[194:197], v[218:221], v[102:105]
	v_mfma_f32_16x16x32_bf16 v[94:97], v[202:205], v[218:221], v[94:97]
	v_mfma_f32_16x16x32_bf16 v[86:89], v[194:197], v[226:229], v[86:89]
	s_setprio 2
	s_barrier
	v_mfma_f32_16x16x32_bf16 v[78:81], v[202:205], v[226:229], v[78:81]
	v_mfma_f32_16x16x32_bf16 v[70:73], v[194:197], v[234:237], v[70:73]
	v_mfma_f32_16x16x32_bf16 v[66:69], v[202:205], v[234:237], v[66:69]
	s_setprio 0
	s_add_i32 s72, s72, s65
	v_lshl_add_u64 v[164:165], s[50:51], 0, v[146:147]
	s_mov_b32 m0, s72
	ds_read_b128 v[206:209], v161 offset:16384
	ds_read_b128 v[210:213], v161 offset:17408
	ds_read_b128 v[214:217], v161 offset:18432
	ds_read_b128 v[218:221], v161 offset:19456
	ds_read_b128 v[222:225], v161 offset:20480
	ds_read_b128 v[226:229], v161 offset:21504
	ds_read_b128 v[230:233], v161 offset:22528
	ds_read_b128 v[234:237], v161 offset:23552
	global_load_lds_dwordx4 v[164:165], off
	s_add_i32 m0, s72, 0x2000
	s_add_u32 s72, s50, 0x40000
	v_lshl_add_u64 v[238:239], s[50:51], 0, v[132:133]
	s_addc_u32 s73, s51, 0
	s_add_i32 s41, s41, s65
	global_load_lds_dwordx4 v[238:239], off
	v_lshl_add_u64 v[240:241], s[72:73], 0, v[146:147]
	s_mov_b32 m0, s41
	v_lshl_add_u64 v[242:243], s[52:53], 0, v[144:145]
	global_load_lds_dwordx4 v[240:241], off
	v_lshl_add_u64 v[240:241], s[72:73], 0, v[132:133]
	s_add_i32 m0, s41, 0x2000
	s_nop 0
	global_load_lds_dwordx4 v[240:241], off
	v_lshl_add_u64 v[240:241], s[52:53], 0, v[148:149]
	s_mov_b32 m0, s27
	s_nop 0
	global_load_lds_dwordx4 v[240:241], off
	s_mov_b32 m0, s74
	s_nop 0
	global_load_lds_dwordx4 v[242:243], off
	s_waitcnt vmcnt(24)
	s_waitcnt lgkmcnt(0)
	s_barrier
	s_setprio 1
	s_waitcnt lgkmcnt(0)
	v_mfma_f32_16x16x32_bf16 v[62:65], v[154:157], v[206:209], 0
	v_mfma_f32_16x16x32_bf16 v[58:61], v[182:185], v[206:209], 0
	v_mfma_f32_16x16x32_bf16 v[50:53], v[154:157], v[214:217], 0
	v_mfma_f32_16x16x32_bf16 v[42:45], v[182:185], v[214:217], 0
	v_mfma_f32_16x16x32_bf16 v[34:37], v[154:157], v[222:225], 0
	v_mfma_f32_16x16x32_bf16 v[26:29], v[182:185], v[222:225], 0
	v_mfma_f32_16x16x32_bf16 v[18:21], v[154:157], v[230:233], 0
	v_mfma_f32_16x16x32_bf16 v[10:13], v[182:185], v[230:233], 0
	v_mfma_f32_16x16x32_bf16 v[62:65], v[178:181], v[210:213], v[62:65]
	v_mfma_f32_16x16x32_bf16 v[58:61], v[186:189], v[210:213], v[58:61]
	v_mfma_f32_16x16x32_bf16 v[50:53], v[178:181], v[218:221], v[50:53]
	v_mfma_f32_16x16x32_bf16 v[42:45], v[186:189], v[218:221], v[42:45]
	v_mfma_f32_16x16x32_bf16 v[34:37], v[178:181], v[226:229], v[34:37]
	v_mfma_f32_16x16x32_bf16 v[26:29], v[186:189], v[226:229], v[26:29]
	v_mfma_f32_16x16x32_bf16 v[18:21], v[178:181], v[234:237], v[18:21]
	v_mfma_f32_16x16x32_bf16 v[10:13], v[186:189], v[234:237], v[10:13]
	s_setprio 0
	s_setprio 1
	v_mfma_f32_16x16x32_bf16 v[54:57], v[190:193], v[206:209], 0
	v_mfma_f32_16x16x32_bf16 v[46:49], v[198:201], v[206:209], 0
	v_mfma_f32_16x16x32_bf16 v[38:41], v[190:193], v[214:217], 0
	v_mfma_f32_16x16x32_bf16 v[30:33], v[198:201], v[214:217], 0
	v_mfma_f32_16x16x32_bf16 v[22:25], v[190:193], v[222:225], 0
	v_mfma_f32_16x16x32_bf16 v[14:17], v[198:201], v[222:225], 0
	v_mfma_f32_16x16x32_bf16 v[6:9], v[190:193], v[230:233], 0
	v_mfma_f32_16x16x32_bf16 v[2:5], v[198:201], v[230:233], 0
	v_mfma_f32_16x16x32_bf16 v[54:57], v[194:197], v[210:213], v[54:57]
	v_mfma_f32_16x16x32_bf16 v[46:49], v[202:205], v[210:213], v[46:49]
	v_mfma_f32_16x16x32_bf16 v[38:41], v[194:197], v[218:221], v[38:41]
	v_mfma_f32_16x16x32_bf16 v[30:33], v[202:205], v[218:221], v[30:33]
	v_mfma_f32_16x16x32_bf16 v[22:25], v[194:197], v[226:229], v[22:25]
	s_setprio 2
	s_barrier
	v_mfma_f32_16x16x32_bf16 v[14:17], v[202:205], v[226:229], v[14:17]
	v_mfma_f32_16x16x32_bf16 v[6:9], v[194:197], v[234:237], v[6:9]
	v_mfma_f32_16x16x32_bf16 v[2:5], v[202:205], v[234:237], v[2:5]
	s_setprio 0
	s_add_i32 s41, 0, 0x18000
	v_add_u32_e32 v162, s41, v159
	s_add_i32 s72, 0, 0x1c000
	ds_read_b128 v[154:157], v162
	ds_read_b128 v[178:181], v162 offset:1024
	ds_read_b128 v[182:185], v162 offset:2048
	ds_read_b128 v[186:189], v162 offset:3072
	v_add_u32_e32 v162, s72, v159
	ds_read_b128 v[190:193], v162
	ds_read_b128 v[194:197], v162 offset:1024
	ds_read_b128 v[198:201], v162 offset:2048
	ds_read_b128 v[202:205], v162 offset:3072
	s_add_u32 s52, s52, 0x40000
	s_addc_u32 s53, s53, 0
	s_mov_b32 m0, s75
	v_lshl_add_u64 v[244:245], s[52:53], 0, v[148:149]
	ds_read_b128 v[206:209], v161 offset:32768
	ds_read_b128 v[210:213], v161 offset:33792
	ds_read_b128 v[214:217], v161 offset:34816
	ds_read_b128 v[218:221], v161 offset:35840
	ds_read_b128 v[222:225], v161 offset:36864
	ds_read_b128 v[226:229], v161 offset:37888
	ds_read_b128 v[230:233], v161 offset:38912
	ds_read_b128 v[234:237], v161 offset:39936
	global_load_lds_dwordx4 v[244:245], off
	v_lshl_add_u64 v[244:245], s[52:53], 0, v[144:145]
	s_mov_b32 m0, s97
	s_nop 0
	global_load_lds_dwordx4 v[244:245], off
	s_waitcnt vmcnt(8)
	s_waitcnt lgkmcnt(0)
	s_barrier
	s_setprio 1
	s_waitcnt lgkmcnt(0)
	v_mfma_f32_16x16x32_bf16 v[126:129], v[154:157], v[206:209], v[126:129]
	v_mfma_f32_16x16x32_bf16 v[122:125], v[182:185], v[206:209], v[122:125]
	v_mfma_f32_16x16x32_bf16 v[114:117], v[154:157], v[214:217], v[114:117]
	v_mfma_f32_16x16x32_bf16 v[106:109], v[182:185], v[214:217], v[106:109]
	v_mfma_f32_16x16x32_bf16 v[98:101], v[154:157], v[222:225], v[98:101]
	v_mfma_f32_16x16x32_bf16 v[90:93], v[182:185], v[222:225], v[90:93]
	v_mfma_f32_16x16x32_bf16 v[82:85], v[154:157], v[230:233], v[82:85]
	v_mfma_f32_16x16x32_bf16 v[74:77], v[182:185], v[230:233], v[74:77]
	v_mfma_f32_16x16x32_bf16 v[126:129], v[178:181], v[210:213], v[126:129]
	v_mfma_f32_16x16x32_bf16 v[122:125], v[186:189], v[210:213], v[122:125]
	v_mfma_f32_16x16x32_bf16 v[114:117], v[178:181], v[218:221], v[114:117]
	v_mfma_f32_16x16x32_bf16 v[106:109], v[186:189], v[218:221], v[106:109]
	v_mfma_f32_16x16x32_bf16 v[98:101], v[178:181], v[226:229], v[98:101]
	v_mfma_f32_16x16x32_bf16 v[90:93], v[186:189], v[226:229], v[90:93]
	v_mfma_f32_16x16x32_bf16 v[82:85], v[178:181], v[234:237], v[82:85]
	v_mfma_f32_16x16x32_bf16 v[74:77], v[186:189], v[234:237], v[74:77]
	s_setprio 0
	s_setprio 1
	v_mfma_f32_16x16x32_bf16 v[118:121], v[190:193], v[206:209], v[118:121]
	v_mfma_f32_16x16x32_bf16 v[110:113], v[198:201], v[206:209], v[110:113]
	v_mfma_f32_16x16x32_bf16 v[102:105], v[190:193], v[214:217], v[102:105]
	v_mfma_f32_16x16x32_bf16 v[94:97], v[198:201], v[214:217], v[94:97]
	v_mfma_f32_16x16x32_bf16 v[86:89], v[190:193], v[222:225], v[86:89]
	v_mfma_f32_16x16x32_bf16 v[78:81], v[198:201], v[222:225], v[78:81]
	v_mfma_f32_16x16x32_bf16 v[70:73], v[190:193], v[230:233], v[70:73]
	v_mfma_f32_16x16x32_bf16 v[66:69], v[198:201], v[230:233], v[66:69]
	v_mfma_f32_16x16x32_bf16 v[118:121], v[194:197], v[210:213], v[118:121]
	v_mfma_f32_16x16x32_bf16 v[110:113], v[202:205], v[210:213], v[110:113]
	v_mfma_f32_16x16x32_bf16 v[102:105], v[194:197], v[218:221], v[102:105]
	v_mfma_f32_16x16x32_bf16 v[94:97], v[202:205], v[218:221], v[94:97]
	v_mfma_f32_16x16x32_bf16 v[86:89], v[194:197], v[226:229], v[86:89]
	s_setprio 2
	s_barrier
	v_mfma_f32_16x16x32_bf16 v[78:81], v[202:205], v[226:229], v[78:81]
	v_mfma_f32_16x16x32_bf16 v[70:73], v[194:197], v[234:237], v[70:73]
	v_mfma_f32_16x16x32_bf16 v[66:69], v[202:205], v[234:237], v[66:69]
	s_setprio 0
	s_add_i32 s41, s41, s65
	v_lshl_add_u64 v[164:165], v[164:165], 0, s[66:67]
	s_mov_b32 m0, s41
	ds_read_b128 v[206:209], v161 offset:49152
	ds_read_b128 v[210:213], v161 offset:50176
	ds_read_b128 v[214:217], v161 offset:51200
	ds_read_b128 v[218:221], v161 offset:52224
	ds_read_b128 v[222:225], v161 offset:53248
	ds_read_b128 v[226:229], v161 offset:54272
	ds_read_b128 v[230:233], v161 offset:55296
	ds_read_b128 v[234:237], v161 offset:56320
	global_load_lds_dwordx4 v[164:165], off
	s_add_i32 m0, s41, 0x2000
	s_add_u32 s50, s50, 0x40080
	v_lshl_add_u64 v[164:165], v[238:239], 0, s[66:67]
	s_addc_u32 s51, s51, 0
	s_add_i32 s41, s72, s65
	global_load_lds_dwordx4 v[164:165], off
	v_lshl_add_u64 v[164:165], s[50:51], 0, v[146:147]
	s_mov_b32 m0, s41
	s_nop 0
	global_load_lds_dwordx4 v[164:165], off
	v_lshl_add_u64 v[164:165], s[50:51], 0, v[132:133]
	s_add_i32 m0, s41, 0x2000
	s_nop 0
	global_load_lds_dwordx4 v[164:165], off
	v_lshl_add_u64 v[164:165], v[240:241], 0, s[66:67]
	s_mov_b32 m0, s24
	s_nop 0
	global_load_lds_dwordx4 v[164:165], off
	v_lshl_add_u64 v[164:165], v[242:243], 0, s[66:67]
	s_mov_b32 m0, s25
	s_nop 0
	global_load_lds_dwordx4 v[164:165], off
	s_waitcnt vmcnt(8)
	s_waitcnt lgkmcnt(0)
	s_barrier
	s_setprio 1
	s_waitcnt lgkmcnt(0)
	v_mfma_f32_16x16x32_bf16 v[62:65], v[154:157], v[206:209], v[62:65]
	v_mfma_f32_16x16x32_bf16 v[58:61], v[182:185], v[206:209], v[58:61]
	v_mfma_f32_16x16x32_bf16 v[50:53], v[154:157], v[214:217], v[50:53]
	v_mfma_f32_16x16x32_bf16 v[42:45], v[182:185], v[214:217], v[42:45]
	v_mfma_f32_16x16x32_bf16 v[34:37], v[154:157], v[222:225], v[34:37]
	v_mfma_f32_16x16x32_bf16 v[26:29], v[182:185], v[222:225], v[26:29]
	v_mfma_f32_16x16x32_bf16 v[18:21], v[154:157], v[230:233], v[18:21]
	v_mfma_f32_16x16x32_bf16 v[10:13], v[182:185], v[230:233], v[10:13]
	v_mfma_f32_16x16x32_bf16 v[62:65], v[178:181], v[210:213], v[62:65]
	v_mfma_f32_16x16x32_bf16 v[58:61], v[186:189], v[210:213], v[58:61]
	v_mfma_f32_16x16x32_bf16 v[50:53], v[178:181], v[218:221], v[50:53]
	v_mfma_f32_16x16x32_bf16 v[42:45], v[186:189], v[218:221], v[42:45]
	v_mfma_f32_16x16x32_bf16 v[34:37], v[178:181], v[226:229], v[34:37]
	v_mfma_f32_16x16x32_bf16 v[26:29], v[186:189], v[226:229], v[26:29]
	v_mfma_f32_16x16x32_bf16 v[18:21], v[178:181], v[234:237], v[18:21]
	v_mfma_f32_16x16x32_bf16 v[10:13], v[186:189], v[234:237], v[10:13]
	s_setprio 0
	s_setprio 1
	v_mfma_f32_16x16x32_bf16 v[54:57], v[190:193], v[206:209], v[54:57]
	v_mfma_f32_16x16x32_bf16 v[46:49], v[198:201], v[206:209], v[46:49]
	v_mfma_f32_16x16x32_bf16 v[38:41], v[190:193], v[214:217], v[38:41]
	v_mfma_f32_16x16x32_bf16 v[30:33], v[198:201], v[214:217], v[30:33]
	v_mfma_f32_16x16x32_bf16 v[22:25], v[190:193], v[222:225], v[22:25]
	v_mfma_f32_16x16x32_bf16 v[14:17], v[198:201], v[222:225], v[14:17]
	v_mfma_f32_16x16x32_bf16 v[6:9], v[190:193], v[230:233], v[6:9]
	v_mfma_f32_16x16x32_bf16 v[2:5], v[198:201], v[230:233], v[2:5]
	v_mfma_f32_16x16x32_bf16 v[54:57], v[194:197], v[210:213], v[54:57]
	v_mfma_f32_16x16x32_bf16 v[46:49], v[202:205], v[210:213], v[46:49]
	v_mfma_f32_16x16x32_bf16 v[38:41], v[194:197], v[218:221], v[38:41]
	v_mfma_f32_16x16x32_bf16 v[30:33], v[202:205], v[218:221], v[30:33]
	v_mfma_f32_16x16x32_bf16 v[22:25], v[194:197], v[226:229], v[22:25]
	s_setprio 2
	s_barrier
	v_mfma_f32_16x16x32_bf16 v[14:17], v[202:205], v[226:229], v[14:17]
	v_mfma_f32_16x16x32_bf16 v[6:9], v[194:197], v[234:237], v[6:9]
	v_mfma_f32_16x16x32_bf16 v[2:5], v[202:205], v[234:237], v[2:5]
	s_setprio 0
	s_add_i32 s71, s71, 2
	s_add_u32 s98, s98, 0x100
	s_addc_u32 s99, s99, 0
	s_add_u32 vcc_hi, vcc_hi, 0x100
	s_addc_u32 s70, s70, 0
	s_cmp_gt_u32 s71, 13
.LBB0_259:
	s_add_u32 s50, s98, 0xfffc0080
	s_addc_u32 s51, s99, -1
	s_add_i32 s72, 0, 0x10000
	s_cmp_eq_u32 s71, 12
	s_cselect_b32 s53, s60, s51
	s_cselect_b32 s52, s93, s50
	v_add_u32_e32 v162, s72, v159
	s_cselect_b32 s51, s47, s70
	s_cselect_b32 s50, vcc_lo, vcc_hi
	s_add_i32 s41, 0, 0x14000
	ds_read_b128 v[154:157], v162
	ds_read_b128 v[178:181], v162 offset:1024
	ds_read_b128 v[182:185], v162 offset:2048
	ds_read_b128 v[186:189], v162 offset:3072
	v_add_u32_e32 v162, s41, v159
	ds_read_b128 v[190:193], v162
	ds_read_b128 v[194:197], v162 offset:1024
	ds_read_b128 v[198:201], v162 offset:2048
	ds_read_b128 v[202:205], v162 offset:3072
	v_lshl_add_u64 v[164:165], s[98:99], 0, v[150:151]
	s_add_i32 m0, s27, 0xc000
	ds_read_b128 v[206:209], v161
	ds_read_b128 v[210:213], v161 offset:1024
	ds_read_b128 v[214:217], v161 offset:2048
	ds_read_b128 v[218:221], v161 offset:3072
	ds_read_b128 v[222:225], v161 offset:4096
	ds_read_b128 v[226:229], v161 offset:5120
	ds_read_b128 v[230:233], v161 offset:6144
	ds_read_b128 v[234:237], v161 offset:7168
	global_load_lds_dwordx4 v[164:165], off
	v_lshl_add_u64 v[164:165], s[98:99], 0, v[152:153]
	s_add_i32 m0, s27, 0xe000
	s_nop 0
	global_load_lds_dwordx4 v[164:165], off
	s_waitcnt vmcnt(8)
	s_waitcnt lgkmcnt(0)
	s_barrier
	s_setprio 1
	s_waitcnt lgkmcnt(0)
	v_mfma_f32_16x16x32_bf16 v[126:129], v[154:157], v[206:209], v[126:129]
	v_mfma_f32_16x16x32_bf16 v[122:125], v[182:185], v[206:209], v[122:125]
	v_mfma_f32_16x16x32_bf16 v[114:117], v[154:157], v[214:217], v[114:117]
	v_mfma_f32_16x16x32_bf16 v[106:109], v[182:185], v[214:217], v[106:109]
	v_mfma_f32_16x16x32_bf16 v[98:101], v[154:157], v[222:225], v[98:101]
	v_mfma_f32_16x16x32_bf16 v[90:93], v[182:185], v[222:225], v[90:93]
	v_mfma_f32_16x16x32_bf16 v[82:85], v[154:157], v[230:233], v[82:85]
	v_mfma_f32_16x16x32_bf16 v[74:77], v[182:185], v[230:233], v[74:77]
	v_mfma_f32_16x16x32_bf16 v[126:129], v[178:181], v[210:213], v[126:129]
	v_mfma_f32_16x16x32_bf16 v[122:125], v[186:189], v[210:213], v[122:125]
	v_mfma_f32_16x16x32_bf16 v[114:117], v[178:181], v[218:221], v[114:117]
	v_mfma_f32_16x16x32_bf16 v[106:109], v[186:189], v[218:221], v[106:109]
	v_mfma_f32_16x16x32_bf16 v[98:101], v[178:181], v[226:229], v[98:101]
	v_mfma_f32_16x16x32_bf16 v[90:93], v[186:189], v[226:229], v[90:93]
	v_mfma_f32_16x16x32_bf16 v[82:85], v[178:181], v[234:237], v[82:85]
	v_mfma_f32_16x16x32_bf16 v[74:77], v[186:189], v[234:237], v[74:77]
	s_setprio 0
	s_setprio 1
	v_mfma_f32_16x16x32_bf16 v[118:121], v[190:193], v[206:209], v[118:121]
	v_mfma_f32_16x16x32_bf16 v[110:113], v[198:201], v[206:209], v[110:113]
	v_mfma_f32_16x16x32_bf16 v[102:105], v[190:193], v[214:217], v[102:105]
	v_mfma_f32_16x16x32_bf16 v[94:97], v[198:201], v[214:217], v[94:97]
	v_mfma_f32_16x16x32_bf16 v[86:89], v[190:193], v[222:225], v[86:89]
	v_mfma_f32_16x16x32_bf16 v[78:81], v[198:201], v[222:225], v[78:81]
	v_mfma_f32_16x16x32_bf16 v[70:73], v[190:193], v[230:233], v[70:73]
	v_mfma_f32_16x16x32_bf16 v[66:69], v[198:201], v[230:233], v[66:69]
	v_mfma_f32_16x16x32_bf16 v[118:121], v[194:197], v[210:213], v[118:121]
	v_mfma_f32_16x16x32_bf16 v[110:113], v[202:205], v[210:213], v[110:113]
	v_mfma_f32_16x16x32_bf16 v[102:105], v[194:197], v[218:221], v[102:105]
	v_mfma_f32_16x16x32_bf16 v[94:97], v[202:205], v[218:221], v[94:97]
	v_mfma_f32_16x16x32_bf16 v[86:89], v[194:197], v[226:229], v[86:89]
	s_setprio 2
	s_barrier
	v_mfma_f32_16x16x32_bf16 v[78:81], v[202:205], v[226:229], v[78:81]
	v_mfma_f32_16x16x32_bf16 v[70:73], v[194:197], v[234:237], v[70:73]
	v_mfma_f32_16x16x32_bf16 v[66:69], v[202:205], v[234:237], v[66:69]
	s_setprio 0
	s_add_i32 s72, s72, s65
	v_lshl_add_u64 v[164:165], s[50:51], 0, v[146:147]
	s_mov_b32 m0, s72
	ds_read_b128 v[206:209], v161 offset:16384
	ds_read_b128 v[210:213], v161 offset:17408
	ds_read_b128 v[214:217], v161 offset:18432
	ds_read_b128 v[218:221], v161 offset:19456
	ds_read_b128 v[222:225], v161 offset:20480
	ds_read_b128 v[226:229], v161 offset:21504
	ds_read_b128 v[230:233], v161 offset:22528
	ds_read_b128 v[234:237], v161 offset:23552
	global_load_lds_dwordx4 v[164:165], off
	s_add_i32 m0, s72, 0x2000
	s_add_u32 s72, s50, 0x40000
	v_lshl_add_u64 v[238:239], s[50:51], 0, v[132:133]
	s_addc_u32 s73, s51, 0
	s_add_i32 s41, s41, s65
	global_load_lds_dwordx4 v[238:239], off
	v_lshl_add_u64 v[240:241], s[72:73], 0, v[146:147]
	s_mov_b32 m0, s41
	v_lshl_add_u64 v[242:243], s[52:53], 0, v[144:145]
	global_load_lds_dwordx4 v[240:241], off
	v_lshl_add_u64 v[240:241], s[72:73], 0, v[132:133]
	s_add_i32 m0, s41, 0x2000
	s_nop 0
	global_load_lds_dwordx4 v[240:241], off
	v_lshl_add_u64 v[240:241], s[52:53], 0, v[148:149]
	s_mov_b32 m0, s27
	s_nop 0
	global_load_lds_dwordx4 v[240:241], off
	s_mov_b32 m0, s74
	s_nop 0
	global_load_lds_dwordx4 v[242:243], off
	s_waitcnt vmcnt(8)
	s_waitcnt lgkmcnt(0)
	s_barrier
	s_setprio 1
	s_waitcnt lgkmcnt(0)
	v_mfma_f32_16x16x32_bf16 v[62:65], v[154:157], v[206:209], v[62:65]
	v_mfma_f32_16x16x32_bf16 v[58:61], v[182:185], v[206:209], v[58:61]
	v_mfma_f32_16x16x32_bf16 v[50:53], v[154:157], v[214:217], v[50:53]
	v_mfma_f32_16x16x32_bf16 v[42:45], v[182:185], v[214:217], v[42:45]
	v_mfma_f32_16x16x32_bf16 v[34:37], v[154:157], v[222:225], v[34:37]
	v_mfma_f32_16x16x32_bf16 v[26:29], v[182:185], v[222:225], v[26:29]
	v_mfma_f32_16x16x32_bf16 v[18:21], v[154:157], v[230:233], v[18:21]
	v_mfma_f32_16x16x32_bf16 v[10:13], v[182:185], v[230:233], v[10:13]
	v_mfma_f32_16x16x32_bf16 v[62:65], v[178:181], v[210:213], v[62:65]
	v_mfma_f32_16x16x32_bf16 v[58:61], v[186:189], v[210:213], v[58:61]
	v_mfma_f32_16x16x32_bf16 v[50:53], v[178:181], v[218:221], v[50:53]
	v_mfma_f32_16x16x32_bf16 v[42:45], v[186:189], v[218:221], v[42:45]
	v_mfma_f32_16x16x32_bf16 v[34:37], v[178:181], v[226:229], v[34:37]
	v_mfma_f32_16x16x32_bf16 v[26:29], v[186:189], v[226:229], v[26:29]
	v_mfma_f32_16x16x32_bf16 v[18:21], v[178:181], v[234:237], v[18:21]
	v_mfma_f32_16x16x32_bf16 v[10:13], v[186:189], v[234:237], v[10:13]
	s_setprio 0
	s_setprio 1
	v_mfma_f32_16x16x32_bf16 v[54:57], v[190:193], v[206:209], v[54:57]
	v_mfma_f32_16x16x32_bf16 v[46:49], v[198:201], v[206:209], v[46:49]
	v_mfma_f32_16x16x32_bf16 v[38:41], v[190:193], v[214:217], v[38:41]
	v_mfma_f32_16x16x32_bf16 v[30:33], v[198:201], v[214:217], v[30:33]
	v_mfma_f32_16x16x32_bf16 v[22:25], v[190:193], v[222:225], v[22:25]
	v_mfma_f32_16x16x32_bf16 v[14:17], v[198:201], v[222:225], v[14:17]
	v_mfma_f32_16x16x32_bf16 v[6:9], v[190:193], v[230:233], v[6:9]
	v_mfma_f32_16x16x32_bf16 v[2:5], v[198:201], v[230:233], v[2:5]
	v_mfma_f32_16x16x32_bf16 v[54:57], v[194:197], v[210:213], v[54:57]
	v_mfma_f32_16x16x32_bf16 v[46:49], v[202:205], v[210:213], v[46:49]
	v_mfma_f32_16x16x32_bf16 v[38:41], v[194:197], v[218:221], v[38:41]
	v_mfma_f32_16x16x32_bf16 v[30:33], v[202:205], v[218:221], v[30:33]
	v_mfma_f32_16x16x32_bf16 v[22:25], v[194:197], v[226:229], v[22:25]
	s_setprio 2
	s_barrier
	v_mfma_f32_16x16x32_bf16 v[14:17], v[202:205], v[226:229], v[14:17]
	v_mfma_f32_16x16x32_bf16 v[6:9], v[194:197], v[234:237], v[6:9]
	v_mfma_f32_16x16x32_bf16 v[2:5], v[202:205], v[234:237], v[2:5]
	s_setprio 0
	s_add_i32 s41, 0, 0x18000
	v_add_u32_e32 v162, s41, v159
	s_add_i32 s72, 0, 0x1c000
	ds_read_b128 v[154:157], v162
	ds_read_b128 v[178:181], v162 offset:1024
	ds_read_b128 v[182:185], v162 offset:2048
	ds_read_b128 v[186:189], v162 offset:3072
	v_add_u32_e32 v162, s72, v159
	ds_read_b128 v[190:193], v162
	ds_read_b128 v[194:197], v162 offset:1024
	ds_read_b128 v[198:201], v162 offset:2048
	ds_read_b128 v[202:205], v162 offset:3072
	s_add_u32 s52, s52, 0x40000
	s_addc_u32 s53, s53, 0
	s_mov_b32 m0, s75
	v_lshl_add_u64 v[244:245], s[52:53], 0, v[148:149]
	ds_read_b128 v[206:209], v161 offset:32768
	ds_read_b128 v[210:213], v161 offset:33792
	ds_read_b128 v[214:217], v161 offset:34816
	ds_read_b128 v[218:221], v161 offset:35840
	ds_read_b128 v[222:225], v161 offset:36864
	ds_read_b128 v[226:229], v161 offset:37888
	ds_read_b128 v[230:233], v161 offset:38912
	ds_read_b128 v[234:237], v161 offset:39936
	global_load_lds_dwordx4 v[244:245], off
	v_lshl_add_u64 v[244:245], s[52:53], 0, v[144:145]
	s_mov_b32 m0, s97
	s_nop 0
	global_load_lds_dwordx4 v[244:245], off
	s_waitcnt vmcnt(8)
	s_waitcnt lgkmcnt(0)
	s_barrier
	s_setprio 1
	s_waitcnt lgkmcnt(0)
	v_mfma_f32_16x16x32_bf16 v[126:129], v[154:157], v[206:209], v[126:129]
	v_mfma_f32_16x16x32_bf16 v[122:125], v[182:185], v[206:209], v[122:125]
	v_mfma_f32_16x16x32_bf16 v[114:117], v[154:157], v[214:217], v[114:117]
	v_mfma_f32_16x16x32_bf16 v[106:109], v[182:185], v[214:217], v[106:109]
	v_mfma_f32_16x16x32_bf16 v[98:101], v[154:157], v[222:225], v[98:101]
	v_mfma_f32_16x16x32_bf16 v[90:93], v[182:185], v[222:225], v[90:93]
	v_mfma_f32_16x16x32_bf16 v[82:85], v[154:157], v[230:233], v[82:85]
	v_mfma_f32_16x16x32_bf16 v[74:77], v[182:185], v[230:233], v[74:77]
	v_mfma_f32_16x16x32_bf16 v[126:129], v[178:181], v[210:213], v[126:129]
	v_mfma_f32_16x16x32_bf16 v[122:125], v[186:189], v[210:213], v[122:125]
	v_mfma_f32_16x16x32_bf16 v[114:117], v[178:181], v[218:221], v[114:117]
	v_mfma_f32_16x16x32_bf16 v[106:109], v[186:189], v[218:221], v[106:109]
	v_mfma_f32_16x16x32_bf16 v[98:101], v[178:181], v[226:229], v[98:101]
	v_mfma_f32_16x16x32_bf16 v[90:93], v[186:189], v[226:229], v[90:93]
	v_mfma_f32_16x16x32_bf16 v[82:85], v[178:181], v[234:237], v[82:85]
	v_mfma_f32_16x16x32_bf16 v[74:77], v[186:189], v[234:237], v[74:77]
	s_setprio 0
	s_setprio 1
	v_mfma_f32_16x16x32_bf16 v[118:121], v[190:193], v[206:209], v[118:121]
	v_mfma_f32_16x16x32_bf16 v[110:113], v[198:201], v[206:209], v[110:113]
	v_mfma_f32_16x16x32_bf16 v[102:105], v[190:193], v[214:217], v[102:105]
	v_mfma_f32_16x16x32_bf16 v[94:97], v[198:201], v[214:217], v[94:97]
	v_mfma_f32_16x16x32_bf16 v[86:89], v[190:193], v[222:225], v[86:89]
	v_mfma_f32_16x16x32_bf16 v[78:81], v[198:201], v[222:225], v[78:81]
	v_mfma_f32_16x16x32_bf16 v[70:73], v[190:193], v[230:233], v[70:73]
	v_mfma_f32_16x16x32_bf16 v[66:69], v[198:201], v[230:233], v[66:69]
	v_mfma_f32_16x16x32_bf16 v[118:121], v[194:197], v[210:213], v[118:121]
	v_mfma_f32_16x16x32_bf16 v[110:113], v[202:205], v[210:213], v[110:113]
	v_mfma_f32_16x16x32_bf16 v[102:105], v[194:197], v[218:221], v[102:105]
	v_mfma_f32_16x16x32_bf16 v[94:97], v[202:205], v[218:221], v[94:97]
	v_mfma_f32_16x16x32_bf16 v[86:89], v[194:197], v[226:229], v[86:89]
	s_setprio 2
	s_barrier
	v_mfma_f32_16x16x32_bf16 v[78:81], v[202:205], v[226:229], v[78:81]
	v_mfma_f32_16x16x32_bf16 v[70:73], v[194:197], v[234:237], v[70:73]
	v_mfma_f32_16x16x32_bf16 v[66:69], v[202:205], v[234:237], v[66:69]
	s_setprio 0
	s_add_i32 s41, s41, s65
	v_lshl_add_u64 v[164:165], v[164:165], 0, s[66:67]
	s_mov_b32 m0, s41
	ds_read_b128 v[206:209], v161 offset:49152
	ds_read_b128 v[210:213], v161 offset:50176
	ds_read_b128 v[214:217], v161 offset:51200
	ds_read_b128 v[218:221], v161 offset:52224
	ds_read_b128 v[222:225], v161 offset:53248
	ds_read_b128 v[226:229], v161 offset:54272
	ds_read_b128 v[230:233], v161 offset:55296
	ds_read_b128 v[234:237], v161 offset:56320
	global_load_lds_dwordx4 v[164:165], off
	s_add_i32 m0, s41, 0x2000
	s_add_u32 s50, s50, 0x40080
	v_lshl_add_u64 v[164:165], v[238:239], 0, s[66:67]
	s_addc_u32 s51, s51, 0
	s_add_i32 s41, s72, s65
	global_load_lds_dwordx4 v[164:165], off
	v_lshl_add_u64 v[164:165], s[50:51], 0, v[146:147]
	s_mov_b32 m0, s41
	s_nop 0
	global_load_lds_dwordx4 v[164:165], off
	v_lshl_add_u64 v[164:165], s[50:51], 0, v[132:133]
	s_add_i32 m0, s41, 0x2000
	s_nop 0
	global_load_lds_dwordx4 v[164:165], off
	v_lshl_add_u64 v[164:165], v[240:241], 0, s[66:67]
	s_mov_b32 m0, s24
	s_nop 0
	global_load_lds_dwordx4 v[164:165], off
	v_lshl_add_u64 v[164:165], v[242:243], 0, s[66:67]
	s_mov_b32 m0, s25
	s_nop 0
	global_load_lds_dwordx4 v[164:165], off
	s_waitcnt vmcnt(8)
	s_waitcnt lgkmcnt(0)
	s_barrier
	s_setprio 1
	s_waitcnt lgkmcnt(0)
	v_mfma_f32_16x16x32_bf16 v[62:65], v[154:157], v[206:209], v[62:65]
	v_mfma_f32_16x16x32_bf16 v[58:61], v[182:185], v[206:209], v[58:61]
	v_mfma_f32_16x16x32_bf16 v[50:53], v[154:157], v[214:217], v[50:53]
	v_mfma_f32_16x16x32_bf16 v[42:45], v[182:185], v[214:217], v[42:45]
	v_mfma_f32_16x16x32_bf16 v[34:37], v[154:157], v[222:225], v[34:37]
	v_mfma_f32_16x16x32_bf16 v[26:29], v[182:185], v[222:225], v[26:29]
	v_mfma_f32_16x16x32_bf16 v[18:21], v[154:157], v[230:233], v[18:21]
	v_mfma_f32_16x16x32_bf16 v[10:13], v[182:185], v[230:233], v[10:13]
	v_mfma_f32_16x16x32_bf16 v[62:65], v[178:181], v[210:213], v[62:65]
	v_mfma_f32_16x16x32_bf16 v[58:61], v[186:189], v[210:213], v[58:61]
	v_mfma_f32_16x16x32_bf16 v[50:53], v[178:181], v[218:221], v[50:53]
	v_mfma_f32_16x16x32_bf16 v[42:45], v[186:189], v[218:221], v[42:45]
	v_mfma_f32_16x16x32_bf16 v[34:37], v[178:181], v[226:229], v[34:37]
	v_mfma_f32_16x16x32_bf16 v[26:29], v[186:189], v[226:229], v[26:29]
	v_mfma_f32_16x16x32_bf16 v[18:21], v[178:181], v[234:237], v[18:21]
	v_mfma_f32_16x16x32_bf16 v[10:13], v[186:189], v[234:237], v[10:13]
	s_setprio 0
	s_setprio 1
	v_mfma_f32_16x16x32_bf16 v[54:57], v[190:193], v[206:209], v[54:57]
	v_mfma_f32_16x16x32_bf16 v[46:49], v[198:201], v[206:209], v[46:49]
	v_mfma_f32_16x16x32_bf16 v[38:41], v[190:193], v[214:217], v[38:41]
	v_mfma_f32_16x16x32_bf16 v[30:33], v[198:201], v[214:217], v[30:33]
	v_mfma_f32_16x16x32_bf16 v[22:25], v[190:193], v[222:225], v[22:25]
	v_mfma_f32_16x16x32_bf16 v[14:17], v[198:201], v[222:225], v[14:17]
	v_mfma_f32_16x16x32_bf16 v[6:9], v[190:193], v[230:233], v[6:9]
	v_mfma_f32_16x16x32_bf16 v[2:5], v[198:201], v[230:233], v[2:5]
	v_mfma_f32_16x16x32_bf16 v[54:57], v[194:197], v[210:213], v[54:57]
	v_mfma_f32_16x16x32_bf16 v[46:49], v[202:205], v[210:213], v[46:49]
	v_mfma_f32_16x16x32_bf16 v[38:41], v[194:197], v[218:221], v[38:41]
	v_mfma_f32_16x16x32_bf16 v[30:33], v[202:205], v[218:221], v[30:33]
	v_mfma_f32_16x16x32_bf16 v[22:25], v[194:197], v[226:229], v[22:25]
	s_setprio 2
	s_barrier
	v_mfma_f32_16x16x32_bf16 v[14:17], v[202:205], v[226:229], v[14:17]
	v_mfma_f32_16x16x32_bf16 v[6:9], v[194:197], v[234:237], v[6:9]
	v_mfma_f32_16x16x32_bf16 v[2:5], v[202:205], v[234:237], v[2:5]
	s_setprio 0
	s_add_i32 s71, s71, 2
	s_add_u32 s98, s98, 0x100
	s_addc_u32 s99, s99, 0
	s_add_u32 vcc_hi, vcc_hi, 0x100
	s_addc_u32 s70, s70, 0
	s_cmp_gt_u32 s71, 13
	s_cbranch_scc0 .LBB0_259
	s_and_b64 vcc, exec, s[44:45]
	s_cbranch_vccz .LBB0_262
	s_barrier

.Lpz_up:
	s_add_u32 s26, s22, 0xfffc0080
	s_addc_u32 s27, s23, -1
	s_add_i32 s69, 0, 0x10000
	s_cmp_eq_u32 s68, 12
	s_cselect_b32 s45, s30, s27
	s_cselect_b32 s44, s37, s26
	v_add_u32_e32 v156, s69, v152
	s_cselect_b32 s27, s13, s65
	s_cselect_b32 s26, s47, s56
	s_add_i32 s72, 0, 0x14000
	ds_read_b128 v[178:181], v156
	ds_read_b128 v[182:185], v156 offset:1024
	ds_read_b128 v[186:189], v156 offset:2048
	ds_read_b128 v[190:193], v156 offset:3072
	v_add_u32_e32 v156, s72, v152
	ds_read_b128 v[194:197], v156
	ds_read_b128 v[198:201], v156 offset:1024
	ds_read_b128 v[202:205], v156 offset:2048
	ds_read_b128 v[206:209], v156 offset:3072
	v_lshl_add_u64 v[156:157], s[22:23], 0, v[148:149]
	s_add_i32 m0, s50, 0xc000
	ds_read_b128 v[210:213], v155
	ds_read_b128 v[214:217], v155 offset:1024
	ds_read_b128 v[218:221], v155 offset:2048
	ds_read_b128 v[222:225], v155 offset:3072
	ds_read_b128 v[226:229], v155 offset:4096
	ds_read_b128 v[230:233], v155 offset:5120
	ds_read_b128 v[234:237], v155 offset:6144
	ds_read_b128 v[238:241], v155 offset:7168
	global_load_lds_dwordx4 v[156:157], off
	v_lshl_add_u64 v[156:157], s[22:23], 0, v[150:151]
	s_add_i32 m0, s50, 0xe000
	s_nop 0
	global_load_lds_dwordx4 v[156:157], off
	s_waitcnt vmcnt(16)
	s_waitcnt lgkmcnt(0)
	s_barrier
	s_setprio 1
	s_waitcnt lgkmcnt(0)
	v_mfma_f32_16x16x32_bf16 v[126:129], v[178:181], v[210:213], 0
	v_mfma_f32_16x16x32_bf16 v[118:121], v[186:189], v[210:213], 0
	v_mfma_f32_16x16x32_bf16 v[110:113], v[178:181], v[218:221], 0
	v_mfma_f32_16x16x32_bf16 v[102:105], v[186:189], v[218:221], 0
	v_mfma_f32_16x16x32_bf16 v[94:97], v[178:181], v[226:229], 0
	v_mfma_f32_16x16x32_bf16 v[86:89], v[186:189], v[226:229], 0
	v_mfma_f32_16x16x32_bf16 v[78:81], v[178:181], v[234:237], 0
	v_mfma_f32_16x16x32_bf16 v[70:73], v[186:189], v[234:237], 0
	v_mfma_f32_16x16x32_bf16 v[126:129], v[182:185], v[214:217], v[126:129]
	v_mfma_f32_16x16x32_bf16 v[118:121], v[190:193], v[214:217], v[118:121]
	v_mfma_f32_16x16x32_bf16 v[110:113], v[182:185], v[222:225], v[110:113]
	v_mfma_f32_16x16x32_bf16 v[102:105], v[190:193], v[222:225], v[102:105]
	v_mfma_f32_16x16x32_bf16 v[94:97], v[182:185], v[230:233], v[94:97]
	v_mfma_f32_16x16x32_bf16 v[86:89], v[190:193], v[230:233], v[86:89]
	v_mfma_f32_16x16x32_bf16 v[78:81], v[182:185], v[238:241], v[78:81]
	v_mfma_f32_16x16x32_bf16 v[70:73], v[190:193], v[238:241], v[70:73]
	s_setprio 0
	s_setprio 1
	v_mfma_f32_16x16x32_bf16 v[122:125], v[194:197], v[210:213], 0
	v_mfma_f32_16x16x32_bf16 v[114:117], v[202:205], v[210:213], 0
	v_mfma_f32_16x16x32_bf16 v[106:109], v[194:197], v[218:221], 0
	v_mfma_f32_16x16x32_bf16 v[98:101], v[202:205], v[218:221], 0
	v_mfma_f32_16x16x32_bf16 v[90:93], v[194:197], v[226:229], 0
	v_mfma_f32_16x16x32_bf16 v[82:85], v[202:205], v[226:229], 0
	v_mfma_f32_16x16x32_bf16 v[74:77], v[194:197], v[234:237], 0
	v_mfma_f32_16x16x32_bf16 v[66:69], v[202:205], v[234:237], 0
	v_mfma_f32_16x16x32_bf16 v[122:125], v[198:201], v[214:217], v[122:125]
	v_mfma_f32_16x16x32_bf16 v[114:117], v[206:209], v[214:217], v[114:117]
	v_mfma_f32_16x16x32_bf16 v[106:109], v[198:201], v[222:225], v[106:109]
	v_mfma_f32_16x16x32_bf16 v[98:101], v[206:209], v[222:225], v[98:101]
	v_mfma_f32_16x16x32_bf16 v[90:93], v[198:201], v[230:233], v[90:93]
	s_setprio 2
	s_barrier
	v_mfma_f32_16x16x32_bf16 v[82:85], v[206:209], v[230:233], v[82:85]
	v_mfma_f32_16x16x32_bf16 v[74:77], v[198:201], v[238:241], v[74:77]
	v_mfma_f32_16x16x32_bf16 v[66:69], v[206:209], v[238:241], v[66:69]
	s_setprio 0
	s_add_i32 s69, s69, s31
	v_lshl_add_u64 v[156:157], s[26:27], 0, v[134:135]
	s_mov_b32 m0, s69
	ds_read_b128 v[210:213], v155 offset:16384
	ds_read_b128 v[214:217], v155 offset:17408
	ds_read_b128 v[218:221], v155 offset:18432
	ds_read_b128 v[222:225], v155 offset:19456
	ds_read_b128 v[226:229], v155 offset:20480
	ds_read_b128 v[230:233], v155 offset:21504
	ds_read_b128 v[234:237], v155 offset:22528
	ds_read_b128 v[238:241], v155 offset:23552
	global_load_lds_dwordx4 v[156:157], off
	s_add_i32 m0, s69, 0x2000
	s_add_u32 s70, s26, 0x40000
	v_lshl_add_u64 v[160:161], s[26:27], 0, v[132:133]
	s_addc_u32 s71, s27, 0
	s_add_i32 s69, s72, s31
	global_load_lds_dwordx4 v[160:161], off
	v_lshl_add_u64 v[164:165], s[70:71], 0, v[134:135]
	s_mov_b32 m0, s69
	v_lshl_add_u64 v[242:243], s[44:45], 0, v[144:145]
	global_load_lds_dwordx4 v[164:165], off
	v_lshl_add_u64 v[164:165], s[70:71], 0, v[132:133]
	s_add_i32 m0, s69, 0x2000
	s_nop 0
	global_load_lds_dwordx4 v[164:165], off
	v_lshl_add_u64 v[164:165], s[44:45], 0, v[146:147]
	s_mov_b32 m0, s50
	s_nop 0
	global_load_lds_dwordx4 v[164:165], off
	s_mov_b32 m0, s51
	s_nop 0
	global_load_lds_dwordx4 v[242:243], off
	s_waitcnt vmcnt(16)
	s_waitcnt lgkmcnt(0)
	s_barrier
	s_setprio 1
	s_waitcnt lgkmcnt(0)
	v_mfma_f32_16x16x32_bf16 v[62:65], v[178:181], v[210:213], 0
	v_mfma_f32_16x16x32_bf16 v[54:57], v[186:189], v[210:213], 0
	v_mfma_f32_16x16x32_bf16 v[46:49], v[178:181], v[218:221], 0
	v_mfma_f32_16x16x32_bf16 v[38:41], v[186:189], v[218:221], 0
	v_mfma_f32_16x16x32_bf16 v[30:33], v[178:181], v[226:229], 0
	v_mfma_f32_16x16x32_bf16 v[22:25], v[186:189], v[226:229], 0
	v_mfma_f32_16x16x32_bf16 v[14:17], v[178:181], v[234:237], 0
	v_mfma_f32_16x16x32_bf16 v[6:9], v[186:189], v[234:237], 0
	v_mfma_f32_16x16x32_bf16 v[62:65], v[182:185], v[214:217], v[62:65]
	v_mfma_f32_16x16x32_bf16 v[54:57], v[190:193], v[214:217], v[54:57]
	v_mfma_f32_16x16x32_bf16 v[46:49], v[182:185], v[222:225], v[46:49]
	v_mfma_f32_16x16x32_bf16 v[38:41], v[190:193], v[222:225], v[38:41]
	v_mfma_f32_16x16x32_bf16 v[30:33], v[182:185], v[230:233], v[30:33]
	v_mfma_f32_16x16x32_bf16 v[22:25], v[190:193], v[230:233], v[22:25]
	v_mfma_f32_16x16x32_bf16 v[14:17], v[182:185], v[238:241], v[14:17]
	v_mfma_f32_16x16x32_bf16 v[6:9], v[190:193], v[238:241], v[6:9]
	s_setprio 0
	s_setprio 1
	v_mfma_f32_16x16x32_bf16 v[58:61], v[194:197], v[210:213], 0
	v_mfma_f32_16x16x32_bf16 v[50:53], v[202:205], v[210:213], 0
	v_mfma_f32_16x16x32_bf16 v[42:45], v[194:197], v[218:221], 0
	v_mfma_f32_16x16x32_bf16 v[34:37], v[202:205], v[218:221], 0
	v_mfma_f32_16x16x32_bf16 v[26:29], v[194:197], v[226:229], 0
	v_mfma_f32_16x16x32_bf16 v[18:21], v[202:205], v[226:229], 0
	v_mfma_f32_16x16x32_bf16 v[10:13], v[194:197], v[234:237], 0
	v_mfma_f32_16x16x32_bf16 v[2:5], v[202:205], v[234:237], 0
	v_mfma_f32_16x16x32_bf16 v[58:61], v[198:201], v[214:217], v[58:61]
	v_mfma_f32_16x16x32_bf16 v[50:53], v[206:209], v[214:217], v[50:53]
	v_mfma_f32_16x16x32_bf16 v[42:45], v[198:201], v[222:225], v[42:45]
	v_mfma_f32_16x16x32_bf16 v[34:37], v[206:209], v[222:225], v[34:37]
	v_mfma_f32_16x16x32_bf16 v[26:29], v[198:201], v[230:233], v[26:29]
	s_setprio 2
	s_barrier
	v_mfma_f32_16x16x32_bf16 v[18:21], v[206:209], v[230:233], v[18:21]
	v_mfma_f32_16x16x32_bf16 v[10:13], v[198:201], v[238:241], v[10:13]
	v_mfma_f32_16x16x32_bf16 v[2:5], v[206:209], v[238:241], v[2:5]
	s_setprio 0
	s_add_i32 s69, 0, 0x18000
	v_add_u32_e32 v159, s69, v152
	s_add_i32 s70, 0, 0x1c000
	ds_read_b128 v[178:181], v159
	ds_read_b128 v[182:185], v159 offset:1024
	ds_read_b128 v[186:189], v159 offset:2048
	ds_read_b128 v[190:193], v159 offset:3072
	v_add_u32_e32 v159, s70, v152
	ds_read_b128 v[194:197], v159
	ds_read_b128 v[198:201], v159 offset:1024
	ds_read_b128 v[202:205], v159 offset:2048
	ds_read_b128 v[206:209], v159 offset:3072
	s_add_u32 s44, s44, 0x40000
	s_addc_u32 s45, s45, 0
	s_mov_b32 m0, s52
	v_lshl_add_u64 v[244:245], s[44:45], 0, v[146:147]
	ds_read_b128 v[210:213], v155 offset:32768
	ds_read_b128 v[214:217], v155 offset:33792
	ds_read_b128 v[218:221], v155 offset:34816
	ds_read_b128 v[222:225], v155 offset:35840
	ds_read_b128 v[226:229], v155 offset:36864
	ds_read_b128 v[230:233], v155 offset:37888
	ds_read_b128 v[234:237], v155 offset:38912
	ds_read_b128 v[238:241], v155 offset:39936
	global_load_lds_dwordx4 v[244:245], off
	v_lshl_add_u64 v[244:245], s[44:45], 0, v[144:145]
	s_mov_b32 m0, s53
	s_nop 0
	global_load_lds_dwordx4 v[244:245], off
	s_waitcnt vmcnt(8)
	s_waitcnt lgkmcnt(0)
	s_barrier
	s_setprio 1
	s_waitcnt lgkmcnt(0)
	v_mfma_f32_16x16x32_bf16 v[126:129], v[178:181], v[210:213], v[126:129]
	v_mfma_f32_16x16x32_bf16 v[118:121], v[186:189], v[210:213], v[118:121]
	v_mfma_f32_16x16x32_bf16 v[110:113], v[178:181], v[218:221], v[110:113]
	v_mfma_f32_16x16x32_bf16 v[102:105], v[186:189], v[218:221], v[102:105]
	v_mfma_f32_16x16x32_bf16 v[94:97], v[178:181], v[226:229], v[94:97]
	v_mfma_f32_16x16x32_bf16 v[86:89], v[186:189], v[226:229], v[86:89]
	v_mfma_f32_16x16x32_bf16 v[78:81], v[178:181], v[234:237], v[78:81]
	v_mfma_f32_16x16x32_bf16 v[70:73], v[186:189], v[234:237], v[70:73]
	v_mfma_f32_16x16x32_bf16 v[126:129], v[182:185], v[214:217], v[126:129]
	v_mfma_f32_16x16x32_bf16 v[118:121], v[190:193], v[214:217], v[118:121]
	v_mfma_f32_16x16x32_bf16 v[110:113], v[182:185], v[222:225], v[110:113]
	v_mfma_f32_16x16x32_bf16 v[102:105], v[190:193], v[222:225], v[102:105]
	v_mfma_f32_16x16x32_bf16 v[94:97], v[182:185], v[230:233], v[94:97]
	v_mfma_f32_16x16x32_bf16 v[86:89], v[190:193], v[230:233], v[86:89]
	v_mfma_f32_16x16x32_bf16 v[78:81], v[182:185], v[238:241], v[78:81]
	v_mfma_f32_16x16x32_bf16 v[70:73], v[190:193], v[238:241], v[70:73]
	s_setprio 0
	s_setprio 1
	v_mfma_f32_16x16x32_bf16 v[122:125], v[194:197], v[210:213], v[122:125]
	v_mfma_f32_16x16x32_bf16 v[114:117], v[202:205], v[210:213], v[114:117]
	v_mfma_f32_16x16x32_bf16 v[106:109], v[194:197], v[218:221], v[106:109]
	v_mfma_f32_16x16x32_bf16 v[98:101], v[202:205], v[218:221], v[98:101]
	v_mfma_f32_16x16x32_bf16 v[90:93], v[194:197], v[226:229], v[90:93]
	v_mfma_f32_16x16x32_bf16 v[82:85], v[202:205], v[226:229], v[82:85]
	v_mfma_f32_16x16x32_bf16 v[74:77], v[194:197], v[234:237], v[74:77]
	v_mfma_f32_16x16x32_bf16 v[66:69], v[202:205], v[234:237], v[66:69]
	v_mfma_f32_16x16x32_bf16 v[122:125], v[198:201], v[214:217], v[122:125]
	v_mfma_f32_16x16x32_bf16 v[114:117], v[206:209], v[214:217], v[114:117]
	v_mfma_f32_16x16x32_bf16 v[106:109], v[198:201], v[222:225], v[106:109]
	v_mfma_f32_16x16x32_bf16 v[98:101], v[206:209], v[222:225], v[98:101]
	v_mfma_f32_16x16x32_bf16 v[90:93], v[198:201], v[230:233], v[90:93]
	s_setprio 2
	s_barrier
	v_mfma_f32_16x16x32_bf16 v[82:85], v[206:209], v[230:233], v[82:85]
	v_mfma_f32_16x16x32_bf16 v[74:77], v[198:201], v[238:241], v[74:77]
	v_mfma_f32_16x16x32_bf16 v[66:69], v[206:209], v[238:241], v[66:69]
	s_setprio 0
	s_add_i32 s44, s69, s31
	v_lshl_add_u64 v[156:157], v[156:157], 0, s[66:67]
	s_mov_b32 m0, s44
	ds_read_b128 v[210:213], v155 offset:49152
	ds_read_b128 v[214:217], v155 offset:50176
	ds_read_b128 v[218:221], v155 offset:51200
	ds_read_b128 v[222:225], v155 offset:52224
	ds_read_b128 v[226:229], v155 offset:53248
	ds_read_b128 v[230:233], v155 offset:54272
	ds_read_b128 v[234:237], v155 offset:55296
	ds_read_b128 v[238:241], v155 offset:56320
	global_load_lds_dwordx4 v[156:157], off
	s_add_i32 m0, s44, 0x2000
	s_add_u32 s26, s26, 0x40080
	v_lshl_add_u64 v[156:157], v[160:161], 0, s[66:67]
	s_addc_u32 s27, s27, 0
	s_add_i32 s44, s70, s31
	global_load_lds_dwordx4 v[156:157], off
	v_lshl_add_u64 v[156:157], s[26:27], 0, v[134:135]
	s_mov_b32 m0, s44
	s_nop 0
	global_load_lds_dwordx4 v[156:157], off
	v_lshl_add_u64 v[156:157], s[26:27], 0, v[132:133]
	s_add_i32 m0, s44, 0x2000
	s_nop 0
	global_load_lds_dwordx4 v[156:157], off
	v_lshl_add_u64 v[156:157], v[164:165], 0, s[66:67]
	s_mov_b32 m0, s19
	s_nop 0
	global_load_lds_dwordx4 v[156:157], off
	v_lshl_add_u64 v[156:157], v[242:243], 0, s[66:67]
	s_mov_b32 m0, s60
	s_nop 0
	global_load_lds_dwordx4 v[156:157], off
	s_waitcnt vmcnt(8)
	s_waitcnt lgkmcnt(0)
	s_barrier
	s_setprio 1
	s_waitcnt lgkmcnt(0)
	v_mfma_f32_16x16x32_bf16 v[62:65], v[178:181], v[210:213], v[62:65]
	v_mfma_f32_16x16x32_bf16 v[54:57], v[186:189], v[210:213], v[54:57]
	v_mfma_f32_16x16x32_bf16 v[46:49], v[178:181], v[218:221], v[46:49]
	v_mfma_f32_16x16x32_bf16 v[38:41], v[186:189], v[218:221], v[38:41]
	v_mfma_f32_16x16x32_bf16 v[30:33], v[178:181], v[226:229], v[30:33]
	v_mfma_f32_16x16x32_bf16 v[22:25], v[186:189], v[226:229], v[22:25]
	v_mfma_f32_16x16x32_bf16 v[14:17], v[178:181], v[234:237], v[14:17]
	v_mfma_f32_16x16x32_bf16 v[6:9], v[186:189], v[234:237], v[6:9]
	v_mfma_f32_16x16x32_bf16 v[62:65], v[182:185], v[214:217], v[62:65]
	v_mfma_f32_16x16x32_bf16 v[54:57], v[190:193], v[214:217], v[54:57]
	v_mfma_f32_16x16x32_bf16 v[46:49], v[182:185], v[222:225], v[46:49]
	v_mfma_f32_16x16x32_bf16 v[38:41], v[190:193], v[222:225], v[38:41]
	v_mfma_f32_16x16x32_bf16 v[30:33], v[182:185], v[230:233], v[30:33]
	v_mfma_f32_16x16x32_bf16 v[22:25], v[190:193], v[230:233], v[22:25]
	v_mfma_f32_16x16x32_bf16 v[14:17], v[182:185], v[238:241], v[14:17]
	v_mfma_f32_16x16x32_bf16 v[6:9], v[190:193], v[238:241], v[6:9]
	s_setprio 0
	s_setprio 1
	v_mfma_f32_16x16x32_bf16 v[58:61], v[194:197], v[210:213], v[58:61]
	v_mfma_f32_16x16x32_bf16 v[50:53], v[202:205], v[210:213], v[50:53]
	v_mfma_f32_16x16x32_bf16 v[42:45], v[194:197], v[218:221], v[42:45]
	v_mfma_f32_16x16x32_bf16 v[34:37], v[202:205], v[218:221], v[34:37]
	v_mfma_f32_16x16x32_bf16 v[26:29], v[194:197], v[226:229], v[26:29]
	v_mfma_f32_16x16x32_bf16 v[18:21], v[202:205], v[226:229], v[18:21]
	v_mfma_f32_16x16x32_bf16 v[10:13], v[194:197], v[234:237], v[10:13]
	v_mfma_f32_16x16x32_bf16 v[2:5], v[202:205], v[234:237], v[2:5]
	v_mfma_f32_16x16x32_bf16 v[58:61], v[198:201], v[214:217], v[58:61]
	v_mfma_f32_16x16x32_bf16 v[50:53], v[206:209], v[214:217], v[50:53]
	v_mfma_f32_16x16x32_bf16 v[42:45], v[198:201], v[222:225], v[42:45]
	v_mfma_f32_16x16x32_bf16 v[34:37], v[206:209], v[222:225], v[34:37]
	v_mfma_f32_16x16x32_bf16 v[26:29], v[198:201], v[230:233], v[26:29]
	s_setprio 2
	s_barrier
	v_mfma_f32_16x16x32_bf16 v[18:21], v[206:209], v[230:233], v[18:21]
	v_mfma_f32_16x16x32_bf16 v[10:13], v[198:201], v[238:241], v[10:13]
	v_mfma_f32_16x16x32_bf16 v[2:5], v[206:209], v[238:241], v[2:5]
	s_setprio 0
	s_add_i32 s68, s68, 2
	s_add_u32 s22, s22, 0x100
	s_addc_u32 s23, s23, 0
	s_add_u32 s56, s56, 0x100
	s_addc_u32 s65, s65, 0
	s_cmp_gt_u32 s68, 13
.LBB0_283:
	s_add_u32 s26, s22, 0xfffc0080
	s_addc_u32 s27, s23, -1
	s_add_i32 s69, 0, 0x10000
	s_cmp_eq_u32 s68, 12
	s_cselect_b32 s45, s30, s27
	s_cselect_b32 s44, s37, s26
	v_add_u32_e32 v156, s69, v152
	s_cselect_b32 s27, s13, s65
	s_cselect_b32 s26, s47, s56
	s_add_i32 s72, 0, 0x14000
	ds_read_b128 v[178:181], v156
	ds_read_b128 v[182:185], v156 offset:1024
	ds_read_b128 v[186:189], v156 offset:2048
	ds_read_b128 v[190:193], v156 offset:3072
	v_add_u32_e32 v156, s72, v152
	ds_read_b128 v[194:197], v156
	ds_read_b128 v[198:201], v156 offset:1024
	ds_read_b128 v[202:205], v156 offset:2048
	ds_read_b128 v[206:209], v156 offset:3072
	v_lshl_add_u64 v[156:157], s[22:23], 0, v[148:149]
	s_add_i32 m0, s50, 0xc000
	ds_read_b128 v[210:213], v155
	ds_read_b128 v[214:217], v155 offset:1024
	ds_read_b128 v[218:221], v155 offset:2048
	ds_read_b128 v[222:225], v155 offset:3072
	ds_read_b128 v[226:229], v155 offset:4096
	ds_read_b128 v[230:233], v155 offset:5120
	ds_read_b128 v[234:237], v155 offset:6144
	ds_read_b128 v[238:241], v155 offset:7168
	global_load_lds_dwordx4 v[156:157], off
	v_lshl_add_u64 v[156:157], s[22:23], 0, v[150:151]
	s_add_i32 m0, s50, 0xe000
	s_nop 0
	global_load_lds_dwordx4 v[156:157], off
	s_waitcnt vmcnt(8)
	s_waitcnt lgkmcnt(0)
	s_barrier
	s_setprio 1
	s_waitcnt lgkmcnt(0)
	v_mfma_f32_16x16x32_bf16 v[126:129], v[178:181], v[210:213], v[126:129]
	v_mfma_f32_16x16x32_bf16 v[118:121], v[186:189], v[210:213], v[118:121]
	v_mfma_f32_16x16x32_bf16 v[110:113], v[178:181], v[218:221], v[110:113]
	v_mfma_f32_16x16x32_bf16 v[102:105], v[186:189], v[218:221], v[102:105]
	v_mfma_f32_16x16x32_bf16 v[94:97], v[178:181], v[226:229], v[94:97]
	v_mfma_f32_16x16x32_bf16 v[86:89], v[186:189], v[226:229], v[86:89]
	v_mfma_f32_16x16x32_bf16 v[78:81], v[178:181], v[234:237], v[78:81]
	v_mfma_f32_16x16x32_bf16 v[70:73], v[186:189], v[234:237], v[70:73]
	v_mfma_f32_16x16x32_bf16 v[126:129], v[182:185], v[214:217], v[126:129]
	v_mfma_f32_16x16x32_bf16 v[118:121], v[190:193], v[214:217], v[118:121]
	v_mfma_f32_16x16x32_bf16 v[110:113], v[182:185], v[222:225], v[110:113]
	v_mfma_f32_16x16x32_bf16 v[102:105], v[190:193], v[222:225], v[102:105]
	v_mfma_f32_16x16x32_bf16 v[94:97], v[182:185], v[230:233], v[94:97]
	v_mfma_f32_16x16x32_bf16 v[86:89], v[190:193], v[230:233], v[86:89]
	v_mfma_f32_16x16x32_bf16 v[78:81], v[182:185], v[238:241], v[78:81]
	v_mfma_f32_16x16x32_bf16 v[70:73], v[190:193], v[238:241], v[70:73]
	s_setprio 0
	s_setprio 1
	v_mfma_f32_16x16x32_bf16 v[122:125], v[194:197], v[210:213], v[122:125]
	v_mfma_f32_16x16x32_bf16 v[114:117], v[202:205], v[210:213], v[114:117]
	v_mfma_f32_16x16x32_bf16 v[106:109], v[194:197], v[218:221], v[106:109]
	v_mfma_f32_16x16x32_bf16 v[98:101], v[202:205], v[218:221], v[98:101]
	v_mfma_f32_16x16x32_bf16 v[90:93], v[194:197], v[226:229], v[90:93]
	v_mfma_f32_16x16x32_bf16 v[82:85], v[202:205], v[226:229], v[82:85]
	v_mfma_f32_16x16x32_bf16 v[74:77], v[194:197], v[234:237], v[74:77]
	v_mfma_f32_16x16x32_bf16 v[66:69], v[202:205], v[234:237], v[66:69]
	v_mfma_f32_16x16x32_bf16 v[122:125], v[198:201], v[214:217], v[122:125]
	v_mfma_f32_16x16x32_bf16 v[114:117], v[206:209], v[214:217], v[114:117]
	v_mfma_f32_16x16x32_bf16 v[106:109], v[198:201], v[222:225], v[106:109]
	v_mfma_f32_16x16x32_bf16 v[98:101], v[206:209], v[222:225], v[98:101]
	v_mfma_f32_16x16x32_bf16 v[90:93], v[198:201], v[230:233], v[90:93]
	s_setprio 2
	s_barrier
	v_mfma_f32_16x16x32_bf16 v[82:85], v[206:209], v[230:233], v[82:85]
	v_mfma_f32_16x16x32_bf16 v[74:77], v[198:201], v[238:241], v[74:77]
	v_mfma_f32_16x16x32_bf16 v[66:69], v[206:209], v[238:241], v[66:69]
	s_setprio 0
	s_add_i32 s69, s69, s31
	v_lshl_add_u64 v[156:157], s[26:27], 0, v[134:135]
	s_mov_b32 m0, s69
	ds_read_b128 v[210:213], v155 offset:16384
	ds_read_b128 v[214:217], v155 offset:17408
	ds_read_b128 v[218:221], v155 offset:18432
	ds_read_b128 v[222:225], v155 offset:19456
	ds_read_b128 v[226:229], v155 offset:20480
	ds_read_b128 v[230:233], v155 offset:21504
	ds_read_b128 v[234:237], v155 offset:22528
	ds_read_b128 v[238:241], v155 offset:23552
	global_load_lds_dwordx4 v[156:157], off
	s_add_i32 m0, s69, 0x2000
	s_add_u32 s70, s26, 0x40000
	v_lshl_add_u64 v[160:161], s[26:27], 0, v[132:133]
	s_addc_u32 s71, s27, 0
	s_add_i32 s69, s72, s31
	global_load_lds_dwordx4 v[160:161], off
	v_lshl_add_u64 v[164:165], s[70:71], 0, v[134:135]
	s_mov_b32 m0, s69
	v_lshl_add_u64 v[242:243], s[44:45], 0, v[144:145]
	global_load_lds_dwordx4 v[164:165], off
	v_lshl_add_u64 v[164:165], s[70:71], 0, v[132:133]
	s_add_i32 m0, s69, 0x2000
	s_nop 0
	global_load_lds_dwordx4 v[164:165], off
	v_lshl_add_u64 v[164:165], s[44:45], 0, v[146:147]
	s_mov_b32 m0, s50
	s_nop 0
	global_load_lds_dwordx4 v[164:165], off
	s_mov_b32 m0, s51
	s_nop 0
	global_load_lds_dwordx4 v[242:243], off
	s_waitcnt vmcnt(8)
	s_waitcnt lgkmcnt(0)
	s_barrier
	s_setprio 1
	s_waitcnt lgkmcnt(0)
	v_mfma_f32_16x16x32_bf16 v[62:65], v[178:181], v[210:213], v[62:65]
	v_mfma_f32_16x16x32_bf16 v[54:57], v[186:189], v[210:213], v[54:57]
	v_mfma_f32_16x16x32_bf16 v[46:49], v[178:181], v[218:221], v[46:49]
	v_mfma_f32_16x16x32_bf16 v[38:41], v[186:189], v[218:221], v[38:41]
	v_mfma_f32_16x16x32_bf16 v[30:33], v[178:181], v[226:229], v[30:33]
	v_mfma_f32_16x16x32_bf16 v[22:25], v[186:189], v[226:229], v[22:25]
	v_mfma_f32_16x16x32_bf16 v[14:17], v[178:181], v[234:237], v[14:17]
	v_mfma_f32_16x16x32_bf16 v[6:9], v[186:189], v[234:237], v[6:9]
	v_mfma_f32_16x16x32_bf16 v[62:65], v[182:185], v[214:217], v[62:65]
	v_mfma_f32_16x16x32_bf16 v[54:57], v[190:193], v[214:217], v[54:57]
	v_mfma_f32_16x16x32_bf16 v[46:49], v[182:185], v[222:225], v[46:49]
	v_mfma_f32_16x16x32_bf16 v[38:41], v[190:193], v[222:225], v[38:41]
	v_mfma_f32_16x16x32_bf16 v[30:33], v[182:185], v[230:233], v[30:33]
	v_mfma_f32_16x16x32_bf16 v[22:25], v[190:193], v[230:233], v[22:25]
	v_mfma_f32_16x16x32_bf16 v[14:17], v[182:185], v[238:241], v[14:17]
	v_mfma_f32_16x16x32_bf16 v[6:9], v[190:193], v[238:241], v[6:9]
	s_setprio 0
	s_setprio 1
	v_mfma_f32_16x16x32_bf16 v[58:61], v[194:197], v[210:213], v[58:61]
	v_mfma_f32_16x16x32_bf16 v[50:53], v[202:205], v[210:213], v[50:53]
	v_mfma_f32_16x16x32_bf16 v[42:45], v[194:197], v[218:221], v[42:45]
	v_mfma_f32_16x16x32_bf16 v[34:37], v[202:205], v[218:221], v[34:37]
	v_mfma_f32_16x16x32_bf16 v[26:29], v[194:197], v[226:229], v[26:29]
	v_mfma_f32_16x16x32_bf16 v[18:21], v[202:205], v[226:229], v[18:21]
	v_mfma_f32_16x16x32_bf16 v[10:13], v[194:197], v[234:237], v[10:13]
	v_mfma_f32_16x16x32_bf16 v[2:5], v[202:205], v[234:237], v[2:5]
	v_mfma_f32_16x16x32_bf16 v[58:61], v[198:201], v[214:217], v[58:61]
	v_mfma_f32_16x16x32_bf16 v[50:53], v[206:209], v[214:217], v[50:53]
	v_mfma_f32_16x16x32_bf16 v[42:45], v[198:201], v[222:225], v[42:45]
	v_mfma_f32_16x16x32_bf16 v[34:37], v[206:209], v[222:225], v[34:37]
	v_mfma_f32_16x16x32_bf16 v[26:29], v[198:201], v[230:233], v[26:29]
	s_setprio 2
	s_barrier
	v_mfma_f32_16x16x32_bf16 v[18:21], v[206:209], v[230:233], v[18:21]
	v_mfma_f32_16x16x32_bf16 v[10:13], v[198:201], v[238:241], v[10:13]
	v_mfma_f32_16x16x32_bf16 v[2:5], v[206:209], v[238:241], v[2:5]
	s_setprio 0
	s_add_i32 s69, 0, 0x18000
	v_add_u32_e32 v159, s69, v152
	s_add_i32 s70, 0, 0x1c000
	ds_read_b128 v[178:181], v159
	ds_read_b128 v[182:185], v159 offset:1024
	ds_read_b128 v[186:189], v159 offset:2048
	ds_read_b128 v[190:193], v159 offset:3072
	v_add_u32_e32 v159, s70, v152
	ds_read_b128 v[194:197], v159
	ds_read_b128 v[198:201], v159 offset:1024
	ds_read_b128 v[202:205], v159 offset:2048
	ds_read_b128 v[206:209], v159 offset:3072
	s_add_u32 s44, s44, 0x40000
	s_addc_u32 s45, s45, 0
	s_mov_b32 m0, s52
	v_lshl_add_u64 v[244:245], s[44:45], 0, v[146:147]
	ds_read_b128 v[210:213], v155 offset:32768
	ds_read_b128 v[214:217], v155 offset:33792
	ds_read_b128 v[218:221], v155 offset:34816
	ds_read_b128 v[222:225], v155 offset:35840
	ds_read_b128 v[226:229], v155 offset:36864
	ds_read_b128 v[230:233], v155 offset:37888
	ds_read_b128 v[234:237], v155 offset:38912
	ds_read_b128 v[238:241], v155 offset:39936
	global_load_lds_dwordx4 v[244:245], off
	v_lshl_add_u64 v[244:245], s[44:45], 0, v[144:145]
	s_mov_b32 m0, s53
	s_nop 0
	global_load_lds_dwordx4 v[244:245], off
	s_waitcnt vmcnt(8)
	s_waitcnt lgkmcnt(0)
	s_barrier
	s_setprio 1
	s_waitcnt lgkmcnt(0)
	v_mfma_f32_16x16x32_bf16 v[126:129], v[178:181], v[210:213], v[126:129]
	v_mfma_f32_16x16x32_bf16 v[118:121], v[186:189], v[210:213], v[118:121]
	v_mfma_f32_16x16x32_bf16 v[110:113], v[178:181], v[218:221], v[110:113]
	v_mfma_f32_16x16x32_bf16 v[102:105], v[186:189], v[218:221], v[102:105]
	v_mfma_f32_16x16x32_bf16 v[94:97], v[178:181], v[226:229], v[94:97]
	v_mfma_f32_16x16x32_bf16 v[86:89], v[186:189], v[226:229], v[86:89]
	v_mfma_f32_16x16x32_bf16 v[78:81], v[178:181], v[234:237], v[78:81]
	v_mfma_f32_16x16x32_bf16 v[70:73], v[186:189], v[234:237], v[70:73]
	v_mfma_f32_16x16x32_bf16 v[126:129], v[182:185], v[214:217], v[126:129]
	v_mfma_f32_16x16x32_bf16 v[118:121], v[190:193], v[214:217], v[118:121]
	v_mfma_f32_16x16x32_bf16 v[110:113], v[182:185], v[222:225], v[110:113]
	v_mfma_f32_16x16x32_bf16 v[102:105], v[190:193], v[222:225], v[102:105]
	v_mfma_f32_16x16x32_bf16 v[94:97], v[182:185], v[230:233], v[94:97]
	v_mfma_f32_16x16x32_bf16 v[86:89], v[190:193], v[230:233], v[86:89]
	v_mfma_f32_16x16x32_bf16 v[78:81], v[182:185], v[238:241], v[78:81]
	v_mfma_f32_16x16x32_bf16 v[70:73], v[190:193], v[238:241], v[70:73]
	s_setprio 0
	s_setprio 1
	v_mfma_f32_16x16x32_bf16 v[122:125], v[194:197], v[210:213], v[122:125]
	v_mfma_f32_16x16x32_bf16 v[114:117], v[202:205], v[210:213], v[114:117]
	v_mfma_f32_16x16x32_bf16 v[106:109], v[194:197], v[218:221], v[106:109]
	v_mfma_f32_16x16x32_bf16 v[98:101], v[202:205], v[218:221], v[98:101]
	v_mfma_f32_16x16x32_bf16 v[90:93], v[194:197], v[226:229], v[90:93]
	v_mfma_f32_16x16x32_bf16 v[82:85], v[202:205], v[226:229], v[82:85]
	v_mfma_f32_16x16x32_bf16 v[74:77], v[194:197], v[234:237], v[74:77]
	v_mfma_f32_16x16x32_bf16 v[66:69], v[202:205], v[234:237], v[66:69]
	v_mfma_f32_16x16x32_bf16 v[122:125], v[198:201], v[214:217], v[122:125]
	v_mfma_f32_16x16x32_bf16 v[114:117], v[206:209], v[214:217], v[114:117]
	v_mfma_f32_16x16x32_bf16 v[106:109], v[198:201], v[222:225], v[106:109]
	v_mfma_f32_16x16x32_bf16 v[98:101], v[206:209], v[222:225], v[98:101]
	v_mfma_f32_16x16x32_bf16 v[90:93], v[198:201], v[230:233], v[90:93]
	s_setprio 2
	s_barrier
	v_mfma_f32_16x16x32_bf16 v[82:85], v[206:209], v[230:233], v[82:85]
	v_mfma_f32_16x16x32_bf16 v[74:77], v[198:201], v[238:241], v[74:77]
	v_mfma_f32_16x16x32_bf16 v[66:69], v[206:209], v[238:241], v[66:69]
	s_setprio 0
	s_add_i32 s44, s69, s31
	v_lshl_add_u64 v[156:157], v[156:157], 0, s[66:67]
	s_mov_b32 m0, s44
	ds_read_b128 v[210:213], v155 offset:49152
	ds_read_b128 v[214:217], v155 offset:50176
	ds_read_b128 v[218:221], v155 offset:51200
	ds_read_b128 v[222:225], v155 offset:52224
	ds_read_b128 v[226:229], v155 offset:53248
	ds_read_b128 v[230:233], v155 offset:54272
	ds_read_b128 v[234:237], v155 offset:55296
	ds_read_b128 v[238:241], v155 offset:56320
	global_load_lds_dwordx4 v[156:157], off
	s_add_i32 m0, s44, 0x2000
	s_add_u32 s26, s26, 0x40080
	v_lshl_add_u64 v[156:157], v[160:161], 0, s[66:67]
	s_addc_u32 s27, s27, 0
	s_add_i32 s44, s70, s31
	global_load_lds_dwordx4 v[156:157], off
	v_lshl_add_u64 v[156:157], s[26:27], 0, v[134:135]
	s_mov_b32 m0, s44
	s_nop 0
	global_load_lds_dwordx4 v[156:157], off
	v_lshl_add_u64 v[156:157], s[26:27], 0, v[132:133]
	s_add_i32 m0, s44, 0x2000
	s_nop 0
	global_load_lds_dwordx4 v[156:157], off
	v_lshl_add_u64 v[156:157], v[164:165], 0, s[66:67]
	s_mov_b32 m0, s19
	s_nop 0
	global_load_lds_dwordx4 v[156:157], off
	v_lshl_add_u64 v[156:157], v[242:243], 0, s[66:67]
	s_mov_b32 m0, s60
	s_nop 0
	global_load_lds_dwordx4 v[156:157], off
	s_waitcnt vmcnt(8)
	s_waitcnt lgkmcnt(0)
	s_barrier
	s_setprio 1
	s_waitcnt lgkmcnt(0)
	v_mfma_f32_16x16x32_bf16 v[62:65], v[178:181], v[210:213], v[62:65]
	v_mfma_f32_16x16x32_bf16 v[54:57], v[186:189], v[210:213], v[54:57]
	v_mfma_f32_16x16x32_bf16 v[46:49], v[178:181], v[218:221], v[46:49]
	v_mfma_f32_16x16x32_bf16 v[38:41], v[186:189], v[218:221], v[38:41]
	v_mfma_f32_16x16x32_bf16 v[30:33], v[178:181], v[226:229], v[30:33]
	v_mfma_f32_16x16x32_bf16 v[22:25], v[186:189], v[226:229], v[22:25]
	v_mfma_f32_16x16x32_bf16 v[14:17], v[178:181], v[234:237], v[14:17]
	v_mfma_f32_16x16x32_bf16 v[6:9], v[186:189], v[234:237], v[6:9]
	v_mfma_f32_16x16x32_bf16 v[62:65], v[182:185], v[214:217], v[62:65]
	v_mfma_f32_16x16x32_bf16 v[54:57], v[190:193], v[214:217], v[54:57]
	v_mfma_f32_16x16x32_bf16 v[46:49], v[182:185], v[222:225], v[46:49]
	v_mfma_f32_16x16x32_bf16 v[38:41], v[190:193], v[222:225], v[38:41]
	v_mfma_f32_16x16x32_bf16 v[30:33], v[182:185], v[230:233], v[30:33]
	v_mfma_f32_16x16x32_bf16 v[22:25], v[190:193], v[230:233], v[22:25]
	v_mfma_f32_16x16x32_bf16 v[14:17], v[182:185], v[238:241], v[14:17]
	v_mfma_f32_16x16x32_bf16 v[6:9], v[190:193], v[238:241], v[6:9]
	s_setprio 0
	s_setprio 1
	v_mfma_f32_16x16x32_bf16 v[58:61], v[194:197], v[210:213], v[58:61]
	v_mfma_f32_16x16x32_bf16 v[50:53], v[202:205], v[210:213], v[50:53]
	v_mfma_f32_16x16x32_bf16 v[42:45], v[194:197], v[218:221], v[42:45]
	v_mfma_f32_16x16x32_bf16 v[34:37], v[202:205], v[218:221], v[34:37]
	v_mfma_f32_16x16x32_bf16 v[26:29], v[194:197], v[226:229], v[26:29]
	v_mfma_f32_16x16x32_bf16 v[18:21], v[202:205], v[226:229], v[18:21]
	v_mfma_f32_16x16x32_bf16 v[10:13], v[194:197], v[234:237], v[10:13]
	v_mfma_f32_16x16x32_bf16 v[2:5], v[202:205], v[234:237], v[2:5]
	v_mfma_f32_16x16x32_bf16 v[58:61], v[198:201], v[214:217], v[58:61]
	v_mfma_f32_16x16x32_bf16 v[50:53], v[206:209], v[214:217], v[50:53]
	v_mfma_f32_16x16x32_bf16 v[42:45], v[198:201], v[222:225], v[42:45]
	v_mfma_f32_16x16x32_bf16 v[34:37], v[206:209], v[222:225], v[34:37]
	v_mfma_f32_16x16x32_bf16 v[26:29], v[198:201], v[230:233], v[26:29]
	s_setprio 2
	s_barrier
	v_mfma_f32_16x16x32_bf16 v[18:21], v[206:209], v[230:233], v[18:21]
	v_mfma_f32_16x16x32_bf16 v[10:13], v[198:201], v[238:241], v[10:13]
	v_mfma_f32_16x16x32_bf16 v[2:5], v[206:209], v[238:241], v[2:5]
	s_setprio 0
	s_add_i32 s68, s68, 2
	s_add_u32 s22, s22, 0x100
	s_addc_u32 s23, s23, 0
	s_add_u32 s56, s56, 0x100
	s_addc_u32 s65, s65, 0
	s_cmp_gt_u32 s68, 13
	s_cbranch_scc0 .LBB0_283
	s_and_b64 vcc, exec, s[92:93]
	s_cbranch_vccz .LBB0_286
	s_barrier

.Lpz_res:
	s_add_i32 s30, s22, 2
	s_add_u32 s37, s12, 0x80
	s_addc_u32 s23, s13, 0
	s_add_i32 s56, 0, 0x10000
	s_cmp_eq_u32 s5, s22
	s_cselect_b32 s23, s11, s23
	s_cselect_b32 s22, s10, s37
	v_add_u32_e32 v156, s56, v159
	s_cselect_b32 s69, s99, s25
	s_cselect_b32 s68, s98, s24
	s_add_i32 s37, 0, 0x14000
	ds_read_b128 v[152:155], v156
	ds_read_b128 v[178:181], v156 offset:1024
	ds_read_b128 v[182:185], v156 offset:2048
	ds_read_b128 v[186:189], v156 offset:3072
	v_add_u32_e32 v156, s37, v159
	ds_read_b128 v[190:193], v156
	ds_read_b128 v[194:197], v156 offset:1024
	ds_read_b128 v[198:201], v156 offset:2048
	ds_read_b128 v[202:205], v156 offset:3072
	v_lshl_add_u64 v[156:157], s[12:13], 0, v[148:149]
	s_add_i32 m0, s45, 0xc000
	ds_read_b128 v[206:209], v161
	ds_read_b128 v[210:213], v161 offset:1024
	ds_read_b128 v[214:217], v161 offset:2048
	ds_read_b128 v[218:221], v161 offset:3072
	ds_read_b128 v[222:225], v161 offset:4096
	ds_read_b128 v[226:229], v161 offset:5120
	ds_read_b128 v[230:233], v161 offset:6144
	ds_read_b128 v[234:237], v161 offset:7168
	global_load_lds_dwordx4 v[156:157], off
	v_lshl_add_u64 v[156:157], s[12:13], 0, v[150:151]
	s_add_i32 m0, s45, 0xe000
	s_nop 0
	global_load_lds_dwordx4 v[156:157], off
	s_waitcnt vmcnt(32)
	s_waitcnt lgkmcnt(0)
	s_barrier
	s_setprio 1
	s_waitcnt lgkmcnt(0)
	v_mfma_f32_16x16x32_bf16 v[126:129], v[152:155], v[206:209], 0
	v_mfma_f32_16x16x32_bf16 v[122:125], v[182:185], v[206:209], 0
	v_mfma_f32_16x16x32_bf16 v[110:113], v[152:155], v[214:217], 0
	v_mfma_f32_16x16x32_bf16 v[106:109], v[182:185], v[214:217], 0
	v_mfma_f32_16x16x32_bf16 v[94:97], v[152:155], v[222:225], 0
	v_mfma_f32_16x16x32_bf16 v[90:93], v[182:185], v[222:225], 0
	v_mfma_f32_16x16x32_bf16 v[78:81], v[152:155], v[230:233], 0
	v_mfma_f32_16x16x32_bf16 v[74:77], v[182:185], v[230:233], 0
	v_mfma_f32_16x16x32_bf16 v[126:129], v[178:181], v[210:213], v[126:129]
	v_mfma_f32_16x16x32_bf16 v[122:125], v[186:189], v[210:213], v[122:125]
	v_mfma_f32_16x16x32_bf16 v[110:113], v[178:181], v[218:221], v[110:113]
	v_mfma_f32_16x16x32_bf16 v[106:109], v[186:189], v[218:221], v[106:109]
	v_mfma_f32_16x16x32_bf16 v[94:97], v[178:181], v[226:229], v[94:97]
	v_mfma_f32_16x16x32_bf16 v[90:93], v[186:189], v[226:229], v[90:93]
	v_mfma_f32_16x16x32_bf16 v[78:81], v[178:181], v[234:237], v[78:81]
	v_mfma_f32_16x16x32_bf16 v[74:77], v[186:189], v[234:237], v[74:77]
	s_setprio 0
	s_setprio 1
	v_mfma_f32_16x16x32_bf16 v[118:121], v[190:193], v[206:209], 0
	v_mfma_f32_16x16x32_bf16 v[114:117], v[198:201], v[206:209], 0
	v_mfma_f32_16x16x32_bf16 v[102:105], v[190:193], v[214:217], 0
	v_mfma_f32_16x16x32_bf16 v[98:101], v[198:201], v[214:217], 0
	v_mfma_f32_16x16x32_bf16 v[86:89], v[190:193], v[222:225], 0
	v_mfma_f32_16x16x32_bf16 v[82:85], v[198:201], v[222:225], 0
	v_mfma_f32_16x16x32_bf16 v[70:73], v[190:193], v[230:233], 0
	v_mfma_f32_16x16x32_bf16 v[66:69], v[198:201], v[230:233], 0
	v_mfma_f32_16x16x32_bf16 v[118:121], v[194:197], v[210:213], v[118:121]
	v_mfma_f32_16x16x32_bf16 v[114:117], v[202:205], v[210:213], v[114:117]
	v_mfma_f32_16x16x32_bf16 v[102:105], v[194:197], v[218:221], v[102:105]
	v_mfma_f32_16x16x32_bf16 v[98:101], v[202:205], v[218:221], v[98:101]
	v_mfma_f32_16x16x32_bf16 v[86:89], v[194:197], v[226:229], v[86:89]
	s_setprio 2
	s_barrier
	v_mfma_f32_16x16x32_bf16 v[82:85], v[202:205], v[226:229], v[82:85]
	v_mfma_f32_16x16x32_bf16 v[70:73], v[194:197], v[234:237], v[70:73]
	v_mfma_f32_16x16x32_bf16 v[66:69], v[202:205], v[234:237], v[66:69]
	s_setprio 0
	s_add_i32 s56, s56, s26
	v_lshl_add_u64 v[156:157], s[68:69], 0, v[134:135]
	s_mov_b32 m0, s56
	ds_read_b128 v[206:209], v161 offset:16384
	ds_read_b128 v[210:213], v161 offset:17408
	ds_read_b128 v[214:217], v161 offset:18432
	ds_read_b128 v[218:221], v161 offset:19456
	ds_read_b128 v[222:225], v161 offset:20480
	ds_read_b128 v[226:229], v161 offset:21504
	ds_read_b128 v[230:233], v161 offset:22528
	ds_read_b128 v[234:237], v161 offset:23552
	global_load_lds_dwordx4 v[156:157], off
	s_add_i32 m0, s56, 0x2000
	v_lshl_add_u64 v[164:165], s[68:69], 0, v[132:133]
	s_add_u32 s68, s68, s92
	s_addc_u32 s69, s69, 0
	s_add_i32 s37, s37, s26
	global_load_lds_dwordx4 v[164:165], off
	v_lshl_add_u64 v[238:239], s[68:69], 0, v[134:135]
	s_mov_b32 m0, s37
	v_lshl_add_u64 v[240:241], s[68:69], 0, v[132:133]
	global_load_lds_dwordx4 v[238:239], off
	s_add_i32 m0, s37, 0x2000
	v_lshl_add_u64 v[242:243], s[22:23], 0, v[146:147]
	global_load_lds_dwordx4 v[240:241], off
	s_mov_b32 m0, s45
	v_lshl_add_u64 v[244:245], s[22:23], 0, v[144:145]
	global_load_lds_dwordx4 v[242:243], off
	s_mov_b32 m0, s46
	s_nop 0
	global_load_lds_dwordx4 v[244:245], off
	s_waitcnt vmcnt(32)
	s_waitcnt lgkmcnt(0)
	s_barrier
	s_setprio 1
	s_waitcnt lgkmcnt(0)
	v_mfma_f32_16x16x32_bf16 v[62:65], v[152:155], v[206:209], 0
	v_mfma_f32_16x16x32_bf16 v[58:61], v[182:185], v[206:209], 0
	v_mfma_f32_16x16x32_bf16 v[46:49], v[152:155], v[214:217], 0
	v_mfma_f32_16x16x32_bf16 v[42:45], v[182:185], v[214:217], 0
	v_mfma_f32_16x16x32_bf16 v[30:33], v[152:155], v[222:225], 0
	v_mfma_f32_16x16x32_bf16 v[26:29], v[182:185], v[222:225], 0
	v_mfma_f32_16x16x32_bf16 v[14:17], v[152:155], v[230:233], 0
	v_mfma_f32_16x16x32_bf16 v[10:13], v[182:185], v[230:233], 0
	v_mfma_f32_16x16x32_bf16 v[62:65], v[178:181], v[210:213], v[62:65]
	v_mfma_f32_16x16x32_bf16 v[58:61], v[186:189], v[210:213], v[58:61]
	v_mfma_f32_16x16x32_bf16 v[46:49], v[178:181], v[218:221], v[46:49]
	v_mfma_f32_16x16x32_bf16 v[42:45], v[186:189], v[218:221], v[42:45]
	v_mfma_f32_16x16x32_bf16 v[30:33], v[178:181], v[226:229], v[30:33]
	v_mfma_f32_16x16x32_bf16 v[26:29], v[186:189], v[226:229], v[26:29]
	v_mfma_f32_16x16x32_bf16 v[14:17], v[178:181], v[234:237], v[14:17]
	v_mfma_f32_16x16x32_bf16 v[10:13], v[186:189], v[234:237], v[10:13]
	s_setprio 0
	s_setprio 1
	v_mfma_f32_16x16x32_bf16 v[54:57], v[190:193], v[206:209], 0
	v_mfma_f32_16x16x32_bf16 v[50:53], v[198:201], v[206:209], 0
	v_mfma_f32_16x16x32_bf16 v[38:41], v[190:193], v[214:217], 0
	v_mfma_f32_16x16x32_bf16 v[34:37], v[198:201], v[214:217], 0
	v_mfma_f32_16x16x32_bf16 v[22:25], v[190:193], v[222:225], 0
	v_mfma_f32_16x16x32_bf16 v[18:21], v[198:201], v[222:225], 0
	v_mfma_f32_16x16x32_bf16 v[6:9], v[190:193], v[230:233], 0
	v_mfma_f32_16x16x32_bf16 v[2:5], v[198:201], v[230:233], 0
	v_mfma_f32_16x16x32_bf16 v[54:57], v[194:197], v[210:213], v[54:57]
	v_mfma_f32_16x16x32_bf16 v[50:53], v[202:205], v[210:213], v[50:53]
	v_mfma_f32_16x16x32_bf16 v[38:41], v[194:197], v[218:221], v[38:41]
	v_mfma_f32_16x16x32_bf16 v[34:37], v[202:205], v[218:221], v[34:37]
	v_mfma_f32_16x16x32_bf16 v[22:25], v[194:197], v[226:229], v[22:25]
	s_setprio 2
	s_barrier
	v_mfma_f32_16x16x32_bf16 v[18:21], v[202:205], v[226:229], v[18:21]
	v_mfma_f32_16x16x32_bf16 v[6:9], v[194:197], v[234:237], v[6:9]
	v_mfma_f32_16x16x32_bf16 v[2:5], v[202:205], v[234:237], v[2:5]
	s_setprio 0
	s_add_i32 s37, 0, 0x18000
	v_add_u32_e32 v162, s37, v159
	s_add_i32 s56, 0, 0x1c000
	ds_read_b128 v[152:155], v162
	ds_read_b128 v[178:181], v162 offset:1024
	ds_read_b128 v[182:185], v162 offset:2048
	ds_read_b128 v[186:189], v162 offset:3072
	v_add_u32_e32 v162, s56, v159
	ds_read_b128 v[190:193], v162
	ds_read_b128 v[194:197], v162 offset:1024
	ds_read_b128 v[198:201], v162 offset:2048
	ds_read_b128 v[202:205], v162 offset:3072
	s_add_u32 s22, s22, s92
	s_addc_u32 s23, s23, 0
	s_mov_b32 m0, s47
	v_lshl_add_u64 v[246:247], s[22:23], 0, v[146:147]
	ds_read_b128 v[206:209], v161 offset:32768
	ds_read_b128 v[210:213], v161 offset:33792
	ds_read_b128 v[214:217], v161 offset:34816
	ds_read_b128 v[218:221], v161 offset:35840
	ds_read_b128 v[222:225], v161 offset:36864
	ds_read_b128 v[226:229], v161 offset:37888
	ds_read_b128 v[230:233], v161 offset:38912
	ds_read_b128 v[234:237], v161 offset:39936
	global_load_lds_dwordx4 v[246:247], off
	v_lshl_add_u64 v[246:247], s[22:23], 0, v[144:145]
	s_mov_b32 m0, s50
	s_nop 0
	global_load_lds_dwordx4 v[246:247], off
	s_waitcnt vmcnt(8)
	s_waitcnt lgkmcnt(0)
	s_barrier
	s_setprio 1
	s_waitcnt lgkmcnt(0)
	v_mfma_f32_16x16x32_bf16 v[126:129], v[152:155], v[206:209], v[126:129]
	v_mfma_f32_16x16x32_bf16 v[122:125], v[182:185], v[206:209], v[122:125]
	v_mfma_f32_16x16x32_bf16 v[110:113], v[152:155], v[214:217], v[110:113]
	v_mfma_f32_16x16x32_bf16 v[106:109], v[182:185], v[214:217], v[106:109]
	v_mfma_f32_16x16x32_bf16 v[94:97], v[152:155], v[222:225], v[94:97]
	v_mfma_f32_16x16x32_bf16 v[90:93], v[182:185], v[222:225], v[90:93]
	v_mfma_f32_16x16x32_bf16 v[78:81], v[152:155], v[230:233], v[78:81]
	v_mfma_f32_16x16x32_bf16 v[74:77], v[182:185], v[230:233], v[74:77]
	v_mfma_f32_16x16x32_bf16 v[126:129], v[178:181], v[210:213], v[126:129]
	v_mfma_f32_16x16x32_bf16 v[122:125], v[186:189], v[210:213], v[122:125]
	v_mfma_f32_16x16x32_bf16 v[110:113], v[178:181], v[218:221], v[110:113]
	v_mfma_f32_16x16x32_bf16 v[106:109], v[186:189], v[218:221], v[106:109]
	v_mfma_f32_16x16x32_bf16 v[94:97], v[178:181], v[226:229], v[94:97]
	v_mfma_f32_16x16x32_bf16 v[90:93], v[186:189], v[226:229], v[90:93]
	v_mfma_f32_16x16x32_bf16 v[78:81], v[178:181], v[234:237], v[78:81]
	v_mfma_f32_16x16x32_bf16 v[74:77], v[186:189], v[234:237], v[74:77]
	s_setprio 0
	s_setprio 1
	v_mfma_f32_16x16x32_bf16 v[118:121], v[190:193], v[206:209], v[118:121]
	v_mfma_f32_16x16x32_bf16 v[114:117], v[198:201], v[206:209], v[114:117]
	v_mfma_f32_16x16x32_bf16 v[102:105], v[190:193], v[214:217], v[102:105]
	v_mfma_f32_16x16x32_bf16 v[98:101], v[198:201], v[214:217], v[98:101]
	v_mfma_f32_16x16x32_bf16 v[86:89], v[190:193], v[222:225], v[86:89]
	v_mfma_f32_16x16x32_bf16 v[82:85], v[198:201], v[222:225], v[82:85]
	v_mfma_f32_16x16x32_bf16 v[70:73], v[190:193], v[230:233], v[70:73]
	v_mfma_f32_16x16x32_bf16 v[66:69], v[198:201], v[230:233], v[66:69]
	v_mfma_f32_16x16x32_bf16 v[118:121], v[194:197], v[210:213], v[118:121]
	v_mfma_f32_16x16x32_bf16 v[114:117], v[202:205], v[210:213], v[114:117]
	v_mfma_f32_16x16x32_bf16 v[102:105], v[194:197], v[218:221], v[102:105]
	v_mfma_f32_16x16x32_bf16 v[98:101], v[202:205], v[218:221], v[98:101]
	v_mfma_f32_16x16x32_bf16 v[86:89], v[194:197], v[226:229], v[86:89]
	s_setprio 2
	s_barrier
	v_mfma_f32_16x16x32_bf16 v[82:85], v[202:205], v[226:229], v[82:85]
	v_mfma_f32_16x16x32_bf16 v[70:73], v[194:197], v[234:237], v[70:73]
	v_mfma_f32_16x16x32_bf16 v[66:69], v[202:205], v[234:237], v[66:69]
	s_setprio 0
	s_add_i32 s22, s37, s26
	v_lshl_add_u64 v[156:157], v[156:157], 0, s[66:67]
	s_mov_b32 m0, s22
	ds_read_b128 v[206:209], v161 offset:49152
	ds_read_b128 v[210:213], v161 offset:50176
	ds_read_b128 v[214:217], v161 offset:51200
	ds_read_b128 v[218:221], v161 offset:52224
	ds_read_b128 v[222:225], v161 offset:53248
	ds_read_b128 v[226:229], v161 offset:54272
	ds_read_b128 v[230:233], v161 offset:55296
	ds_read_b128 v[234:237], v161 offset:56320
	global_load_lds_dwordx4 v[156:157], off
	v_lshl_add_u64 v[156:157], v[164:165], 0, s[66:67]
	s_add_i32 m0, s22, 0x2000
	s_add_i32 s22, s56, s26
	global_load_lds_dwordx4 v[156:157], off
	v_lshl_add_u64 v[156:157], v[238:239], 0, s[66:67]
	s_mov_b32 m0, s22
	s_nop 0
	global_load_lds_dwordx4 v[156:157], off
	v_lshl_add_u64 v[156:157], v[240:241], 0, s[66:67]
	s_add_i32 m0, s22, 0x2000
	s_nop 0
	global_load_lds_dwordx4 v[156:157], off
	v_lshl_add_u64 v[156:157], v[242:243], 0, s[66:67]
	s_mov_b32 m0, s51
	s_nop 0
	global_load_lds_dwordx4 v[156:157], off
	v_lshl_add_u64 v[156:157], v[244:245], 0, s[66:67]
	s_mov_b32 m0, s52
	s_nop 0
	global_load_lds_dwordx4 v[156:157], off
	s_waitcnt vmcnt(8)
	s_waitcnt lgkmcnt(0)
	s_barrier
	s_setprio 1
	s_waitcnt lgkmcnt(0)
	v_mfma_f32_16x16x32_bf16 v[62:65], v[152:155], v[206:209], v[62:65]
	v_mfma_f32_16x16x32_bf16 v[58:61], v[182:185], v[206:209], v[58:61]
	v_mfma_f32_16x16x32_bf16 v[46:49], v[152:155], v[214:217], v[46:49]
	v_mfma_f32_16x16x32_bf16 v[42:45], v[182:185], v[214:217], v[42:45]
	v_mfma_f32_16x16x32_bf16 v[30:33], v[152:155], v[222:225], v[30:33]
	v_mfma_f32_16x16x32_bf16 v[26:29], v[182:185], v[222:225], v[26:29]
	v_mfma_f32_16x16x32_bf16 v[14:17], v[152:155], v[230:233], v[14:17]
	v_mfma_f32_16x16x32_bf16 v[10:13], v[182:185], v[230:233], v[10:13]
	v_mfma_f32_16x16x32_bf16 v[62:65], v[178:181], v[210:213], v[62:65]
	v_mfma_f32_16x16x32_bf16 v[58:61], v[186:189], v[210:213], v[58:61]
	v_mfma_f32_16x16x32_bf16 v[46:49], v[178:181], v[218:221], v[46:49]
	v_mfma_f32_16x16x32_bf16 v[42:45], v[186:189], v[218:221], v[42:45]
	v_mfma_f32_16x16x32_bf16 v[30:33], v[178:181], v[226:229], v[30:33]
	v_mfma_f32_16x16x32_bf16 v[26:29], v[186:189], v[226:229], v[26:29]
	v_mfma_f32_16x16x32_bf16 v[14:17], v[178:181], v[234:237], v[14:17]
	v_mfma_f32_16x16x32_bf16 v[10:13], v[186:189], v[234:237], v[10:13]
	s_setprio 0
	s_setprio 1
	v_mfma_f32_16x16x32_bf16 v[54:57], v[190:193], v[206:209], v[54:57]
	v_mfma_f32_16x16x32_bf16 v[50:53], v[198:201], v[206:209], v[50:53]
	v_mfma_f32_16x16x32_bf16 v[38:41], v[190:193], v[214:217], v[38:41]
	v_mfma_f32_16x16x32_bf16 v[34:37], v[198:201], v[214:217], v[34:37]
	v_mfma_f32_16x16x32_bf16 v[22:25], v[190:193], v[222:225], v[22:25]
	v_mfma_f32_16x16x32_bf16 v[18:21], v[198:201], v[222:225], v[18:21]
	v_mfma_f32_16x16x32_bf16 v[6:9], v[190:193], v[230:233], v[6:9]
	v_mfma_f32_16x16x32_bf16 v[2:5], v[198:201], v[230:233], v[2:5]
	v_mfma_f32_16x16x32_bf16 v[54:57], v[194:197], v[210:213], v[54:57]
	v_mfma_f32_16x16x32_bf16 v[50:53], v[202:205], v[210:213], v[50:53]
	v_mfma_f32_16x16x32_bf16 v[38:41], v[194:197], v[218:221], v[38:41]
	v_mfma_f32_16x16x32_bf16 v[34:37], v[202:205], v[218:221], v[34:37]
	v_mfma_f32_16x16x32_bf16 v[22:25], v[194:197], v[226:229], v[22:25]
	s_setprio 2
	s_barrier
	v_mfma_f32_16x16x32_bf16 v[18:21], v[202:205], v[226:229], v[18:21]
	v_mfma_f32_16x16x32_bf16 v[6:9], v[194:197], v[234:237], v[6:9]
	v_mfma_f32_16x16x32_bf16 v[2:5], v[202:205], v[234:237], v[2:5]
	s_setprio 0
	s_add_u32 s12, s12, 0x100
	s_addc_u32 s13, s13, 0
	s_add_u32 s24, s24, 0x100
	s_addc_u32 s25, s25, 0
	s_cmp_ge_u32 s30, s4
	s_mov_b32 s22, s30
.LBB0_318:
	s_add_i32 s30, s22, 2
	s_add_u32 s37, s12, 0x80
	s_addc_u32 s23, s13, 0
	s_add_i32 s56, 0, 0x10000
	s_cmp_eq_u32 s5, s22
	s_cselect_b32 s23, s11, s23
	s_cselect_b32 s22, s10, s37
	v_add_u32_e32 v156, s56, v159
	s_cselect_b32 s69, s99, s25
	s_cselect_b32 s68, s98, s24
	s_add_i32 s37, 0, 0x14000
	ds_read_b128 v[152:155], v156
	ds_read_b128 v[178:181], v156 offset:1024
	ds_read_b128 v[182:185], v156 offset:2048
	ds_read_b128 v[186:189], v156 offset:3072
	v_add_u32_e32 v156, s37, v159
	ds_read_b128 v[190:193], v156
	ds_read_b128 v[194:197], v156 offset:1024
	ds_read_b128 v[198:201], v156 offset:2048
	ds_read_b128 v[202:205], v156 offset:3072
	v_lshl_add_u64 v[156:157], s[12:13], 0, v[148:149]
	s_add_i32 m0, s45, 0xc000
	ds_read_b128 v[206:209], v161
	ds_read_b128 v[210:213], v161 offset:1024
	ds_read_b128 v[214:217], v161 offset:2048
	ds_read_b128 v[218:221], v161 offset:3072
	ds_read_b128 v[222:225], v161 offset:4096
	ds_read_b128 v[226:229], v161 offset:5120
	ds_read_b128 v[230:233], v161 offset:6144
	ds_read_b128 v[234:237], v161 offset:7168
	global_load_lds_dwordx4 v[156:157], off
	v_lshl_add_u64 v[156:157], s[12:13], 0, v[150:151]
	s_add_i32 m0, s45, 0xe000
	s_nop 0
	global_load_lds_dwordx4 v[156:157], off
	s_waitcnt vmcnt(8)
	s_waitcnt lgkmcnt(0)
	s_barrier
	s_setprio 1
	s_waitcnt lgkmcnt(0)
	v_mfma_f32_16x16x32_bf16 v[126:129], v[152:155], v[206:209], v[126:129]
	v_mfma_f32_16x16x32_bf16 v[122:125], v[182:185], v[206:209], v[122:125]
	v_mfma_f32_16x16x32_bf16 v[110:113], v[152:155], v[214:217], v[110:113]
	v_mfma_f32_16x16x32_bf16 v[106:109], v[182:185], v[214:217], v[106:109]
	v_mfma_f32_16x16x32_bf16 v[94:97], v[152:155], v[222:225], v[94:97]
	v_mfma_f32_16x16x32_bf16 v[90:93], v[182:185], v[222:225], v[90:93]
	v_mfma_f32_16x16x32_bf16 v[78:81], v[152:155], v[230:233], v[78:81]
	v_mfma_f32_16x16x32_bf16 v[74:77], v[182:185], v[230:233], v[74:77]
	v_mfma_f32_16x16x32_bf16 v[126:129], v[178:181], v[210:213], v[126:129]
	v_mfma_f32_16x16x32_bf16 v[122:125], v[186:189], v[210:213], v[122:125]
	v_mfma_f32_16x16x32_bf16 v[110:113], v[178:181], v[218:221], v[110:113]
	v_mfma_f32_16x16x32_bf16 v[106:109], v[186:189], v[218:221], v[106:109]
	v_mfma_f32_16x16x32_bf16 v[94:97], v[178:181], v[226:229], v[94:97]
	v_mfma_f32_16x16x32_bf16 v[90:93], v[186:189], v[226:229], v[90:93]
	v_mfma_f32_16x16x32_bf16 v[78:81], v[178:181], v[234:237], v[78:81]
	v_mfma_f32_16x16x32_bf16 v[74:77], v[186:189], v[234:237], v[74:77]
	s_setprio 0
	s_setprio 1
	v_mfma_f32_16x16x32_bf16 v[118:121], v[190:193], v[206:209], v[118:121]
	v_mfma_f32_16x16x32_bf16 v[114:117], v[198:201], v[206:209], v[114:117]
	v_mfma_f32_16x16x32_bf16 v[102:105], v[190:193], v[214:217], v[102:105]
	v_mfma_f32_16x16x32_bf16 v[98:101], v[198:201], v[214:217], v[98:101]
	v_mfma_f32_16x16x32_bf16 v[86:89], v[190:193], v[222:225], v[86:89]
	v_mfma_f32_16x16x32_bf16 v[82:85], v[198:201], v[222:225], v[82:85]
	v_mfma_f32_16x16x32_bf16 v[70:73], v[190:193], v[230:233], v[70:73]
	v_mfma_f32_16x16x32_bf16 v[66:69], v[198:201], v[230:233], v[66:69]
	v_mfma_f32_16x16x32_bf16 v[118:121], v[194:197], v[210:213], v[118:121]
	v_mfma_f32_16x16x32_bf16 v[114:117], v[202:205], v[210:213], v[114:117]
	v_mfma_f32_16x16x32_bf16 v[102:105], v[194:197], v[218:221], v[102:105]
	v_mfma_f32_16x16x32_bf16 v[98:101], v[202:205], v[218:221], v[98:101]
	v_mfma_f32_16x16x32_bf16 v[86:89], v[194:197], v[226:229], v[86:89]
	s_setprio 2
	s_barrier
	v_mfma_f32_16x16x32_bf16 v[82:85], v[202:205], v[226:229], v[82:85]
	v_mfma_f32_16x16x32_bf16 v[70:73], v[194:197], v[234:237], v[70:73]
	v_mfma_f32_16x16x32_bf16 v[66:69], v[202:205], v[234:237], v[66:69]
	s_setprio 0
	s_add_i32 s56, s56, s26
	v_lshl_add_u64 v[156:157], s[68:69], 0, v[134:135]
	s_mov_b32 m0, s56
	ds_read_b128 v[206:209], v161 offset:16384
	ds_read_b128 v[210:213], v161 offset:17408
	ds_read_b128 v[214:217], v161 offset:18432
	ds_read_b128 v[218:221], v161 offset:19456
	ds_read_b128 v[222:225], v161 offset:20480
	ds_read_b128 v[226:229], v161 offset:21504
	ds_read_b128 v[230:233], v161 offset:22528
	ds_read_b128 v[234:237], v161 offset:23552
	global_load_lds_dwordx4 v[156:157], off
	s_add_i32 m0, s56, 0x2000
	v_lshl_add_u64 v[164:165], s[68:69], 0, v[132:133]
	s_add_u32 s68, s68, s92
	s_addc_u32 s69, s69, 0
	s_add_i32 s37, s37, s26
	global_load_lds_dwordx4 v[164:165], off
	v_lshl_add_u64 v[238:239], s[68:69], 0, v[134:135]
	s_mov_b32 m0, s37
	v_lshl_add_u64 v[240:241], s[68:69], 0, v[132:133]
	global_load_lds_dwordx4 v[238:239], off
	s_add_i32 m0, s37, 0x2000
	v_lshl_add_u64 v[242:243], s[22:23], 0, v[146:147]
	global_load_lds_dwordx4 v[240:241], off
	s_mov_b32 m0, s45
	v_lshl_add_u64 v[244:245], s[22:23], 0, v[144:145]
	global_load_lds_dwordx4 v[242:243], off
	s_mov_b32 m0, s46
	s_nop 0
	global_load_lds_dwordx4 v[244:245], off
	s_waitcnt vmcnt(8)
	s_waitcnt lgkmcnt(0)
	s_barrier
	s_setprio 1
	s_waitcnt lgkmcnt(0)
	v_mfma_f32_16x16x32_bf16 v[62:65], v[152:155], v[206:209], v[62:65]
	v_mfma_f32_16x16x32_bf16 v[58:61], v[182:185], v[206:209], v[58:61]
	v_mfma_f32_16x16x32_bf16 v[46:49], v[152:155], v[214:217], v[46:49]
	v_mfma_f32_16x16x32_bf16 v[42:45], v[182:185], v[214:217], v[42:45]
	v_mfma_f32_16x16x32_bf16 v[30:33], v[152:155], v[222:225], v[30:33]
	v_mfma_f32_16x16x32_bf16 v[26:29], v[182:185], v[222:225], v[26:29]
	v_mfma_f32_16x16x32_bf16 v[14:17], v[152:155], v[230:233], v[14:17]
	v_mfma_f32_16x16x32_bf16 v[10:13], v[182:185], v[230:233], v[10:13]
	v_mfma_f32_16x16x32_bf16 v[62:65], v[178:181], v[210:213], v[62:65]
	v_mfma_f32_16x16x32_bf16 v[58:61], v[186:189], v[210:213], v[58:61]
	v_mfma_f32_16x16x32_bf16 v[46:49], v[178:181], v[218:221], v[46:49]
	v_mfma_f32_16x16x32_bf16 v[42:45], v[186:189], v[218:221], v[42:45]
	v_mfma_f32_16x16x32_bf16 v[30:33], v[178:181], v[226:229], v[30:33]
	v_mfma_f32_16x16x32_bf16 v[26:29], v[186:189], v[226:229], v[26:29]
	v_mfma_f32_16x16x32_bf16 v[14:17], v[178:181], v[234:237], v[14:17]
	v_mfma_f32_16x16x32_bf16 v[10:13], v[186:189], v[234:237], v[10:13]
	s_setprio 0
	s_setprio 1
	v_mfma_f32_16x16x32_bf16 v[54:57], v[190:193], v[206:209], v[54:57]
	v_mfma_f32_16x16x32_bf16 v[50:53], v[198:201], v[206:209], v[50:53]
	v_mfma_f32_16x16x32_bf16 v[38:41], v[190:193], v[214:217], v[38:41]
	v_mfma_f32_16x16x32_bf16 v[34:37], v[198:201], v[214:217], v[34:37]
	v_mfma_f32_16x16x32_bf16 v[22:25], v[190:193], v[222:225], v[22:25]
	v_mfma_f32_16x16x32_bf16 v[18:21], v[198:201], v[222:225], v[18:21]
	v_mfma_f32_16x16x32_bf16 v[6:9], v[190:193], v[230:233], v[6:9]
	v_mfma_f32_16x16x32_bf16 v[2:5], v[198:201], v[230:233], v[2:5]
	v_mfma_f32_16x16x32_bf16 v[54:57], v[194:197], v[210:213], v[54:57]
	v_mfma_f32_16x16x32_bf16 v[50:53], v[202:205], v[210:213], v[50:53]
	v_mfma_f32_16x16x32_bf16 v[38:41], v[194:197], v[218:221], v[38:41]
	v_mfma_f32_16x16x32_bf16 v[34:37], v[202:205], v[218:221], v[34:37]
	v_mfma_f32_16x16x32_bf16 v[22:25], v[194:197], v[226:229], v[22:25]
	s_setprio 2
	s_barrier
	v_mfma_f32_16x16x32_bf16 v[18:21], v[202:205], v[226:229], v[18:21]
	v_mfma_f32_16x16x32_bf16 v[6:9], v[194:197], v[234:237], v[6:9]
	v_mfma_f32_16x16x32_bf16 v[2:5], v[202:205], v[234:237], v[2:5]
	s_setprio 0
	s_add_i32 s37, 0, 0x18000
	v_add_u32_e32 v162, s37, v159
	s_add_i32 s56, 0, 0x1c000
	ds_read_b128 v[152:155], v162
	ds_read_b128 v[178:181], v162 offset:1024
	ds_read_b128 v[182:185], v162 offset:2048
	ds_read_b128 v[186:189], v162 offset:3072
	v_add_u32_e32 v162, s56, v159
	ds_read_b128 v[190:193], v162
	ds_read_b128 v[194:197], v162 offset:1024
	ds_read_b128 v[198:201], v162 offset:2048
	ds_read_b128 v[202:205], v162 offset:3072
	s_add_u32 s22, s22, s92
	s_addc_u32 s23, s23, 0
	s_mov_b32 m0, s47
	v_lshl_add_u64 v[246:247], s[22:23], 0, v[146:147]
	ds_read_b128 v[206:209], v161 offset:32768
	ds_read_b128 v[210:213], v161 offset:33792
	ds_read_b128 v[214:217], v161 offset:34816
	ds_read_b128 v[218:221], v161 offset:35840
	ds_read_b128 v[222:225], v161 offset:36864
	ds_read_b128 v[226:229], v161 offset:37888
	ds_read_b128 v[230:233], v161 offset:38912
	ds_read_b128 v[234:237], v161 offset:39936
	global_load_lds_dwordx4 v[246:247], off
	v_lshl_add_u64 v[246:247], s[22:23], 0, v[144:145]
	s_mov_b32 m0, s50
	s_nop 0
	global_load_lds_dwordx4 v[246:247], off
	s_waitcnt vmcnt(8)
	s_waitcnt lgkmcnt(0)
	s_barrier
	s_setprio 1
	s_waitcnt lgkmcnt(0)
	v_mfma_f32_16x16x32_bf16 v[126:129], v[152:155], v[206:209], v[126:129]
	v_mfma_f32_16x16x32_bf16 v[122:125], v[182:185], v[206:209], v[122:125]
	v_mfma_f32_16x16x32_bf16 v[110:113], v[152:155], v[214:217], v[110:113]
	v_mfma_f32_16x16x32_bf16 v[106:109], v[182:185], v[214:217], v[106:109]
	v_mfma_f32_16x16x32_bf16 v[94:97], v[152:155], v[222:225], v[94:97]
	v_mfma_f32_16x16x32_bf16 v[90:93], v[182:185], v[222:225], v[90:93]
	v_mfma_f32_16x16x32_bf16 v[78:81], v[152:155], v[230:233], v[78:81]
	v_mfma_f32_16x16x32_bf16 v[74:77], v[182:185], v[230:233], v[74:77]
	v_mfma_f32_16x16x32_bf16 v[126:129], v[178:181], v[210:213], v[126:129]
	v_mfma_f32_16x16x32_bf16 v[122:125], v[186:189], v[210:213], v[122:125]
	v_mfma_f32_16x16x32_bf16 v[110:113], v[178:181], v[218:221], v[110:113]
	v_mfma_f32_16x16x32_bf16 v[106:109], v[186:189], v[218:221], v[106:109]
	v_mfma_f32_16x16x32_bf16 v[94:97], v[178:181], v[226:229], v[94:97]
	v_mfma_f32_16x16x32_bf16 v[90:93], v[186:189], v[226:229], v[90:93]
	v_mfma_f32_16x16x32_bf16 v[78:81], v[178:181], v[234:237], v[78:81]
	v_mfma_f32_16x16x32_bf16 v[74:77], v[186:189], v[234:237], v[74:77]
	s_setprio 0
	s_setprio 1
	v_mfma_f32_16x16x32_bf16 v[118:121], v[190:193], v[206:209], v[118:121]
	v_mfma_f32_16x16x32_bf16 v[114:117], v[198:201], v[206:209], v[114:117]
	v_mfma_f32_16x16x32_bf16 v[102:105], v[190:193], v[214:217], v[102:105]
	v_mfma_f32_16x16x32_bf16 v[98:101], v[198:201], v[214:217], v[98:101]
	v_mfma_f32_16x16x32_bf16 v[86:89], v[190:193], v[222:225], v[86:89]
	v_mfma_f32_16x16x32_bf16 v[82:85], v[198:201], v[222:225], v[82:85]
	v_mfma_f32_16x16x32_bf16 v[70:73], v[190:193], v[230:233], v[70:73]
	v_mfma_f32_16x16x32_bf16 v[66:69], v[198:201], v[230:233], v[66:69]
	v_mfma_f32_16x16x32_bf16 v[118:121], v[194:197], v[210:213], v[118:121]
	v_mfma_f32_16x16x32_bf16 v[114:117], v[202:205], v[210:213], v[114:117]
	v_mfma_f32_16x16x32_bf16 v[102:105], v[194:197], v[218:221], v[102:105]
	v_mfma_f32_16x16x32_bf16 v[98:101], v[202:205], v[218:221], v[98:101]
	v_mfma_f32_16x16x32_bf16 v[86:89], v[194:197], v[226:229], v[86:89]
	s_setprio 2
	s_barrier
	v_mfma_f32_16x16x32_bf16 v[82:85], v[202:205], v[226:229], v[82:85]
	v_mfma_f32_16x16x32_bf16 v[70:73], v[194:197], v[234:237], v[70:73]
	v_mfma_f32_16x16x32_bf16 v[66:69], v[202:205], v[234:237], v[66:69]
	s_setprio 0
	s_add_i32 s22, s37, s26
	v_lshl_add_u64 v[156:157], v[156:157], 0, s[66:67]
	s_mov_b32 m0, s22
	ds_read_b128 v[206:209], v161 offset:49152
	ds_read_b128 v[210:213], v161 offset:50176
	ds_read_b128 v[214:217], v161 offset:51200
	ds_read_b128 v[218:221], v161 offset:52224
	ds_read_b128 v[222:225], v161 offset:53248
	ds_read_b128 v[226:229], v161 offset:54272
	ds_read_b128 v[230:233], v161 offset:55296
	ds_read_b128 v[234:237], v161 offset:56320
	global_load_lds_dwordx4 v[156:157], off
	v_lshl_add_u64 v[156:157], v[164:165], 0, s[66:67]
	s_add_i32 m0, s22, 0x2000
	s_add_i32 s22, s56, s26
	global_load_lds_dwordx4 v[156:157], off
	v_lshl_add_u64 v[156:157], v[238:239], 0, s[66:67]
	s_mov_b32 m0, s22
	s_nop 0
	global_load_lds_dwordx4 v[156:157], off
	v_lshl_add_u64 v[156:157], v[240:241], 0, s[66:67]
	s_add_i32 m0, s22, 0x2000
	s_nop 0
	global_load_lds_dwordx4 v[156:157], off
	v_lshl_add_u64 v[156:157], v[242:243], 0, s[66:67]
	s_mov_b32 m0, s51
	s_nop 0
	global_load_lds_dwordx4 v[156:157], off
	v_lshl_add_u64 v[156:157], v[244:245], 0, s[66:67]
	s_mov_b32 m0, s52
	s_nop 0
	global_load_lds_dwordx4 v[156:157], off
	s_waitcnt vmcnt(8)
	s_waitcnt lgkmcnt(0)
	s_barrier
	s_setprio 1
	s_waitcnt lgkmcnt(0)
	v_mfma_f32_16x16x32_bf16 v[62:65], v[152:155], v[206:209], v[62:65]
	v_mfma_f32_16x16x32_bf16 v[58:61], v[182:185], v[206:209], v[58:61]
	v_mfma_f32_16x16x32_bf16 v[46:49], v[152:155], v[214:217], v[46:49]
	v_mfma_f32_16x16x32_bf16 v[42:45], v[182:185], v[214:217], v[42:45]
	v_mfma_f32_16x16x32_bf16 v[30:33], v[152:155], v[222:225], v[30:33]
	v_mfma_f32_16x16x32_bf16 v[26:29], v[182:185], v[222:225], v[26:29]
	v_mfma_f32_16x16x32_bf16 v[14:17], v[152:155], v[230:233], v[14:17]
	v_mfma_f32_16x16x32_bf16 v[10:13], v[182:185], v[230:233], v[10:13]
	v_mfma_f32_16x16x32_bf16 v[62:65], v[178:181], v[210:213], v[62:65]
	v_mfma_f32_16x16x32_bf16 v[58:61], v[186:189], v[210:213], v[58:61]
	v_mfma_f32_16x16x32_bf16 v[46:49], v[178:181], v[218:221], v[46:49]
	v_mfma_f32_16x16x32_bf16 v[42:45], v[186:189], v[218:221], v[42:45]
	v_mfma_f32_16x16x32_bf16 v[30:33], v[178:181], v[226:229], v[30:33]
	v_mfma_f32_16x16x32_bf16 v[26:29], v[186:189], v[226:229], v[26:29]
	v_mfma_f32_16x16x32_bf16 v[14:17], v[178:181], v[234:237], v[14:17]
	v_mfma_f32_16x16x32_bf16 v[10:13], v[186:189], v[234:237], v[10:13]
	s_setprio 0
	s_setprio 1
	v_mfma_f32_16x16x32_bf16 v[54:57], v[190:193], v[206:209], v[54:57]
	v_mfma_f32_16x16x32_bf16 v[50:53], v[198:201], v[206:209], v[50:53]
	v_mfma_f32_16x16x32_bf16 v[38:41], v[190:193], v[214:217], v[38:41]
	v_mfma_f32_16x16x32_bf16 v[34:37], v[198:201], v[214:217], v[34:37]
	v_mfma_f32_16x16x32_bf16 v[22:25], v[190:193], v[222:225], v[22:25]
	v_mfma_f32_16x16x32_bf16 v[18:21], v[198:201], v[222:225], v[18:21]
	v_mfma_f32_16x16x32_bf16 v[6:9], v[190:193], v[230:233], v[6:9]
	v_mfma_f32_16x16x32_bf16 v[2:5], v[198:201], v[230:233], v[2:5]
	v_mfma_f32_16x16x32_bf16 v[54:57], v[194:197], v[210:213], v[54:57]
	v_mfma_f32_16x16x32_bf16 v[50:53], v[202:205], v[210:213], v[50:53]
	v_mfma_f32_16x16x32_bf16 v[38:41], v[194:197], v[218:221], v[38:41]
	v_mfma_f32_16x16x32_bf16 v[34:37], v[202:205], v[218:221], v[34:37]
	v_mfma_f32_16x16x32_bf16 v[22:25], v[194:197], v[226:229], v[22:25]
	s_setprio 2
	s_barrier
	v_mfma_f32_16x16x32_bf16 v[18:21], v[202:205], v[226:229], v[18:21]
	v_mfma_f32_16x16x32_bf16 v[6:9], v[194:197], v[234:237], v[6:9]
	v_mfma_f32_16x16x32_bf16 v[2:5], v[202:205], v[234:237], v[2:5]
	s_setprio 0
	s_add_u32 s12, s12, 0x100
	s_addc_u32 s13, s13, 0
	s_add_u32 s24, s24, 0x100
	s_addc_u32 s25, s25, 0
	s_cmp_ge_u32 s30, s4
	s_mov_b32 s22, s30
	s_cbranch_scc0 .LBB0_318
	v_lshl_or_b32 v184, s19, 8, v160
	v_ashrrev_i32_e32 v185, 31, v184
	v_lshl_add_u32 v182, s21, 8, v131
	v_ashrrev_i32_e32 v183, 31, v182
	v_lshlrev_b64 v[182:183], 11, v[182:183]
	v_lshl_add_u64 v[182:183], s[78:79], 0, v[182:183]
	v_lshl_add_u64 v[182:183], v[184:185], 1, v[182:183]
	global_load_dwordx4 v[186:189], v[182:183], off
	global_load_dwordx4 v[190:193], v[182:183], off offset:256
	v_lshl_add_u32 v182, s21, 8, v131
	v_add_u32_e32 v182, 16, v182
	v_ashrrev_i32_e32 v183, 31, v182
	v_lshlrev_b64 v[182:183], 11, v[182:183]
	v_lshl_add_u64 v[182:183], s[78:79], 0, v[182:183]
	v_lshl_add_u64 v[182:183], v[184:185], 1, v[182:183]
	global_load_dwordx4 v[194:197], v[182:183], off
	global_load_dwordx4 v[198:201], v[182:183], off offset:256
	v_lshl_add_u32 v182, s21, 8, v131
	v_add_u32_e32 v182, 32, v182
	v_ashrrev_i32_e32 v183, 31, v182
	v_lshlrev_b64 v[182:183], 11, v[182:183]
	v_lshl_add_u64 v[182:183], s[78:79], 0, v[182:183]
	v_lshl_add_u64 v[182:183], v[184:185], 1, v[182:183]
	global_load_dwordx4 v[202:205], v[182:183], off
	global_load_dwordx4 v[206:209], v[182:183], off offset:256
	v_lshl_add_u32 v182, s21, 8, v131
	v_add_u32_e32 v182, 48, v182
	v_ashrrev_i32_e32 v183, 31, v182
	v_lshlrev_b64 v[182:183], 11, v[182:183]
	v_lshl_add_u64 v[182:183], s[78:79], 0, v[182:183]
	v_lshl_add_u64 v[182:183], v[184:185], 1, v[182:183]
	global_load_dwordx4 v[210:213], v[182:183], off
	global_load_dwordx4 v[214:217], v[182:183], off offset:256
	v_lshl_add_u32 v182, s21, 8, v131
	v_add_u32_e32 v182, 0x80, v182
	v_ashrrev_i32_e32 v183, 31, v182
	v_lshlrev_b64 v[182:183], 11, v[182:183]
	v_lshl_add_u64 v[182:183], s[78:79], 0, v[182:183]
	v_lshl_add_u64 v[182:183], v[184:185], 1, v[182:183]
	global_load_dwordx4 v[218:221], v[182:183], off
	global_load_dwordx4 v[222:225], v[182:183], off offset:256
	v_lshl_add_u32 v182, s21, 8, v131
	v_add_u32_e32 v182, 0x90, v182
	v_ashrrev_i32_e32 v183, 31, v182
	v_lshlrev_b64 v[182:183], 11, v[182:183]
	v_lshl_add_u64 v[182:183], s[78:79], 0, v[182:183]
	v_lshl_add_u64 v[182:183], v[184:185], 1, v[182:183]
	global_load_dwordx4 v[226:229], v[182:183], off
	global_load_dwordx4 v[230:233], v[182:183], off offset:256
	v_lshl_add_u32 v182, s21, 8, v131
	v_add_u32_e32 v182, 0xa0, v182
	v_ashrrev_i32_e32 v183, 31, v182
	v_lshlrev_b64 v[182:183], 11, v[182:183]
	v_lshl_add_u64 v[182:183], s[78:79], 0, v[182:183]
	v_lshl_add_u64 v[182:183], v[184:185], 1, v[182:183]
	global_load_dwordx4 v[234:237], v[182:183], off
	global_load_dwordx4 v[238:241], v[182:183], off offset:256
	v_lshl_add_u32 v182, s21, 8, v131
	v_add_u32_e32 v182, 0xb0, v182
	v_ashrrev_i32_e32 v183, 31, v182
	v_lshlrev_b64 v[182:183], 11, v[182:183]
	v_lshl_add_u64 v[182:183], s[78:79], 0, v[182:183]
	v_lshl_add_u64 v[182:183], v[184:185], 1, v[182:183]
	global_load_dwordx4 v[242:245], v[182:183], off
	global_load_dwordx4 v[246:249], v[182:183], off offset:256
	s_and_b64 vcc, exec, s[96:97]
	s_cbranch_vccz .LBB0_321
	s_barrier

.LBB0_371:
	s_add_u32 s50, s46, 0xfffc0080
	s_addc_u32 s51, s47, -1
	s_add_i32 s70, 0, 0x10000
	s_cmp_eq_u32 s69, 12
	s_cselect_b32 s53, s13, s51
	s_cselect_b32 s52, s62, s50
	v_add_u32_e32 v179, s70, v165
	s_cselect_b32 s51, s11, s68
	s_cselect_b32 s50, s64, s65
	s_add_i32 s72, 0, 0x14000
	ds_read_b128 v[180:183], v179
	ds_read_b128 v[184:187], v179 offset:1024
	ds_read_b128 v[188:191], v179 offset:2048
	ds_read_b128 v[192:195], v179 offset:3072
	v_add_u32_e32 v179, s72, v165
	ds_read_b128 v[196:199], v179
	ds_read_b128 v[200:203], v179 offset:1024
	ds_read_b128 v[204:207], v179 offset:2048
	ds_read_b128 v[208:211], v179 offset:3072
	v_lshl_add_u64 v[244:245], s[46:47], 0, v[150:151]
	s_add_i32 m0, s24, 0xc000
	ds_read_b128 v[212:215], v178
	ds_read_b128 v[216:219], v178 offset:1024
	ds_read_b128 v[220:223], v178 offset:2048
	ds_read_b128 v[224:227], v178 offset:3072
	ds_read_b128 v[228:231], v178 offset:4096
	ds_read_b128 v[232:235], v178 offset:5120
	ds_read_b128 v[236:239], v178 offset:6144
	ds_read_b128 v[240:243], v178 offset:7168
	global_load_lds_dwordx4 v[244:245], off
	v_lshl_add_u64 v[244:245], s[46:47], 0, v[152:153]
	s_add_i32 m0, s24, 0xe000
	s_nop 0
	global_load_lds_dwordx4 v[244:245], off
	s_waitcnt vmcnt(8)
	s_waitcnt lgkmcnt(0)
	s_barrier
	s_setprio 1
	s_waitcnt lgkmcnt(0)
	v_mfma_f32_16x16x32_bf16 v[126:129], v[180:183], v[212:215], v[126:129]
	v_mfma_f32_16x16x32_bf16 v[122:125], v[188:191], v[212:215], v[122:125]
	v_mfma_f32_16x16x32_bf16 v[118:121], v[180:183], v[220:223], v[118:121]
	v_mfma_f32_16x16x32_bf16 v[114:117], v[188:191], v[220:223], v[114:117]
	v_mfma_f32_16x16x32_bf16 v[102:105], v[180:183], v[228:231], v[102:105]
	v_mfma_f32_16x16x32_bf16 v[98:101], v[188:191], v[228:231], v[98:101]
	v_mfma_f32_16x16x32_bf16 v[86:89], v[180:183], v[236:239], v[86:89]
	v_mfma_f32_16x16x32_bf16 v[82:85], v[188:191], v[236:239], v[82:85]
	v_mfma_f32_16x16x32_bf16 v[126:129], v[184:187], v[216:219], v[126:129]
	v_mfma_f32_16x16x32_bf16 v[122:125], v[192:195], v[216:219], v[122:125]
	v_mfma_f32_16x16x32_bf16 v[118:121], v[184:187], v[224:227], v[118:121]
	v_mfma_f32_16x16x32_bf16 v[114:117], v[192:195], v[224:227], v[114:117]
	v_mfma_f32_16x16x32_bf16 v[102:105], v[184:187], v[232:235], v[102:105]
	v_mfma_f32_16x16x32_bf16 v[98:101], v[192:195], v[232:235], v[98:101]
	v_mfma_f32_16x16x32_bf16 v[86:89], v[184:187], v[240:243], v[86:89]
	v_mfma_f32_16x16x32_bf16 v[82:85], v[192:195], v[240:243], v[82:85]
	s_setprio 0
	s_setprio 1
	v_mfma_f32_16x16x32_bf16 v[110:113], v[196:199], v[212:215], v[110:113]
	v_mfma_f32_16x16x32_bf16 v[106:109], v[204:207], v[212:215], v[106:109]
	v_mfma_f32_16x16x32_bf16 v[94:97], v[196:199], v[220:223], v[94:97]
	v_mfma_f32_16x16x32_bf16 v[90:93], v[204:207], v[220:223], v[90:93]
	v_mfma_f32_16x16x32_bf16 v[78:81], v[196:199], v[228:231], v[78:81]
	v_mfma_f32_16x16x32_bf16 v[74:77], v[204:207], v[228:231], v[74:77]
	v_mfma_f32_16x16x32_bf16 v[70:73], v[196:199], v[236:239], v[70:73]
	v_mfma_f32_16x16x32_bf16 v[66:69], v[204:207], v[236:239], v[66:69]
	v_mfma_f32_16x16x32_bf16 v[110:113], v[200:203], v[216:219], v[110:113]
	v_mfma_f32_16x16x32_bf16 v[106:109], v[208:211], v[216:219], v[106:109]
	v_mfma_f32_16x16x32_bf16 v[94:97], v[200:203], v[224:227], v[94:97]
	v_mfma_f32_16x16x32_bf16 v[90:93], v[208:211], v[224:227], v[90:93]
	v_mfma_f32_16x16x32_bf16 v[78:81], v[200:203], v[232:235], v[78:81]
	s_setprio 2
	s_barrier
	v_mfma_f32_16x16x32_bf16 v[74:77], v[208:211], v[232:235], v[74:77]
	v_mfma_f32_16x16x32_bf16 v[70:73], v[200:203], v[240:243], v[70:73]
	v_mfma_f32_16x16x32_bf16 v[66:69], v[208:211], v[240:243], v[66:69]
	s_setprio 0
	s_add_i32 s70, s70, s21
	v_lshl_add_u64 v[244:245], s[50:51], 0, v[134:135]
	s_mov_b32 m0, s70
	ds_read_b128 v[212:215], v178 offset:16384
	ds_read_b128 v[216:219], v178 offset:17408
	ds_read_b128 v[220:223], v178 offset:18432
	ds_read_b128 v[224:227], v178 offset:19456
	ds_read_b128 v[228:231], v178 offset:20480
	ds_read_b128 v[232:235], v178 offset:21504
	ds_read_b128 v[236:239], v178 offset:22528
	ds_read_b128 v[240:243], v178 offset:23552
	global_load_lds_dwordx4 v[244:245], off
	s_add_i32 m0, s70, 0x2000
	s_add_u32 s70, s50, 0x40000
	v_lshl_add_u64 v[246:247], s[50:51], 0, v[146:147]
	s_addc_u32 s71, s51, 0
	s_add_i32 s72, s72, s21
	global_load_lds_dwordx4 v[246:247], off
	v_lshl_add_u64 v[248:249], s[70:71], 0, v[134:135]
	s_mov_b32 m0, s72
	v_lshl_add_u64 v[250:251], s[52:53], 0, v[144:145]
	global_load_lds_dwordx4 v[248:249], off
	v_lshl_add_u64 v[248:249], s[70:71], 0, v[146:147]
	s_add_i32 m0, s72, 0x2000
	s_nop 0
	global_load_lds_dwordx4 v[248:249], off
	v_lshl_add_u64 v[248:249], s[52:53], 0, v[132:133]
	s_mov_b32 m0, s24
	s_nop 0
	global_load_lds_dwordx4 v[248:249], off
	s_mov_b32 m0, s25
	s_nop 0
	global_load_lds_dwordx4 v[250:251], off
	s_waitcnt vmcnt(8)
	s_waitcnt lgkmcnt(0)
	s_barrier
	s_setprio 1
	s_waitcnt lgkmcnt(0)
	v_mfma_f32_16x16x32_bf16 v[62:65], v[180:183], v[212:215], v[62:65]
	v_mfma_f32_16x16x32_bf16 v[58:61], v[188:191], v[212:215], v[58:61]
	v_mfma_f32_16x16x32_bf16 v[54:57], v[180:183], v[220:223], v[54:57]
	v_mfma_f32_16x16x32_bf16 v[50:53], v[188:191], v[220:223], v[50:53]
	v_mfma_f32_16x16x32_bf16 v[38:41], v[180:183], v[228:231], v[38:41]
	v_mfma_f32_16x16x32_bf16 v[34:37], v[188:191], v[228:231], v[34:37]
	v_mfma_f32_16x16x32_bf16 v[22:25], v[180:183], v[236:239], v[22:25]
	v_mfma_f32_16x16x32_bf16 v[18:21], v[188:191], v[236:239], v[18:21]
	v_mfma_f32_16x16x32_bf16 v[62:65], v[184:187], v[216:219], v[62:65]
	v_mfma_f32_16x16x32_bf16 v[58:61], v[192:195], v[216:219], v[58:61]
	v_mfma_f32_16x16x32_bf16 v[54:57], v[184:187], v[224:227], v[54:57]
	v_mfma_f32_16x16x32_bf16 v[50:53], v[192:195], v[224:227], v[50:53]
	v_mfma_f32_16x16x32_bf16 v[38:41], v[184:187], v[232:235], v[38:41]
	v_mfma_f32_16x16x32_bf16 v[34:37], v[192:195], v[232:235], v[34:37]
	v_mfma_f32_16x16x32_bf16 v[22:25], v[184:187], v[240:243], v[22:25]
	v_mfma_f32_16x16x32_bf16 v[18:21], v[192:195], v[240:243], v[18:21]
	s_setprio 0
	s_setprio 1
	v_mfma_f32_16x16x32_bf16 v[46:49], v[196:199], v[212:215], v[46:49]
	v_mfma_f32_16x16x32_bf16 v[42:45], v[204:207], v[212:215], v[42:45]
	v_mfma_f32_16x16x32_bf16 v[30:33], v[196:199], v[220:223], v[30:33]
	v_mfma_f32_16x16x32_bf16 v[26:29], v[204:207], v[220:223], v[26:29]
	v_mfma_f32_16x16x32_bf16 v[14:17], v[196:199], v[228:231], v[14:17]
	v_mfma_f32_16x16x32_bf16 v[10:13], v[204:207], v[228:231], v[10:13]
	v_mfma_f32_16x16x32_bf16 v[6:9], v[196:199], v[236:239], v[6:9]
	v_mfma_f32_16x16x32_bf16 v[2:5], v[204:207], v[236:239], v[2:5]
	v_mfma_f32_16x16x32_bf16 v[46:49], v[200:203], v[216:219], v[46:49]
	v_mfma_f32_16x16x32_bf16 v[42:45], v[208:211], v[216:219], v[42:45]
	v_mfma_f32_16x16x32_bf16 v[30:33], v[200:203], v[224:227], v[30:33]
	v_mfma_f32_16x16x32_bf16 v[26:29], v[208:211], v[224:227], v[26:29]
	v_mfma_f32_16x16x32_bf16 v[14:17], v[200:203], v[232:235], v[14:17]
	s_setprio 2
	s_barrier
	v_mfma_f32_16x16x32_bf16 v[10:13], v[208:211], v[232:235], v[10:13]
	v_mfma_f32_16x16x32_bf16 v[6:9], v[200:203], v[240:243], v[6:9]
	v_mfma_f32_16x16x32_bf16 v[2:5], v[208:211], v[240:243], v[2:5]
	s_setprio 0
	s_add_i32 s70, 0, 0x18000
	v_add_u32_e32 v179, s70, v165
	s_add_i32 s71, 0, 0x1c000
	ds_read_b128 v[180:183], v179
	ds_read_b128 v[184:187], v179 offset:1024
	ds_read_b128 v[188:191], v179 offset:2048
	ds_read_b128 v[192:195], v179 offset:3072
	v_add_u32_e32 v179, s71, v165
	ds_read_b128 v[196:199], v179
	ds_read_b128 v[200:203], v179 offset:1024
	ds_read_b128 v[204:207], v179 offset:2048
	ds_read_b128 v[208:211], v179 offset:3072
	s_add_u32 s52, s52, 0x40000
	s_addc_u32 s53, s53, 0
	s_mov_b32 m0, s30
	v_lshl_add_u64 v[252:253], s[52:53], 0, v[132:133]
	ds_read_b128 v[212:215], v178 offset:32768
	ds_read_b128 v[216:219], v178 offset:33792
	ds_read_b128 v[220:223], v178 offset:34816
	ds_read_b128 v[224:227], v178 offset:35840
	ds_read_b128 v[228:231], v178 offset:36864
	ds_read_b128 v[232:235], v178 offset:37888
	ds_read_b128 v[236:239], v178 offset:38912
	ds_read_b128 v[240:243], v178 offset:39936
	global_load_lds_dwordx4 v[252:253], off
	v_lshl_add_u64 v[252:253], s[52:53], 0, v[144:145]
	s_mov_b32 m0, s31
	s_nop 0
	global_load_lds_dwordx4 v[252:253], off
	s_waitcnt vmcnt(8)
	s_waitcnt lgkmcnt(0)
	s_barrier
	s_setprio 1
	s_waitcnt lgkmcnt(0)
	v_mfma_f32_16x16x32_bf16 v[126:129], v[180:183], v[212:215], v[126:129]
	v_mfma_f32_16x16x32_bf16 v[122:125], v[188:191], v[212:215], v[122:125]
	v_mfma_f32_16x16x32_bf16 v[118:121], v[180:183], v[220:223], v[118:121]
	v_mfma_f32_16x16x32_bf16 v[114:117], v[188:191], v[220:223], v[114:117]
	v_mfma_f32_16x16x32_bf16 v[102:105], v[180:183], v[228:231], v[102:105]
	v_mfma_f32_16x16x32_bf16 v[98:101], v[188:191], v[228:231], v[98:101]
	v_mfma_f32_16x16x32_bf16 v[86:89], v[180:183], v[236:239], v[86:89]
	v_mfma_f32_16x16x32_bf16 v[82:85], v[188:191], v[236:239], v[82:85]
	v_mfma_f32_16x16x32_bf16 v[126:129], v[184:187], v[216:219], v[126:129]
	v_mfma_f32_16x16x32_bf16 v[122:125], v[192:195], v[216:219], v[122:125]
	v_mfma_f32_16x16x32_bf16 v[118:121], v[184:187], v[224:227], v[118:121]
	v_mfma_f32_16x16x32_bf16 v[114:117], v[192:195], v[224:227], v[114:117]
	v_mfma_f32_16x16x32_bf16 v[102:105], v[184:187], v[232:235], v[102:105]
	v_mfma_f32_16x16x32_bf16 v[98:101], v[192:195], v[232:235], v[98:101]
	v_mfma_f32_16x16x32_bf16 v[86:89], v[184:187], v[240:243], v[86:89]
	v_mfma_f32_16x16x32_bf16 v[82:85], v[192:195], v[240:243], v[82:85]
	s_setprio 0
	s_setprio 1
	v_mfma_f32_16x16x32_bf16 v[110:113], v[196:199], v[212:215], v[110:113]
	v_mfma_f32_16x16x32_bf16 v[106:109], v[204:207], v[212:215], v[106:109]
	v_mfma_f32_16x16x32_bf16 v[94:97], v[196:199], v[220:223], v[94:97]
	v_mfma_f32_16x16x32_bf16 v[90:93], v[204:207], v[220:223], v[90:93]
	v_mfma_f32_16x16x32_bf16 v[78:81], v[196:199], v[228:231], v[78:81]
	v_mfma_f32_16x16x32_bf16 v[74:77], v[204:207], v[228:231], v[74:77]
	v_mfma_f32_16x16x32_bf16 v[70:73], v[196:199], v[236:239], v[70:73]
	v_mfma_f32_16x16x32_bf16 v[66:69], v[204:207], v[236:239], v[66:69]
	v_mfma_f32_16x16x32_bf16 v[110:113], v[200:203], v[216:219], v[110:113]
	v_mfma_f32_16x16x32_bf16 v[106:109], v[208:211], v[216:219], v[106:109]
	v_mfma_f32_16x16x32_bf16 v[94:97], v[200:203], v[224:227], v[94:97]
	v_mfma_f32_16x16x32_bf16 v[90:93], v[208:211], v[224:227], v[90:93]
	v_mfma_f32_16x16x32_bf16 v[78:81], v[200:203], v[232:235], v[78:81]
	s_setprio 2
	s_barrier
	v_mfma_f32_16x16x32_bf16 v[74:77], v[208:211], v[232:235], v[74:77]
	v_mfma_f32_16x16x32_bf16 v[70:73], v[200:203], v[240:243], v[70:73]
	v_mfma_f32_16x16x32_bf16 v[66:69], v[208:211], v[240:243], v[66:69]
	s_setprio 0
	s_add_i32 s52, s70, s21
	v_lshl_add_u64 v[244:245], v[244:245], 0, s[66:67]
	s_mov_b32 m0, s52
	ds_read_b128 v[212:215], v178 offset:49152
	ds_read_b128 v[216:219], v178 offset:50176
	ds_read_b128 v[220:223], v178 offset:51200
	ds_read_b128 v[224:227], v178 offset:52224
	ds_read_b128 v[228:231], v178 offset:53248
	ds_read_b128 v[232:235], v178 offset:54272
	ds_read_b128 v[236:239], v178 offset:55296
	ds_read_b128 v[240:243], v178 offset:56320
	global_load_lds_dwordx4 v[244:245], off
	s_add_i32 m0, s52, 0x2000
	s_add_u32 s50, s50, 0x40080
	v_lshl_add_u64 v[244:245], v[246:247], 0, s[66:67]
	s_addc_u32 s51, s51, 0
	s_add_i32 s52, s71, s21
	global_load_lds_dwordx4 v[244:245], off
	v_lshl_add_u64 v[244:245], s[50:51], 0, v[134:135]
	s_mov_b32 m0, s52
	s_nop 0
	global_load_lds_dwordx4 v[244:245], off
	v_lshl_add_u64 v[244:245], s[50:51], 0, v[146:147]
	s_add_i32 m0, s52, 0x2000
	s_nop 0
	global_load_lds_dwordx4 v[244:245], off
	v_lshl_add_u64 v[244:245], v[248:249], 0, s[66:67]
	s_mov_b32 m0, s35
	s_nop 0
	global_load_lds_dwordx4 v[244:245], off
	v_lshl_add_u64 v[244:245], v[250:251], 0, s[66:67]
	s_mov_b32 m0, s37
	s_nop 0
	global_load_lds_dwordx4 v[244:245], off
	s_waitcnt vmcnt(8)
	s_waitcnt lgkmcnt(0)
	s_barrier
	s_setprio 1
	s_waitcnt lgkmcnt(0)
	v_mfma_f32_16x16x32_bf16 v[62:65], v[180:183], v[212:215], v[62:65]
	v_mfma_f32_16x16x32_bf16 v[58:61], v[188:191], v[212:215], v[58:61]
	v_mfma_f32_16x16x32_bf16 v[54:57], v[180:183], v[220:223], v[54:57]
	v_mfma_f32_16x16x32_bf16 v[50:53], v[188:191], v[220:223], v[50:53]
	v_mfma_f32_16x16x32_bf16 v[38:41], v[180:183], v[228:231], v[38:41]
	v_mfma_f32_16x16x32_bf16 v[34:37], v[188:191], v[228:231], v[34:37]
	v_mfma_f32_16x16x32_bf16 v[22:25], v[180:183], v[236:239], v[22:25]
	v_mfma_f32_16x16x32_bf16 v[18:21], v[188:191], v[236:239], v[18:21]
	v_mfma_f32_16x16x32_bf16 v[62:65], v[184:187], v[216:219], v[62:65]
	v_mfma_f32_16x16x32_bf16 v[58:61], v[192:195], v[216:219], v[58:61]
	v_mfma_f32_16x16x32_bf16 v[54:57], v[184:187], v[224:227], v[54:57]
	v_mfma_f32_16x16x32_bf16 v[50:53], v[192:195], v[224:227], v[50:53]
	v_mfma_f32_16x16x32_bf16 v[38:41], v[184:187], v[232:235], v[38:41]
	v_mfma_f32_16x16x32_bf16 v[34:37], v[192:195], v[232:235], v[34:37]
	v_mfma_f32_16x16x32_bf16 v[22:25], v[184:187], v[240:243], v[22:25]
	v_mfma_f32_16x16x32_bf16 v[18:21], v[192:195], v[240:243], v[18:21]
	s_setprio 0
	s_setprio 1
	v_mfma_f32_16x16x32_bf16 v[46:49], v[196:199], v[212:215], v[46:49]
	v_mfma_f32_16x16x32_bf16 v[42:45], v[204:207], v[212:215], v[42:45]
	v_mfma_f32_16x16x32_bf16 v[30:33], v[196:199], v[220:223], v[30:33]
	v_mfma_f32_16x16x32_bf16 v[26:29], v[204:207], v[220:223], v[26:29]
	v_mfma_f32_16x16x32_bf16 v[14:17], v[196:199], v[228:231], v[14:17]
	v_mfma_f32_16x16x32_bf16 v[10:13], v[204:207], v[228:231], v[10:13]
	v_mfma_f32_16x16x32_bf16 v[6:9], v[196:199], v[236:239], v[6:9]
	v_mfma_f32_16x16x32_bf16 v[2:5], v[204:207], v[236:239], v[2:5]
	v_mfma_f32_16x16x32_bf16 v[46:49], v[200:203], v[216:219], v[46:49]
	v_mfma_f32_16x16x32_bf16 v[42:45], v[208:211], v[216:219], v[42:45]
	v_mfma_f32_16x16x32_bf16 v[30:33], v[200:203], v[224:227], v[30:33]
	v_mfma_f32_16x16x32_bf16 v[26:29], v[208:211], v[224:227], v[26:29]
	v_mfma_f32_16x16x32_bf16 v[14:17], v[200:203], v[232:235], v[14:17]
	s_setprio 2
	s_barrier
	v_mfma_f32_16x16x32_bf16 v[10:13], v[208:211], v[232:235], v[10:13]
	v_mfma_f32_16x16x32_bf16 v[6:9], v[200:203], v[240:243], v[6:9]
	v_mfma_f32_16x16x32_bf16 v[2:5], v[208:211], v[240:243], v[2:5]
	s_setprio 0
	s_add_i32 s69, s69, 2
	s_add_u32 s46, s46, 0x100
	s_addc_u32 s47, s47, 0
	s_add_u32 s65, s65, 0x100
	s_addc_u32 s68, s68, 0
	s_cmp_gt_u32 s69, 13
	s_cbranch_scc0 .LBB0_371
	s_and_b64 vcc, exec, s[8:9]
	s_cbranch_vccz .LBB0_374
	s_barrier

.LBB0_385:
	s_add_u32 s50, s44, s90
	s_addc_u32 s51, s45, s91
	s_add_u32 s50, s50, 0x100
	s_addc_u32 s51, s51, 0
	s_add_u32 s69, s25, s90
	s_addc_u32 s70, s30, s91
	s_add_i32 s71, 0, 0x10000
	s_cmpk_eq_i32 s90, 0x700
	s_cselect_b32 s53, s13, s51
	s_cselect_b32 s52, s37, s50
	v_add_u32_e32 v159, s71, v149
	s_cselect_b32 s51, s47, s70
	s_cselect_b32 s50, s56, s69
	s_add_i32 s69, 0, 0x14000
	ds_read_b128 v[178:181], v159
	ds_read_b128 v[182:185], v159 offset:1024
	ds_read_b128 v[186:189], v159 offset:2048
	ds_read_b128 v[190:193], v159 offset:3072
	v_add_u32_e32 v159, s69, v149
	ds_read_b128 v[194:197], v159
	ds_read_b128 v[198:201], v159 offset:1024
	ds_read_b128 v[202:205], v159 offset:2048
	ds_read_b128 v[206:209], v159 offset:3072
	v_lshl_add_u64 v[160:161], v[154:155], 0, s[90:91]
	s_add_i32 m0, s38, 0xc000
	ds_read_b128 v[210:213], v158
	ds_read_b128 v[214:217], v158 offset:1024
	ds_read_b128 v[218:221], v158 offset:2048
	ds_read_b128 v[222:225], v158 offset:3072
	ds_read_b128 v[226:229], v158 offset:4096
	ds_read_b128 v[230:233], v158 offset:5120
	ds_read_b128 v[234:237], v158 offset:6144
	ds_read_b128 v[238:241], v158 offset:7168
	global_load_lds_dwordx4 v[160:161], off
	v_lshl_add_u64 v[160:161], v[156:157], 0, s[90:91]
	s_add_i32 m0, s38, 0xe000
	s_nop 0
	global_load_lds_dwordx4 v[160:161], off
	s_waitcnt vmcnt(8)
	s_waitcnt lgkmcnt(0)
	s_barrier
	s_setprio 1
	s_waitcnt lgkmcnt(0)
	v_mfma_f32_16x16x32_bf16 v[126:129], v[178:181], v[210:213], v[126:129]
	v_mfma_f32_16x16x32_bf16 v[122:125], v[186:189], v[210:213], v[122:125]
	v_mfma_f32_16x16x32_bf16 v[118:121], v[178:181], v[218:221], v[118:121]
	v_mfma_f32_16x16x32_bf16 v[114:117], v[186:189], v[218:221], v[114:117]
	v_mfma_f32_16x16x32_bf16 v[110:113], v[178:181], v[226:229], v[110:113]
	v_mfma_f32_16x16x32_bf16 v[106:109], v[186:189], v[226:229], v[106:109]
	v_mfma_f32_16x16x32_bf16 v[102:105], v[178:181], v[234:237], v[102:105]
	v_mfma_f32_16x16x32_bf16 v[98:101], v[186:189], v[234:237], v[98:101]
	v_mfma_f32_16x16x32_bf16 v[126:129], v[182:185], v[214:217], v[126:129]
	v_mfma_f32_16x16x32_bf16 v[122:125], v[190:193], v[214:217], v[122:125]
	v_mfma_f32_16x16x32_bf16 v[118:121], v[182:185], v[222:225], v[118:121]
	v_mfma_f32_16x16x32_bf16 v[114:117], v[190:193], v[222:225], v[114:117]
	v_mfma_f32_16x16x32_bf16 v[110:113], v[182:185], v[230:233], v[110:113]
	v_mfma_f32_16x16x32_bf16 v[106:109], v[190:193], v[230:233], v[106:109]
	v_mfma_f32_16x16x32_bf16 v[102:105], v[182:185], v[238:241], v[102:105]
	v_mfma_f32_16x16x32_bf16 v[98:101], v[190:193], v[238:241], v[98:101]
	s_setprio 0
	s_setprio 1
	v_mfma_f32_16x16x32_bf16 v[82:85], v[194:197], v[210:213], v[82:85]
	v_mfma_f32_16x16x32_bf16 v[74:77], v[202:205], v[210:213], v[74:77]
	v_mfma_f32_16x16x32_bf16 v[66:69], v[194:197], v[218:221], v[66:69]
	v_mfma_f32_16x16x32_bf16 v[58:61], v[202:205], v[218:221], v[58:61]
	v_mfma_f32_16x16x32_bf16 v[54:57], v[194:197], v[226:229], v[54:57]
	v_mfma_f32_16x16x32_bf16 v[46:49], v[202:205], v[226:229], v[46:49]
	v_mfma_f32_16x16x32_bf16 v[38:41], v[194:197], v[234:237], v[38:41]
	v_mfma_f32_16x16x32_bf16 v[34:37], v[202:205], v[234:237], v[34:37]
	v_mfma_f32_16x16x32_bf16 v[82:85], v[198:201], v[214:217], v[82:85]
	v_mfma_f32_16x16x32_bf16 v[74:77], v[206:209], v[214:217], v[74:77]
	v_mfma_f32_16x16x32_bf16 v[66:69], v[198:201], v[222:225], v[66:69]
	v_mfma_f32_16x16x32_bf16 v[58:61], v[206:209], v[222:225], v[58:61]
	v_mfma_f32_16x16x32_bf16 v[54:57], v[198:201], v[230:233], v[54:57]
	s_setprio 2
	s_barrier
	v_mfma_f32_16x16x32_bf16 v[46:49], v[206:209], v[230:233], v[46:49]
	v_mfma_f32_16x16x32_bf16 v[38:41], v[198:201], v[238:241], v[38:41]
	v_mfma_f32_16x16x32_bf16 v[34:37], v[206:209], v[238:241], v[34:37]
	s_setprio 0
	s_add_i32 s70, s71, s35
	v_lshl_add_u64 v[160:161], s[50:51], 0, v[134:135]
	s_mov_b32 m0, s70
	ds_read_b128 v[210:213], v158 offset:16384
	ds_read_b128 v[214:217], v158 offset:17408
	ds_read_b128 v[218:221], v158 offset:18432
	ds_read_b128 v[222:225], v158 offset:19456
	ds_read_b128 v[226:229], v158 offset:20480
	ds_read_b128 v[230:233], v158 offset:21504
	ds_read_b128 v[234:237], v158 offset:22528
	ds_read_b128 v[238:241], v158 offset:23552
	global_load_lds_dwordx4 v[160:161], off
	s_add_i32 m0, s70, 0x2000
	s_add_u32 s70, s50, 0x40000
	v_lshl_add_u64 v[164:165], s[50:51], 0, v[146:147]
	s_addc_u32 s71, s51, 0
	s_add_i32 s69, s69, s35
	global_load_lds_dwordx4 v[164:165], off
	v_lshl_add_u64 v[242:243], s[70:71], 0, v[134:135]
	s_mov_b32 m0, s69
	v_lshl_add_u64 v[244:245], s[52:53], 0, v[144:145]
	global_load_lds_dwordx4 v[242:243], off
	v_lshl_add_u64 v[242:243], s[70:71], 0, v[146:147]
	s_add_i32 m0, s69, 0x2000
	s_nop 0
	global_load_lds_dwordx4 v[242:243], off
	v_lshl_add_u64 v[242:243], s[52:53], 0, v[132:133]
	s_mov_b32 m0, s38
	s_nop 0
	global_load_lds_dwordx4 v[242:243], off
	s_mov_b32 m0, s60
	s_nop 0
	global_load_lds_dwordx4 v[244:245], off
	s_waitcnt vmcnt(8)
	s_waitcnt lgkmcnt(0)
	s_barrier
	s_setprio 1
	s_waitcnt lgkmcnt(0)
	v_mfma_f32_16x16x32_bf16 v[94:97], v[178:181], v[210:213], v[94:97]
	v_mfma_f32_16x16x32_bf16 v[90:93], v[186:189], v[210:213], v[90:93]
	v_mfma_f32_16x16x32_bf16 v[86:89], v[178:181], v[218:221], v[86:89]
	v_mfma_f32_16x16x32_bf16 v[78:81], v[186:189], v[218:221], v[78:81]
	v_mfma_f32_16x16x32_bf16 v[70:73], v[178:181], v[226:229], v[70:73]
	v_mfma_f32_16x16x32_bf16 v[62:65], v[186:189], v[226:229], v[62:65]
	v_mfma_f32_16x16x32_bf16 v[50:53], v[178:181], v[234:237], v[50:53]
	v_mfma_f32_16x16x32_bf16 v[42:45], v[186:189], v[234:237], v[42:45]
	v_mfma_f32_16x16x32_bf16 v[94:97], v[182:185], v[214:217], v[94:97]
	v_mfma_f32_16x16x32_bf16 v[90:93], v[190:193], v[214:217], v[90:93]
	v_mfma_f32_16x16x32_bf16 v[86:89], v[182:185], v[222:225], v[86:89]
	v_mfma_f32_16x16x32_bf16 v[78:81], v[190:193], v[222:225], v[78:81]
	v_mfma_f32_16x16x32_bf16 v[70:73], v[182:185], v[230:233], v[70:73]
	v_mfma_f32_16x16x32_bf16 v[62:65], v[190:193], v[230:233], v[62:65]
	v_mfma_f32_16x16x32_bf16 v[50:53], v[182:185], v[238:241], v[50:53]
	v_mfma_f32_16x16x32_bf16 v[42:45], v[190:193], v[238:241], v[42:45]
	s_setprio 0
	s_setprio 1
	v_mfma_f32_16x16x32_bf16 v[30:33], v[194:197], v[210:213], v[30:33]
	v_mfma_f32_16x16x32_bf16 v[26:29], v[202:205], v[210:213], v[26:29]
	v_mfma_f32_16x16x32_bf16 v[22:25], v[194:197], v[218:221], v[22:25]
	v_mfma_f32_16x16x32_bf16 v[18:21], v[202:205], v[218:221], v[18:21]
	v_mfma_f32_16x16x32_bf16 v[14:17], v[194:197], v[226:229], v[14:17]
	v_mfma_f32_16x16x32_bf16 v[10:13], v[202:205], v[226:229], v[10:13]
	v_mfma_f32_16x16x32_bf16 v[6:9], v[194:197], v[234:237], v[6:9]
	v_mfma_f32_16x16x32_bf16 v[2:5], v[202:205], v[234:237], v[2:5]
	v_mfma_f32_16x16x32_bf16 v[30:33], v[198:201], v[214:217], v[30:33]
	v_mfma_f32_16x16x32_bf16 v[26:29], v[206:209], v[214:217], v[26:29]
	v_mfma_f32_16x16x32_bf16 v[22:25], v[198:201], v[222:225], v[22:25]
	v_mfma_f32_16x16x32_bf16 v[18:21], v[206:209], v[222:225], v[18:21]
	v_mfma_f32_16x16x32_bf16 v[14:17], v[198:201], v[230:233], v[14:17]
	s_setprio 2
	s_barrier
	v_mfma_f32_16x16x32_bf16 v[10:13], v[206:209], v[230:233], v[10:13]
	v_mfma_f32_16x16x32_bf16 v[6:9], v[198:201], v[238:241], v[6:9]
	v_mfma_f32_16x16x32_bf16 v[2:5], v[206:209], v[238:241], v[2:5]
	s_setprio 0
	s_add_i32 s69, 0, 0x18000
	v_add_u32_e32 v159, s69, v149
	s_add_i32 s70, 0, 0x1c000
	ds_read_b128 v[178:181], v159
	ds_read_b128 v[182:185], v159 offset:1024
	ds_read_b128 v[186:189], v159 offset:2048
	ds_read_b128 v[190:193], v159 offset:3072
	v_add_u32_e32 v159, s70, v149
	ds_read_b128 v[194:197], v159
	ds_read_b128 v[198:201], v159 offset:1024
	ds_read_b128 v[202:205], v159 offset:2048
	ds_read_b128 v[206:209], v159 offset:3072
	s_add_u32 s52, s52, 0x40000
	s_addc_u32 s53, s53, 0
	s_mov_b32 m0, s64
	v_lshl_add_u64 v[246:247], s[52:53], 0, v[132:133]
	ds_read_b128 v[210:213], v158 offset:32768
	ds_read_b128 v[214:217], v158 offset:33792
	ds_read_b128 v[218:221], v158 offset:34816
	ds_read_b128 v[222:225], v158 offset:35840
	ds_read_b128 v[226:229], v158 offset:36864
	ds_read_b128 v[230:233], v158 offset:37888
	ds_read_b128 v[234:237], v158 offset:38912
	ds_read_b128 v[238:241], v158 offset:39936
	global_load_lds_dwordx4 v[246:247], off
	v_lshl_add_u64 v[246:247], s[52:53], 0, v[144:145]
	s_mov_b32 m0, s65
	s_nop 0
	global_load_lds_dwordx4 v[246:247], off
	s_waitcnt vmcnt(8)
	s_waitcnt lgkmcnt(0)
	s_barrier
	s_setprio 1
	s_waitcnt lgkmcnt(0)
	v_mfma_f32_16x16x32_bf16 v[126:129], v[178:181], v[210:213], v[126:129]
	v_mfma_f32_16x16x32_bf16 v[122:125], v[186:189], v[210:213], v[122:125]
	v_mfma_f32_16x16x32_bf16 v[118:121], v[178:181], v[218:221], v[118:121]
	v_mfma_f32_16x16x32_bf16 v[114:117], v[186:189], v[218:221], v[114:117]
	v_mfma_f32_16x16x32_bf16 v[110:113], v[178:181], v[226:229], v[110:113]
	v_mfma_f32_16x16x32_bf16 v[106:109], v[186:189], v[226:229], v[106:109]
	v_mfma_f32_16x16x32_bf16 v[102:105], v[178:181], v[234:237], v[102:105]
	v_mfma_f32_16x16x32_bf16 v[98:101], v[186:189], v[234:237], v[98:101]
	v_mfma_f32_16x16x32_bf16 v[126:129], v[182:185], v[214:217], v[126:129]
	v_mfma_f32_16x16x32_bf16 v[122:125], v[190:193], v[214:217], v[122:125]
	v_mfma_f32_16x16x32_bf16 v[118:121], v[182:185], v[222:225], v[118:121]
	v_mfma_f32_16x16x32_bf16 v[114:117], v[190:193], v[222:225], v[114:117]
	v_mfma_f32_16x16x32_bf16 v[110:113], v[182:185], v[230:233], v[110:113]
	v_mfma_f32_16x16x32_bf16 v[106:109], v[190:193], v[230:233], v[106:109]
	v_mfma_f32_16x16x32_bf16 v[102:105], v[182:185], v[238:241], v[102:105]
	v_mfma_f32_16x16x32_bf16 v[98:101], v[190:193], v[238:241], v[98:101]
	s_setprio 0
	s_setprio 1
	v_mfma_f32_16x16x32_bf16 v[82:85], v[194:197], v[210:213], v[82:85]
	v_mfma_f32_16x16x32_bf16 v[74:77], v[202:205], v[210:213], v[74:77]
	v_mfma_f32_16x16x32_bf16 v[66:69], v[194:197], v[218:221], v[66:69]
	v_mfma_f32_16x16x32_bf16 v[58:61], v[202:205], v[218:221], v[58:61]
	v_mfma_f32_16x16x32_bf16 v[54:57], v[194:197], v[226:229], v[54:57]
	v_mfma_f32_16x16x32_bf16 v[46:49], v[202:205], v[226:229], v[46:49]
	v_mfma_f32_16x16x32_bf16 v[38:41], v[194:197], v[234:237], v[38:41]
	v_mfma_f32_16x16x32_bf16 v[34:37], v[202:205], v[234:237], v[34:37]
	v_mfma_f32_16x16x32_bf16 v[82:85], v[198:201], v[214:217], v[82:85]
	v_mfma_f32_16x16x32_bf16 v[74:77], v[206:209], v[214:217], v[74:77]
	v_mfma_f32_16x16x32_bf16 v[66:69], v[198:201], v[222:225], v[66:69]
	v_mfma_f32_16x16x32_bf16 v[58:61], v[206:209], v[222:225], v[58:61]
	v_mfma_f32_16x16x32_bf16 v[54:57], v[198:201], v[230:233], v[54:57]
	s_setprio 2
	s_barrier
	v_mfma_f32_16x16x32_bf16 v[46:49], v[206:209], v[230:233], v[46:49]
	v_mfma_f32_16x16x32_bf16 v[38:41], v[198:201], v[238:241], v[38:41]
	v_mfma_f32_16x16x32_bf16 v[34:37], v[206:209], v[238:241], v[34:37]
	s_setprio 0
	s_add_i32 s52, s69, s35
	v_lshl_add_u64 v[160:161], v[160:161], 0, s[66:67]
	s_mov_b32 m0, s52
	ds_read_b128 v[210:213], v158 offset:49152
	ds_read_b128 v[214:217], v158 offset:50176
	ds_read_b128 v[218:221], v158 offset:51200
	ds_read_b128 v[222:225], v158 offset:52224
	ds_read_b128 v[226:229], v158 offset:53248
	ds_read_b128 v[230:233], v158 offset:54272
	ds_read_b128 v[234:237], v158 offset:55296
	ds_read_b128 v[238:241], v158 offset:56320
	global_load_lds_dwordx4 v[160:161], off
	s_add_i32 m0, s52, 0x2000
	s_add_u32 s50, s50, 0x40080
	v_lshl_add_u64 v[160:161], v[164:165], 0, s[66:67]
	s_addc_u32 s51, s51, 0
	s_add_i32 s52, s70, s35
	global_load_lds_dwordx4 v[160:161], off
	v_lshl_add_u64 v[160:161], s[50:51], 0, v[134:135]
	s_mov_b32 m0, s52
	s_nop 0
	global_load_lds_dwordx4 v[160:161], off
	v_lshl_add_u64 v[160:161], s[50:51], 0, v[146:147]
	s_add_i32 m0, s52, 0x2000
	s_nop 0
	global_load_lds_dwordx4 v[160:161], off
	v_lshl_add_u64 v[160:161], v[242:243], 0, s[66:67]
	s_mov_b32 m0, s19
	s_nop 0
	global_load_lds_dwordx4 v[160:161], off
	v_lshl_add_u64 v[160:161], v[244:245], 0, s[66:67]
	s_mov_b32 m0, s62
	s_nop 0
	global_load_lds_dwordx4 v[160:161], off
	s_waitcnt vmcnt(8)
	s_waitcnt lgkmcnt(0)
	s_barrier
	s_setprio 1
	s_waitcnt lgkmcnt(0)
	v_mfma_f32_16x16x32_bf16 v[94:97], v[178:181], v[210:213], v[94:97]
	v_mfma_f32_16x16x32_bf16 v[90:93], v[186:189], v[210:213], v[90:93]
	v_mfma_f32_16x16x32_bf16 v[86:89], v[178:181], v[218:221], v[86:89]
	v_mfma_f32_16x16x32_bf16 v[78:81], v[186:189], v[218:221], v[78:81]
	v_mfma_f32_16x16x32_bf16 v[70:73], v[178:181], v[226:229], v[70:73]
	v_mfma_f32_16x16x32_bf16 v[62:65], v[186:189], v[226:229], v[62:65]
	v_mfma_f32_16x16x32_bf16 v[50:53], v[178:181], v[234:237], v[50:53]
	v_mfma_f32_16x16x32_bf16 v[42:45], v[186:189], v[234:237], v[42:45]
	v_mfma_f32_16x16x32_bf16 v[94:97], v[182:185], v[214:217], v[94:97]
	v_mfma_f32_16x16x32_bf16 v[90:93], v[190:193], v[214:217], v[90:93]
	v_mfma_f32_16x16x32_bf16 v[86:89], v[182:185], v[222:225], v[86:89]
	v_mfma_f32_16x16x32_bf16 v[78:81], v[190:193], v[222:225], v[78:81]
	v_mfma_f32_16x16x32_bf16 v[70:73], v[182:185], v[230:233], v[70:73]
	v_mfma_f32_16x16x32_bf16 v[62:65], v[190:193], v[230:233], v[62:65]
	v_mfma_f32_16x16x32_bf16 v[50:53], v[182:185], v[238:241], v[50:53]
	v_mfma_f32_16x16x32_bf16 v[42:45], v[190:193], v[238:241], v[42:45]
	s_setprio 0
	s_setprio 1
	v_mfma_f32_16x16x32_bf16 v[30:33], v[194:197], v[210:213], v[30:33]
	v_mfma_f32_16x16x32_bf16 v[26:29], v[202:205], v[210:213], v[26:29]
	v_mfma_f32_16x16x32_bf16 v[22:25], v[194:197], v[218:221], v[22:25]
	v_mfma_f32_16x16x32_bf16 v[18:21], v[202:205], v[218:221], v[18:21]
	v_mfma_f32_16x16x32_bf16 v[14:17], v[194:197], v[226:229], v[14:17]
	v_mfma_f32_16x16x32_bf16 v[10:13], v[202:205], v[226:229], v[10:13]
	v_mfma_f32_16x16x32_bf16 v[6:9], v[194:197], v[234:237], v[6:9]
	v_mfma_f32_16x16x32_bf16 v[2:5], v[202:205], v[234:237], v[2:5]
	v_mfma_f32_16x16x32_bf16 v[30:33], v[198:201], v[214:217], v[30:33]
	v_mfma_f32_16x16x32_bf16 v[26:29], v[206:209], v[214:217], v[26:29]
	v_mfma_f32_16x16x32_bf16 v[22:25], v[198:201], v[222:225], v[22:25]
	v_mfma_f32_16x16x32_bf16 v[18:21], v[206:209], v[222:225], v[18:21]
	v_mfma_f32_16x16x32_bf16 v[14:17], v[198:201], v[230:233], v[14:17]
	s_setprio 2
	s_barrier
	v_mfma_f32_16x16x32_bf16 v[10:13], v[206:209], v[230:233], v[10:13]
	v_mfma_f32_16x16x32_bf16 v[6:9], v[198:201], v[238:241], v[6:9]
	v_mfma_f32_16x16x32_bf16 v[2:5], v[206:209], v[238:241], v[2:5]
	s_setprio 0
	s_add_i32 s68, s68, 2
	s_add_u32 s90, s90, 0x100
	s_addc_u32 s91, s91, 0
	s_cmp_gt_u32 s68, 13
	s_cbranch_scc0 .LBB0_385
	s_and_b64 vcc, exec, s[10:11]
	s_cbranch_vccz .LBB0_388
	s_barrier

.Lpz_ain:
	s_add_u32 s22, s12, 0xfffc0080
	s_addc_u32 s23, s13, -1
	s_add_i32 s53, 0, 0x10000
	s_cmp_eq_u32 s52, 12
	s_cselect_b32 s27, s25, s23
	s_cselect_b32 s26, s30, s22
	v_add_u32_e32 v134, s53, v178
	s_cselect_b32 s23, s37, s51
	s_cselect_b32 s22, s47, s50
	s_add_i32 s56, 0, 0x14000
	ds_read_b128 v[130:133], v134
	ds_read_b128 v[182:185], v134 offset:1024
	ds_read_b128 v[186:189], v134 offset:2048
	ds_read_b128 v[190:193], v134 offset:3072
	v_add_u32_e32 v134, s56, v178
	ds_read_b128 v[194:197], v134
	ds_read_b128 v[198:201], v134 offset:1024
	ds_read_b128 v[202:205], v134 offset:2048
	ds_read_b128 v[206:209], v134 offset:3072
	v_lshl_add_u64 v[160:161], s[12:13], 0, v[156:157]
	s_add_i32 m0, s31, 0xc000
	ds_read_b128 v[210:213], v180
	ds_read_b128 v[214:217], v180 offset:1024
	ds_read_b128 v[218:221], v180 offset:2048
	ds_read_b128 v[222:225], v180 offset:3072
	ds_read_b128 v[226:229], v180 offset:4096
	ds_read_b128 v[230:233], v180 offset:5120
	ds_read_b128 v[234:237], v180 offset:6144
	ds_read_b128 v[238:241], v180 offset:7168
	global_load_lds_dwordx4 v[160:161], off
	v_lshl_add_u64 v[160:161], s[12:13], 0, v[158:159]
	s_add_i32 m0, s31, 0xe000
	s_nop 0
	global_load_lds_dwordx4 v[160:161], off
	s_waitcnt vmcnt(16)
	s_waitcnt lgkmcnt(0)
	s_barrier
	s_setprio 1
	s_waitcnt lgkmcnt(0)
	v_mfma_f32_16x16x32_bf16 v[126:129], v[130:133], v[210:213], 0
	v_mfma_f32_16x16x32_bf16 v[122:125], v[186:189], v[210:213], 0
	v_mfma_f32_16x16x32_bf16 v[110:113], v[130:133], v[218:221], 0
	v_mfma_f32_16x16x32_bf16 v[106:109], v[186:189], v[218:221], 0
	v_mfma_f32_16x16x32_bf16 v[98:101], v[130:133], v[226:229], 0
	v_mfma_f32_16x16x32_bf16 v[90:93], v[186:189], v[226:229], 0
	v_mfma_f32_16x16x32_bf16 v[82:85], v[130:133], v[234:237], 0
	v_mfma_f32_16x16x32_bf16 v[74:77], v[186:189], v[234:237], 0
	v_mfma_f32_16x16x32_bf16 v[126:129], v[182:185], v[214:217], v[126:129]
	v_mfma_f32_16x16x32_bf16 v[122:125], v[190:193], v[214:217], v[122:125]
	v_mfma_f32_16x16x32_bf16 v[110:113], v[182:185], v[222:225], v[110:113]
	v_mfma_f32_16x16x32_bf16 v[106:109], v[190:193], v[222:225], v[106:109]
	v_mfma_f32_16x16x32_bf16 v[98:101], v[182:185], v[230:233], v[98:101]
	v_mfma_f32_16x16x32_bf16 v[90:93], v[190:193], v[230:233], v[90:93]
	v_mfma_f32_16x16x32_bf16 v[82:85], v[182:185], v[238:241], v[82:85]
	v_mfma_f32_16x16x32_bf16 v[74:77], v[190:193], v[238:241], v[74:77]
	s_setprio 0
	s_setprio 1
	v_mfma_f32_16x16x32_bf16 v[118:121], v[194:197], v[210:213], 0
	v_mfma_f32_16x16x32_bf16 v[114:117], v[202:205], v[210:213], 0
	v_mfma_f32_16x16x32_bf16 v[102:105], v[194:197], v[218:221], 0
	v_mfma_f32_16x16x32_bf16 v[94:97], v[202:205], v[218:221], 0
	v_mfma_f32_16x16x32_bf16 v[86:89], v[194:197], v[226:229], 0
	v_mfma_f32_16x16x32_bf16 v[78:81], v[202:205], v[226:229], 0
	v_mfma_f32_16x16x32_bf16 v[70:73], v[194:197], v[234:237], 0
	v_mfma_f32_16x16x32_bf16 v[66:69], v[202:205], v[234:237], 0
	v_mfma_f32_16x16x32_bf16 v[118:121], v[198:201], v[214:217], v[118:121]
	v_mfma_f32_16x16x32_bf16 v[114:117], v[206:209], v[214:217], v[114:117]
	v_mfma_f32_16x16x32_bf16 v[102:105], v[198:201], v[222:225], v[102:105]
	v_mfma_f32_16x16x32_bf16 v[94:97], v[206:209], v[222:225], v[94:97]
	v_mfma_f32_16x16x32_bf16 v[86:89], v[198:201], v[230:233], v[86:89]
	s_setprio 2
	s_barrier
	v_mfma_f32_16x16x32_bf16 v[78:81], v[206:209], v[230:233], v[78:81]
	v_mfma_f32_16x16x32_bf16 v[70:73], v[198:201], v[238:241], v[70:73]
	v_mfma_f32_16x16x32_bf16 v[66:69], v[206:209], v[238:241], v[66:69]
	s_setprio 0
	s_add_i32 s53, s53, s20
	v_lshl_add_u64 v[160:161], s[22:23], 0, v[148:149]
	s_mov_b32 m0, s53
	ds_read_b128 v[210:213], v180 offset:16384
	ds_read_b128 v[214:217], v180 offset:17408
	ds_read_b128 v[218:221], v180 offset:18432
	ds_read_b128 v[222:225], v180 offset:19456
	ds_read_b128 v[226:229], v180 offset:20480
	ds_read_b128 v[230:233], v180 offset:21504
	ds_read_b128 v[234:237], v180 offset:22528
	ds_read_b128 v[238:241], v180 offset:23552
	global_load_lds_dwordx4 v[160:161], off
	s_add_i32 m0, s53, 0x2000
	s_add_u32 s64, s22, 0x40000
	v_lshl_add_u64 v[164:165], s[22:23], 0, v[144:145]
	s_addc_u32 s65, s23, 0
	s_add_i32 s53, s56, s20
	global_load_lds_dwordx4 v[164:165], off
	v_lshl_add_u64 v[242:243], s[64:65], 0, v[148:149]
	s_mov_b32 m0, s53
	v_lshl_add_u64 v[244:245], s[26:27], 0, v[146:147]
	global_load_lds_dwordx4 v[242:243], off
	v_lshl_add_u64 v[242:243], s[64:65], 0, v[144:145]
	s_add_i32 m0, s53, 0x2000
	s_nop 0
	global_load_lds_dwordx4 v[242:243], off
	v_lshl_add_u64 v[242:243], s[26:27], 0, v[150:151]
	s_mov_b32 m0, s31
	s_nop 0
	global_load_lds_dwordx4 v[242:243], off
	s_mov_b32 m0, s35
	s_nop 0
	global_load_lds_dwordx4 v[244:245], off
	s_waitcnt vmcnt(16)
	s_waitcnt lgkmcnt(0)
	s_barrier
	s_setprio 1
	s_waitcnt lgkmcnt(0)
	v_mfma_f32_16x16x32_bf16 v[62:65], v[130:133], v[210:213], 0
	v_mfma_f32_16x16x32_bf16 v[58:61], v[186:189], v[210:213], 0
	v_mfma_f32_16x16x32_bf16 v[50:53], v[130:133], v[218:221], 0
	v_mfma_f32_16x16x32_bf16 v[42:45], v[186:189], v[218:221], 0
	v_mfma_f32_16x16x32_bf16 v[34:37], v[130:133], v[226:229], 0
	v_mfma_f32_16x16x32_bf16 v[26:29], v[186:189], v[226:229], 0
	v_mfma_f32_16x16x32_bf16 v[18:21], v[130:133], v[234:237], 0
	v_mfma_f32_16x16x32_bf16 v[10:13], v[186:189], v[234:237], 0
	v_mfma_f32_16x16x32_bf16 v[62:65], v[182:185], v[214:217], v[62:65]
	v_mfma_f32_16x16x32_bf16 v[58:61], v[190:193], v[214:217], v[58:61]
	v_mfma_f32_16x16x32_bf16 v[50:53], v[182:185], v[222:225], v[50:53]
	v_mfma_f32_16x16x32_bf16 v[42:45], v[190:193], v[222:225], v[42:45]
	v_mfma_f32_16x16x32_bf16 v[34:37], v[182:185], v[230:233], v[34:37]
	v_mfma_f32_16x16x32_bf16 v[26:29], v[190:193], v[230:233], v[26:29]
	v_mfma_f32_16x16x32_bf16 v[18:21], v[182:185], v[238:241], v[18:21]
	v_mfma_f32_16x16x32_bf16 v[10:13], v[190:193], v[238:241], v[10:13]
	s_setprio 0
	s_setprio 1
	v_mfma_f32_16x16x32_bf16 v[54:57], v[194:197], v[210:213], 0
	v_mfma_f32_16x16x32_bf16 v[46:49], v[202:205], v[210:213], 0
	v_mfma_f32_16x16x32_bf16 v[38:41], v[194:197], v[218:221], 0
	v_mfma_f32_16x16x32_bf16 v[30:33], v[202:205], v[218:221], 0
	v_mfma_f32_16x16x32_bf16 v[22:25], v[194:197], v[226:229], 0
	v_mfma_f32_16x16x32_bf16 v[14:17], v[202:205], v[226:229], 0
	v_mfma_f32_16x16x32_bf16 v[6:9], v[194:197], v[234:237], 0
	v_mfma_f32_16x16x32_bf16 v[2:5], v[202:205], v[234:237], 0
	v_mfma_f32_16x16x32_bf16 v[54:57], v[198:201], v[214:217], v[54:57]
	v_mfma_f32_16x16x32_bf16 v[46:49], v[206:209], v[214:217], v[46:49]
	v_mfma_f32_16x16x32_bf16 v[38:41], v[198:201], v[222:225], v[38:41]
	v_mfma_f32_16x16x32_bf16 v[30:33], v[206:209], v[222:225], v[30:33]
	v_mfma_f32_16x16x32_bf16 v[22:25], v[198:201], v[230:233], v[22:25]
	s_setprio 2
	s_barrier
	v_mfma_f32_16x16x32_bf16 v[14:17], v[206:209], v[230:233], v[14:17]
	v_mfma_f32_16x16x32_bf16 v[6:9], v[198:201], v[238:241], v[6:9]
	v_mfma_f32_16x16x32_bf16 v[2:5], v[206:209], v[238:241], v[2:5]
	s_setprio 0
	s_add_i32 s53, 0, 0x18000
	v_add_u32_e32 v134, s53, v178
	s_add_i32 s56, 0, 0x1c000
	ds_read_b128 v[130:133], v134
	ds_read_b128 v[182:185], v134 offset:1024
	ds_read_b128 v[186:189], v134 offset:2048
	ds_read_b128 v[190:193], v134 offset:3072
	v_add_u32_e32 v134, s56, v178
	ds_read_b128 v[194:197], v134
	ds_read_b128 v[198:201], v134 offset:1024
	ds_read_b128 v[202:205], v134 offset:2048
	ds_read_b128 v[206:209], v134 offset:3072
	s_add_u32 s26, s26, 0x40000
	s_addc_u32 s27, s27, 0
	s_mov_b32 m0, s38
	v_lshl_add_u64 v[246:247], s[26:27], 0, v[150:151]
	ds_read_b128 v[210:213], v180 offset:32768
	ds_read_b128 v[214:217], v180 offset:33792
	ds_read_b128 v[218:221], v180 offset:34816
	ds_read_b128 v[222:225], v180 offset:35840
	ds_read_b128 v[226:229], v180 offset:36864
	ds_read_b128 v[230:233], v180 offset:37888
	ds_read_b128 v[234:237], v180 offset:38912
	ds_read_b128 v[238:241], v180 offset:39936
	global_load_lds_dwordx4 v[246:247], off
	v_lshl_add_u64 v[246:247], s[26:27], 0, v[146:147]
	s_mov_b32 m0, s40
	s_nop 0
	global_load_lds_dwordx4 v[246:247], off
	s_waitcnt vmcnt(8)
	s_waitcnt lgkmcnt(0)
	s_barrier
	s_setprio 1
	s_waitcnt lgkmcnt(0)
	v_mfma_f32_16x16x32_bf16 v[126:129], v[130:133], v[210:213], v[126:129]
	v_mfma_f32_16x16x32_bf16 v[122:125], v[186:189], v[210:213], v[122:125]
	v_mfma_f32_16x16x32_bf16 v[110:113], v[130:133], v[218:221], v[110:113]
	v_mfma_f32_16x16x32_bf16 v[106:109], v[186:189], v[218:221], v[106:109]
	v_mfma_f32_16x16x32_bf16 v[98:101], v[130:133], v[226:229], v[98:101]
	v_mfma_f32_16x16x32_bf16 v[90:93], v[186:189], v[226:229], v[90:93]
	v_mfma_f32_16x16x32_bf16 v[82:85], v[130:133], v[234:237], v[82:85]
	v_mfma_f32_16x16x32_bf16 v[74:77], v[186:189], v[234:237], v[74:77]
	v_mfma_f32_16x16x32_bf16 v[126:129], v[182:185], v[214:217], v[126:129]
	v_mfma_f32_16x16x32_bf16 v[122:125], v[190:193], v[214:217], v[122:125]
	v_mfma_f32_16x16x32_bf16 v[110:113], v[182:185], v[222:225], v[110:113]
	v_mfma_f32_16x16x32_bf16 v[106:109], v[190:193], v[222:225], v[106:109]
	v_mfma_f32_16x16x32_bf16 v[98:101], v[182:185], v[230:233], v[98:101]
	v_mfma_f32_16x16x32_bf16 v[90:93], v[190:193], v[230:233], v[90:93]
	v_mfma_f32_16x16x32_bf16 v[82:85], v[182:185], v[238:241], v[82:85]
	v_mfma_f32_16x16x32_bf16 v[74:77], v[190:193], v[238:241], v[74:77]
	s_setprio 0
	s_setprio 1
	v_mfma_f32_16x16x32_bf16 v[118:121], v[194:197], v[210:213], v[118:121]
	v_mfma_f32_16x16x32_bf16 v[114:117], v[202:205], v[210:213], v[114:117]
	v_mfma_f32_16x16x32_bf16 v[102:105], v[194:197], v[218:221], v[102:105]
	v_mfma_f32_16x16x32_bf16 v[94:97], v[202:205], v[218:221], v[94:97]
	v_mfma_f32_16x16x32_bf16 v[86:89], v[194:197], v[226:229], v[86:89]
	v_mfma_f32_16x16x32_bf16 v[78:81], v[202:205], v[226:229], v[78:81]
	v_mfma_f32_16x16x32_bf16 v[70:73], v[194:197], v[234:237], v[70:73]
	v_mfma_f32_16x16x32_bf16 v[66:69], v[202:205], v[234:237], v[66:69]
	v_mfma_f32_16x16x32_bf16 v[118:121], v[198:201], v[214:217], v[118:121]
	v_mfma_f32_16x16x32_bf16 v[114:117], v[206:209], v[214:217], v[114:117]
	v_mfma_f32_16x16x32_bf16 v[102:105], v[198:201], v[222:225], v[102:105]
	v_mfma_f32_16x16x32_bf16 v[94:97], v[206:209], v[222:225], v[94:97]
	v_mfma_f32_16x16x32_bf16 v[86:89], v[198:201], v[230:233], v[86:89]
	s_setprio 2
	s_barrier
	v_mfma_f32_16x16x32_bf16 v[78:81], v[206:209], v[230:233], v[78:81]
	v_mfma_f32_16x16x32_bf16 v[70:73], v[198:201], v[238:241], v[70:73]
	v_mfma_f32_16x16x32_bf16 v[66:69], v[206:209], v[238:241], v[66:69]
	s_setprio 0
	s_add_i32 s26, s53, s20
	v_lshl_add_u64 v[160:161], v[160:161], 0, s[66:67]
	s_mov_b32 m0, s26
	ds_read_b128 v[210:213], v180 offset:49152
	ds_read_b128 v[214:217], v180 offset:50176
	ds_read_b128 v[218:221], v180 offset:51200
	ds_read_b128 v[222:225], v180 offset:52224
	ds_read_b128 v[226:229], v180 offset:53248
	ds_read_b128 v[230:233], v180 offset:54272
	ds_read_b128 v[234:237], v180 offset:55296
	ds_read_b128 v[238:241], v180 offset:56320
	global_load_lds_dwordx4 v[160:161], off
	s_add_i32 m0, s26, 0x2000
	s_add_u32 s22, s22, 0x40080
	v_lshl_add_u64 v[160:161], v[164:165], 0, s[66:67]
	s_addc_u32 s23, s23, 0
	s_add_i32 s26, s56, s20
	global_load_lds_dwordx4 v[160:161], off
	v_lshl_add_u64 v[160:161], s[22:23], 0, v[148:149]
	s_mov_b32 m0, s26
	s_nop 0
	global_load_lds_dwordx4 v[160:161], off
	v_lshl_add_u64 v[160:161], s[22:23], 0, v[144:145]
	s_add_i32 m0, s26, 0x2000
	s_nop 0
	global_load_lds_dwordx4 v[160:161], off
	v_lshl_add_u64 v[160:161], v[242:243], 0, s[66:67]
	s_mov_b32 m0, s41
	s_nop 0
	global_load_lds_dwordx4 v[160:161], off
	v_lshl_add_u64 v[160:161], v[244:245], 0, s[66:67]
	s_mov_b32 m0, s44
	s_nop 0
	global_load_lds_dwordx4 v[160:161], off
	s_waitcnt vmcnt(8)
	s_waitcnt lgkmcnt(0)
	s_barrier
	s_setprio 1
	s_waitcnt lgkmcnt(0)
	v_mfma_f32_16x16x32_bf16 v[62:65], v[130:133], v[210:213], v[62:65]
	v_mfma_f32_16x16x32_bf16 v[58:61], v[186:189], v[210:213], v[58:61]
	v_mfma_f32_16x16x32_bf16 v[50:53], v[130:133], v[218:221], v[50:53]
	v_mfma_f32_16x16x32_bf16 v[42:45], v[186:189], v[218:221], v[42:45]
	v_mfma_f32_16x16x32_bf16 v[34:37], v[130:133], v[226:229], v[34:37]
	v_mfma_f32_16x16x32_bf16 v[26:29], v[186:189], v[226:229], v[26:29]
	v_mfma_f32_16x16x32_bf16 v[18:21], v[130:133], v[234:237], v[18:21]
	v_mfma_f32_16x16x32_bf16 v[10:13], v[186:189], v[234:237], v[10:13]
	v_mfma_f32_16x16x32_bf16 v[62:65], v[182:185], v[214:217], v[62:65]
	v_mfma_f32_16x16x32_bf16 v[58:61], v[190:193], v[214:217], v[58:61]
	v_mfma_f32_16x16x32_bf16 v[50:53], v[182:185], v[222:225], v[50:53]
	v_mfma_f32_16x16x32_bf16 v[42:45], v[190:193], v[222:225], v[42:45]
	v_mfma_f32_16x16x32_bf16 v[34:37], v[182:185], v[230:233], v[34:37]
	v_mfma_f32_16x16x32_bf16 v[26:29], v[190:193], v[230:233], v[26:29]
	v_mfma_f32_16x16x32_bf16 v[18:21], v[182:185], v[238:241], v[18:21]
	v_mfma_f32_16x16x32_bf16 v[10:13], v[190:193], v[238:241], v[10:13]
	s_setprio 0
	s_setprio 1
	v_mfma_f32_16x16x32_bf16 v[54:57], v[194:197], v[210:213], v[54:57]
	v_mfma_f32_16x16x32_bf16 v[46:49], v[202:205], v[210:213], v[46:49]
	v_mfma_f32_16x16x32_bf16 v[38:41], v[194:197], v[218:221], v[38:41]
	v_mfma_f32_16x16x32_bf16 v[30:33], v[202:205], v[218:221], v[30:33]
	v_mfma_f32_16x16x32_bf16 v[22:25], v[194:197], v[226:229], v[22:25]
	v_mfma_f32_16x16x32_bf16 v[14:17], v[202:205], v[226:229], v[14:17]
	v_mfma_f32_16x16x32_bf16 v[6:9], v[194:197], v[234:237], v[6:9]
	v_mfma_f32_16x16x32_bf16 v[2:5], v[202:205], v[234:237], v[2:5]
	v_mfma_f32_16x16x32_bf16 v[54:57], v[198:201], v[214:217], v[54:57]
	v_mfma_f32_16x16x32_bf16 v[46:49], v[206:209], v[214:217], v[46:49]
	v_mfma_f32_16x16x32_bf16 v[38:41], v[198:201], v[222:225], v[38:41]
	v_mfma_f32_16x16x32_bf16 v[30:33], v[206:209], v[222:225], v[30:33]
	v_mfma_f32_16x16x32_bf16 v[22:25], v[198:201], v[230:233], v[22:25]
	s_setprio 2
	s_barrier
	v_mfma_f32_16x16x32_bf16 v[14:17], v[206:209], v[230:233], v[14:17]
	v_mfma_f32_16x16x32_bf16 v[6:9], v[198:201], v[238:241], v[6:9]
	v_mfma_f32_16x16x32_bf16 v[2:5], v[206:209], v[238:241], v[2:5]
	s_setprio 0
	s_add_i32 s52, s52, 2
	s_add_u32 s12, s12, 0x100
	s_addc_u32 s13, s13, 0
	s_add_u32 s50, s50, 0x100
	s_addc_u32 s51, s51, 0
	s_cmp_gt_u32 s52, 13
.LBB0_412:
	s_add_u32 s22, s12, 0xfffc0080
	s_addc_u32 s23, s13, -1
	s_add_i32 s53, 0, 0x10000
	s_cmp_eq_u32 s52, 12
	s_cselect_b32 s27, s25, s23
	s_cselect_b32 s26, s30, s22
	v_add_u32_e32 v134, s53, v178
	s_cselect_b32 s23, s37, s51
	s_cselect_b32 s22, s47, s50
	s_add_i32 s56, 0, 0x14000
	ds_read_b128 v[130:133], v134
	ds_read_b128 v[182:185], v134 offset:1024
	ds_read_b128 v[186:189], v134 offset:2048
	ds_read_b128 v[190:193], v134 offset:3072
	v_add_u32_e32 v134, s56, v178
	ds_read_b128 v[194:197], v134
	ds_read_b128 v[198:201], v134 offset:1024
	ds_read_b128 v[202:205], v134 offset:2048
	ds_read_b128 v[206:209], v134 offset:3072
	v_lshl_add_u64 v[160:161], s[12:13], 0, v[156:157]
	s_add_i32 m0, s31, 0xc000
	ds_read_b128 v[210:213], v180
	ds_read_b128 v[214:217], v180 offset:1024
	ds_read_b128 v[218:221], v180 offset:2048
	ds_read_b128 v[222:225], v180 offset:3072
	ds_read_b128 v[226:229], v180 offset:4096
	ds_read_b128 v[230:233], v180 offset:5120
	ds_read_b128 v[234:237], v180 offset:6144
	ds_read_b128 v[238:241], v180 offset:7168
	global_load_lds_dwordx4 v[160:161], off
	v_lshl_add_u64 v[160:161], s[12:13], 0, v[158:159]
	s_add_i32 m0, s31, 0xe000
	s_nop 0
	global_load_lds_dwordx4 v[160:161], off
	s_waitcnt vmcnt(8)
	s_waitcnt lgkmcnt(0)
	s_barrier
	s_setprio 1
	s_waitcnt lgkmcnt(0)
	v_mfma_f32_16x16x32_bf16 v[126:129], v[130:133], v[210:213], v[126:129]
	v_mfma_f32_16x16x32_bf16 v[122:125], v[186:189], v[210:213], v[122:125]
	v_mfma_f32_16x16x32_bf16 v[110:113], v[130:133], v[218:221], v[110:113]
	v_mfma_f32_16x16x32_bf16 v[106:109], v[186:189], v[218:221], v[106:109]
	v_mfma_f32_16x16x32_bf16 v[98:101], v[130:133], v[226:229], v[98:101]
	v_mfma_f32_16x16x32_bf16 v[90:93], v[186:189], v[226:229], v[90:93]
	v_mfma_f32_16x16x32_bf16 v[82:85], v[130:133], v[234:237], v[82:85]
	v_mfma_f32_16x16x32_bf16 v[74:77], v[186:189], v[234:237], v[74:77]
	v_mfma_f32_16x16x32_bf16 v[126:129], v[182:185], v[214:217], v[126:129]
	v_mfma_f32_16x16x32_bf16 v[122:125], v[190:193], v[214:217], v[122:125]
	v_mfma_f32_16x16x32_bf16 v[110:113], v[182:185], v[222:225], v[110:113]
	v_mfma_f32_16x16x32_bf16 v[106:109], v[190:193], v[222:225], v[106:109]
	v_mfma_f32_16x16x32_bf16 v[98:101], v[182:185], v[230:233], v[98:101]
	v_mfma_f32_16x16x32_bf16 v[90:93], v[190:193], v[230:233], v[90:93]
	v_mfma_f32_16x16x32_bf16 v[82:85], v[182:185], v[238:241], v[82:85]
	v_mfma_f32_16x16x32_bf16 v[74:77], v[190:193], v[238:241], v[74:77]
	s_setprio 0
	s_setprio 1
	v_mfma_f32_16x16x32_bf16 v[118:121], v[194:197], v[210:213], v[118:121]
	v_mfma_f32_16x16x32_bf16 v[114:117], v[202:205], v[210:213], v[114:117]
	v_mfma_f32_16x16x32_bf16 v[102:105], v[194:197], v[218:221], v[102:105]
	v_mfma_f32_16x16x32_bf16 v[94:97], v[202:205], v[218:221], v[94:97]
	v_mfma_f32_16x16x32_bf16 v[86:89], v[194:197], v[226:229], v[86:89]
	v_mfma_f32_16x16x32_bf16 v[78:81], v[202:205], v[226:229], v[78:81]
	v_mfma_f32_16x16x32_bf16 v[70:73], v[194:197], v[234:237], v[70:73]
	v_mfma_f32_16x16x32_bf16 v[66:69], v[202:205], v[234:237], v[66:69]
	v_mfma_f32_16x16x32_bf16 v[118:121], v[198:201], v[214:217], v[118:121]
	v_mfma_f32_16x16x32_bf16 v[114:117], v[206:209], v[214:217], v[114:117]
	v_mfma_f32_16x16x32_bf16 v[102:105], v[198:201], v[222:225], v[102:105]
	v_mfma_f32_16x16x32_bf16 v[94:97], v[206:209], v[222:225], v[94:97]
	v_mfma_f32_16x16x32_bf16 v[86:89], v[198:201], v[230:233], v[86:89]
	s_setprio 2
	s_barrier
	v_mfma_f32_16x16x32_bf16 v[78:81], v[206:209], v[230:233], v[78:81]
	v_mfma_f32_16x16x32_bf16 v[70:73], v[198:201], v[238:241], v[70:73]
	v_mfma_f32_16x16x32_bf16 v[66:69], v[206:209], v[238:241], v[66:69]
	s_setprio 0
	s_add_i32 s53, s53, s20
	v_lshl_add_u64 v[160:161], s[22:23], 0, v[148:149]
	s_mov_b32 m0, s53
	ds_read_b128 v[210:213], v180 offset:16384
	ds_read_b128 v[214:217], v180 offset:17408
	ds_read_b128 v[218:221], v180 offset:18432
	ds_read_b128 v[222:225], v180 offset:19456
	ds_read_b128 v[226:229], v180 offset:20480
	ds_read_b128 v[230:233], v180 offset:21504
	ds_read_b128 v[234:237], v180 offset:22528
	ds_read_b128 v[238:241], v180 offset:23552
	global_load_lds_dwordx4 v[160:161], off
	s_add_i32 m0, s53, 0x2000
	s_add_u32 s64, s22, 0x40000
	v_lshl_add_u64 v[164:165], s[22:23], 0, v[144:145]
	s_addc_u32 s65, s23, 0
	s_add_i32 s53, s56, s20
	global_load_lds_dwordx4 v[164:165], off
	v_lshl_add_u64 v[242:243], s[64:65], 0, v[148:149]
	s_mov_b32 m0, s53
	v_lshl_add_u64 v[244:245], s[26:27], 0, v[146:147]
	global_load_lds_dwordx4 v[242:243], off
	v_lshl_add_u64 v[242:243], s[64:65], 0, v[144:145]
	s_add_i32 m0, s53, 0x2000
	s_nop 0
	global_load_lds_dwordx4 v[242:243], off
	v_lshl_add_u64 v[242:243], s[26:27], 0, v[150:151]
	s_mov_b32 m0, s31
	s_nop 0
	global_load_lds_dwordx4 v[242:243], off
	s_mov_b32 m0, s35
	s_nop 0
	global_load_lds_dwordx4 v[244:245], off
	s_waitcnt vmcnt(8)
	s_waitcnt lgkmcnt(0)
	s_barrier
	s_setprio 1
	s_waitcnt lgkmcnt(0)
	v_mfma_f32_16x16x32_bf16 v[62:65], v[130:133], v[210:213], v[62:65]
	v_mfma_f32_16x16x32_bf16 v[58:61], v[186:189], v[210:213], v[58:61]
	v_mfma_f32_16x16x32_bf16 v[50:53], v[130:133], v[218:221], v[50:53]
	v_mfma_f32_16x16x32_bf16 v[42:45], v[186:189], v[218:221], v[42:45]
	v_mfma_f32_16x16x32_bf16 v[34:37], v[130:133], v[226:229], v[34:37]
	v_mfma_f32_16x16x32_bf16 v[26:29], v[186:189], v[226:229], v[26:29]
	v_mfma_f32_16x16x32_bf16 v[18:21], v[130:133], v[234:237], v[18:21]
	v_mfma_f32_16x16x32_bf16 v[10:13], v[186:189], v[234:237], v[10:13]
	v_mfma_f32_16x16x32_bf16 v[62:65], v[182:185], v[214:217], v[62:65]
	v_mfma_f32_16x16x32_bf16 v[58:61], v[190:193], v[214:217], v[58:61]
	v_mfma_f32_16x16x32_bf16 v[50:53], v[182:185], v[222:225], v[50:53]
	v_mfma_f32_16x16x32_bf16 v[42:45], v[190:193], v[222:225], v[42:45]
	v_mfma_f32_16x16x32_bf16 v[34:37], v[182:185], v[230:233], v[34:37]
	v_mfma_f32_16x16x32_bf16 v[26:29], v[190:193], v[230:233], v[26:29]
	v_mfma_f32_16x16x32_bf16 v[18:21], v[182:185], v[238:241], v[18:21]
	v_mfma_f32_16x16x32_bf16 v[10:13], v[190:193], v[238:241], v[10:13]
	s_setprio 0
	s_setprio 1
	v_mfma_f32_16x16x32_bf16 v[54:57], v[194:197], v[210:213], v[54:57]
	v_mfma_f32_16x16x32_bf16 v[46:49], v[202:205], v[210:213], v[46:49]
	v_mfma_f32_16x16x32_bf16 v[38:41], v[194:197], v[218:221], v[38:41]
	v_mfma_f32_16x16x32_bf16 v[30:33], v[202:205], v[218:221], v[30:33]
	v_mfma_f32_16x16x32_bf16 v[22:25], v[194:197], v[226:229], v[22:25]
	v_mfma_f32_16x16x32_bf16 v[14:17], v[202:205], v[226:229], v[14:17]
	v_mfma_f32_16x16x32_bf16 v[6:9], v[194:197], v[234:237], v[6:9]
	v_mfma_f32_16x16x32_bf16 v[2:5], v[202:205], v[234:237], v[2:5]
	v_mfma_f32_16x16x32_bf16 v[54:57], v[198:201], v[214:217], v[54:57]
	v_mfma_f32_16x16x32_bf16 v[46:49], v[206:209], v[214:217], v[46:49]
	v_mfma_f32_16x16x32_bf16 v[38:41], v[198:201], v[222:225], v[38:41]
	v_mfma_f32_16x16x32_bf16 v[30:33], v[206:209], v[222:225], v[30:33]
	v_mfma_f32_16x16x32_bf16 v[22:25], v[198:201], v[230:233], v[22:25]
	s_setprio 2
	s_barrier
	v_mfma_f32_16x16x32_bf16 v[14:17], v[206:209], v[230:233], v[14:17]
	v_mfma_f32_16x16x32_bf16 v[6:9], v[198:201], v[238:241], v[6:9]
	v_mfma_f32_16x16x32_bf16 v[2:5], v[206:209], v[238:241], v[2:5]
	s_setprio 0
	s_add_i32 s53, 0, 0x18000
	v_add_u32_e32 v134, s53, v178
	s_add_i32 s56, 0, 0x1c000
	ds_read_b128 v[130:133], v134
	ds_read_b128 v[182:185], v134 offset:1024
	ds_read_b128 v[186:189], v134 offset:2048
	ds_read_b128 v[190:193], v134 offset:3072
	v_add_u32_e32 v134, s56, v178
	ds_read_b128 v[194:197], v134
	ds_read_b128 v[198:201], v134 offset:1024
	ds_read_b128 v[202:205], v134 offset:2048
	ds_read_b128 v[206:209], v134 offset:3072
	s_add_u32 s26, s26, 0x40000
	s_addc_u32 s27, s27, 0
	s_mov_b32 m0, s38
	v_lshl_add_u64 v[246:247], s[26:27], 0, v[150:151]
	ds_read_b128 v[210:213], v180 offset:32768
	ds_read_b128 v[214:217], v180 offset:33792
	ds_read_b128 v[218:221], v180 offset:34816
	ds_read_b128 v[222:225], v180 offset:35840
	ds_read_b128 v[226:229], v180 offset:36864
	ds_read_b128 v[230:233], v180 offset:37888
	ds_read_b128 v[234:237], v180 offset:38912
	ds_read_b128 v[238:241], v180 offset:39936
	global_load_lds_dwordx4 v[246:247], off
	v_lshl_add_u64 v[246:247], s[26:27], 0, v[146:147]
	s_mov_b32 m0, s40
	s_nop 0
	global_load_lds_dwordx4 v[246:247], off
	s_waitcnt vmcnt(8)
	s_waitcnt lgkmcnt(0)
	s_barrier
	s_setprio 1
	s_waitcnt lgkmcnt(0)
	v_mfma_f32_16x16x32_bf16 v[126:129], v[130:133], v[210:213], v[126:129]
	v_mfma_f32_16x16x32_bf16 v[122:125], v[186:189], v[210:213], v[122:125]
	v_mfma_f32_16x16x32_bf16 v[110:113], v[130:133], v[218:221], v[110:113]
	v_mfma_f32_16x16x32_bf16 v[106:109], v[186:189], v[218:221], v[106:109]
	v_mfma_f32_16x16x32_bf16 v[98:101], v[130:133], v[226:229], v[98:101]
	v_mfma_f32_16x16x32_bf16 v[90:93], v[186:189], v[226:229], v[90:93]
	v_mfma_f32_16x16x32_bf16 v[82:85], v[130:133], v[234:237], v[82:85]
	v_mfma_f32_16x16x32_bf16 v[74:77], v[186:189], v[234:237], v[74:77]
	v_mfma_f32_16x16x32_bf16 v[126:129], v[182:185], v[214:217], v[126:129]
	v_mfma_f32_16x16x32_bf16 v[122:125], v[190:193], v[214:217], v[122:125]
	v_mfma_f32_16x16x32_bf16 v[110:113], v[182:185], v[222:225], v[110:113]
	v_mfma_f32_16x16x32_bf16 v[106:109], v[190:193], v[222:225], v[106:109]
	v_mfma_f32_16x16x32_bf16 v[98:101], v[182:185], v[230:233], v[98:101]
	v_mfma_f32_16x16x32_bf16 v[90:93], v[190:193], v[230:233], v[90:93]
	v_mfma_f32_16x16x32_bf16 v[82:85], v[182:185], v[238:241], v[82:85]
	v_mfma_f32_16x16x32_bf16 v[74:77], v[190:193], v[238:241], v[74:77]
	s_setprio 0
	s_setprio 1
	v_mfma_f32_16x16x32_bf16 v[118:121], v[194:197], v[210:213], v[118:121]
	v_mfma_f32_16x16x32_bf16 v[114:117], v[202:205], v[210:213], v[114:117]
	v_mfma_f32_16x16x32_bf16 v[102:105], v[194:197], v[218:221], v[102:105]
	v_mfma_f32_16x16x32_bf16 v[94:97], v[202:205], v[218:221], v[94:97]
	v_mfma_f32_16x16x32_bf16 v[86:89], v[194:197], v[226:229], v[86:89]
	v_mfma_f32_16x16x32_bf16 v[78:81], v[202:205], v[226:229], v[78:81]
	v_mfma_f32_16x16x32_bf16 v[70:73], v[194:197], v[234:237], v[70:73]
	v_mfma_f32_16x16x32_bf16 v[66:69], v[202:205], v[234:237], v[66:69]
	v_mfma_f32_16x16x32_bf16 v[118:121], v[198:201], v[214:217], v[118:121]
	v_mfma_f32_16x16x32_bf16 v[114:117], v[206:209], v[214:217], v[114:117]
	v_mfma_f32_16x16x32_bf16 v[102:105], v[198:201], v[222:225], v[102:105]
	v_mfma_f32_16x16x32_bf16 v[94:97], v[206:209], v[222:225], v[94:97]
	v_mfma_f32_16x16x32_bf16 v[86:89], v[198:201], v[230:233], v[86:89]
	s_setprio 2
	s_barrier
	v_mfma_f32_16x16x32_bf16 v[78:81], v[206:209], v[230:233], v[78:81]
	v_mfma_f32_16x16x32_bf16 v[70:73], v[198:201], v[238:241], v[70:73]
	v_mfma_f32_16x16x32_bf16 v[66:69], v[206:209], v[238:241], v[66:69]
	s_setprio 0
	s_add_i32 s26, s53, s20
	v_lshl_add_u64 v[160:161], v[160:161], 0, s[66:67]
	s_mov_b32 m0, s26
	ds_read_b128 v[210:213], v180 offset:49152
	ds_read_b128 v[214:217], v180 offset:50176
	ds_read_b128 v[218:221], v180 offset:51200
	ds_read_b128 v[222:225], v180 offset:52224
	ds_read_b128 v[226:229], v180 offset:53248
	ds_read_b128 v[230:233], v180 offset:54272
	ds_read_b128 v[234:237], v180 offset:55296
	ds_read_b128 v[238:241], v180 offset:56320
	global_load_lds_dwordx4 v[160:161], off
	s_add_i32 m0, s26, 0x2000
	s_add_u32 s22, s22, 0x40080
	v_lshl_add_u64 v[160:161], v[164:165], 0, s[66:67]
	s_addc_u32 s23, s23, 0
	s_add_i32 s26, s56, s20
	global_load_lds_dwordx4 v[160:161], off
	v_lshl_add_u64 v[160:161], s[22:23], 0, v[148:149]
	s_mov_b32 m0, s26
	s_nop 0
	global_load_lds_dwordx4 v[160:161], off
	v_lshl_add_u64 v[160:161], s[22:23], 0, v[144:145]
	s_add_i32 m0, s26, 0x2000
	s_nop 0
	global_load_lds_dwordx4 v[160:161], off
	v_lshl_add_u64 v[160:161], v[242:243], 0, s[66:67]
	s_mov_b32 m0, s41
	s_nop 0
	global_load_lds_dwordx4 v[160:161], off
	v_lshl_add_u64 v[160:161], v[244:245], 0, s[66:67]
	s_mov_b32 m0, s44
	s_nop 0
	global_load_lds_dwordx4 v[160:161], off
	s_waitcnt vmcnt(8)
	s_waitcnt lgkmcnt(0)
	s_barrier
	s_setprio 1
	s_waitcnt lgkmcnt(0)
	v_mfma_f32_16x16x32_bf16 v[62:65], v[130:133], v[210:213], v[62:65]
	v_mfma_f32_16x16x32_bf16 v[58:61], v[186:189], v[210:213], v[58:61]
	v_mfma_f32_16x16x32_bf16 v[50:53], v[130:133], v[218:221], v[50:53]
	v_mfma_f32_16x16x32_bf16 v[42:45], v[186:189], v[218:221], v[42:45]
	v_mfma_f32_16x16x32_bf16 v[34:37], v[130:133], v[226:229], v[34:37]
	v_mfma_f32_16x16x32_bf16 v[26:29], v[186:189], v[226:229], v[26:29]
	v_mfma_f32_16x16x32_bf16 v[18:21], v[130:133], v[234:237], v[18:21]
	v_mfma_f32_16x16x32_bf16 v[10:13], v[186:189], v[234:237], v[10:13]
	v_mfma_f32_16x16x32_bf16 v[62:65], v[182:185], v[214:217], v[62:65]
	v_mfma_f32_16x16x32_bf16 v[58:61], v[190:193], v[214:217], v[58:61]
	v_mfma_f32_16x16x32_bf16 v[50:53], v[182:185], v[222:225], v[50:53]
	v_mfma_f32_16x16x32_bf16 v[42:45], v[190:193], v[222:225], v[42:45]
	v_mfma_f32_16x16x32_bf16 v[34:37], v[182:185], v[230:233], v[34:37]
	v_mfma_f32_16x16x32_bf16 v[26:29], v[190:193], v[230:233], v[26:29]
	v_mfma_f32_16x16x32_bf16 v[18:21], v[182:185], v[238:241], v[18:21]
	v_mfma_f32_16x16x32_bf16 v[10:13], v[190:193], v[238:241], v[10:13]
	s_setprio 0
	s_setprio 1
	v_mfma_f32_16x16x32_bf16 v[54:57], v[194:197], v[210:213], v[54:57]
	v_mfma_f32_16x16x32_bf16 v[46:49], v[202:205], v[210:213], v[46:49]
	v_mfma_f32_16x16x32_bf16 v[38:41], v[194:197], v[218:221], v[38:41]
	v_mfma_f32_16x16x32_bf16 v[30:33], v[202:205], v[218:221], v[30:33]
	v_mfma_f32_16x16x32_bf16 v[22:25], v[194:197], v[226:229], v[22:25]
	v_mfma_f32_16x16x32_bf16 v[14:17], v[202:205], v[226:229], v[14:17]
	v_mfma_f32_16x16x32_bf16 v[6:9], v[194:197], v[234:237], v[6:9]
	v_mfma_f32_16x16x32_bf16 v[2:5], v[202:205], v[234:237], v[2:5]
	v_mfma_f32_16x16x32_bf16 v[54:57], v[198:201], v[214:217], v[54:57]
	v_mfma_f32_16x16x32_bf16 v[46:49], v[206:209], v[214:217], v[46:49]
	v_mfma_f32_16x16x32_bf16 v[38:41], v[198:201], v[222:225], v[38:41]
	v_mfma_f32_16x16x32_bf16 v[30:33], v[206:209], v[222:225], v[30:33]
	v_mfma_f32_16x16x32_bf16 v[22:25], v[198:201], v[230:233], v[22:25]
	s_setprio 2
	s_barrier
	v_mfma_f32_16x16x32_bf16 v[14:17], v[206:209], v[230:233], v[14:17]
	v_mfma_f32_16x16x32_bf16 v[6:9], v[198:201], v[238:241], v[6:9]
	v_mfma_f32_16x16x32_bf16 v[2:5], v[206:209], v[238:241], v[2:5]
	s_setprio 0
	s_add_i32 s52, s52, 2
	s_add_u32 s12, s12, 0x100
	s_addc_u32 s13, s13, 0
	s_add_u32 s50, s50, 0x100
	s_addc_u32 s51, s51, 0
	s_cmp_gt_u32 s52, 13
	s_cbranch_scc0 .LBB0_412
	s_and_b64 vcc, exec, s[84:85]
	s_cbranch_vccz .LBB0_415
	s_barrier
